# v69 + first K-loop iteration peeled with srcC=0 on each accumulator's first MFMA, per-tile accumulator zeroing (128 v_mov) removed in all 10 GEMM loops
# speedup vs baseline: 1.0141x; 1.0141x over previous
.Lzskip_1:
	s_add_u32 s20, s20, 0x80
	s_addc_u32 s21, s21, 0
	s_add_u32 s52, s22, 0x100
	s_addc_u32 s53, s23, 0
	s_mov_b32 s22, 0
	ds_read_b128 v[168:171], v165
	ds_read_b128 v[172:175], v165 offset:1024
	ds_read_b128 v[176:179], v165 offset:2048
	ds_read_b128 v[180:183], v165 offset:3072
	ds_read_b128 v[184:187], v166
	ds_read_b128 v[188:191], v166 offset:1024
	ds_read_b128 v[192:195], v166 offset:2048
	ds_read_b128 v[196:199], v166 offset:3072
	s_add_i32 s54, s22, 2
	s_add_u32 s55, s20, 0x80
	s_addc_u32 s23, s21, 0
	s_cmp_eq_u32 s42, s22
	s_cselect_b32 s22, s4, s55
	s_cselect_b32 s23, s5, s23
	s_cselect_b32 s61, s19, s53
	s_cselect_b32 s60, s18, s52
	v_lshl_add_u64 v[234:235], s[20:21], 0, v[154:155]
	s_add_i32 m0, s31, 0xc000
	ds_read_b128 v[200:203], v167
	ds_read_b128 v[204:207], v167 offset:1024
	ds_read_b128 v[208:211], v167 offset:2048
	ds_read_b128 v[212:215], v167 offset:3072
	ds_read_b128 v[216:219], v167 offset:4096
	ds_read_b128 v[222:225], v167 offset:5120
	ds_read_b128 v[226:229], v167 offset:6144
	ds_read_b128 v[230:233], v167 offset:7168
	global_load_lds_dwordx4 v[234:235], off
	v_lshl_add_u64 v[234:235], s[20:21], 0, v[156:157]
	s_add_i32 m0, s31, 0xe000
	s_nop 0
	global_load_lds_dwordx4 v[234:235], off
	s_waitcnt vmcnt(8)
	s_waitcnt lgkmcnt(0)
	s_barrier
	s_waitcnt lgkmcnt(0)
	v_mfma_f32_16x16x32_bf16 v[120:123], v[168:171], v[200:203], 0
	v_mfma_f32_16x16x32_bf16 v[120:123], v[172:175], v[204:207], v[120:123]
	v_mfma_f32_16x16x32_bf16 v[116:119], v[180:183], v[204:207], 0
	v_mfma_f32_16x16x32_bf16 v[116:119], v[176:179], v[200:203], v[116:119]
	v_mfma_f32_16x16x32_bf16 v[124:127], v[184:187], v[200:203], 0
	v_mfma_f32_16x16x32_bf16 v[124:127], v[188:191], v[204:207], v[124:127]
	v_mfma_f32_16x16x32_bf16 v[112:115], v[196:199], v[204:207], 0
	v_mfma_f32_16x16x32_bf16 v[112:115], v[192:195], v[200:203], v[112:115]
	v_mfma_f32_16x16x32_bf16 v[96:99], v[192:195], v[208:211], 0
	v_mfma_f32_16x16x32_bf16 v[96:99], v[196:199], v[212:215], v[96:99]
	v_mfma_f32_16x16x32_bf16 v[104:107], v[188:191], v[212:215], 0
	v_mfma_f32_16x16x32_bf16 v[104:107], v[184:187], v[208:211], v[104:107]
	v_mfma_f32_16x16x32_bf16 v[100:103], v[176:179], v[208:211], 0
	v_mfma_f32_16x16x32_bf16 v[100:103], v[180:183], v[212:215], v[100:103]
	v_mfma_f32_16x16x32_bf16 v[108:111], v[172:175], v[212:215], 0
	v_mfma_f32_16x16x32_bf16 v[108:111], v[168:171], v[208:211], v[108:111]
	v_mfma_f32_16x16x32_bf16 v[92:95], v[168:171], v[216:219], 0
	v_mfma_f32_16x16x32_bf16 v[92:95], v[172:175], v[222:225], v[92:95]
	v_mfma_f32_16x16x32_bf16 v[84:87], v[180:183], v[222:225], 0
	v_mfma_f32_16x16x32_bf16 v[84:87], v[176:179], v[216:219], v[84:87]
	v_mfma_f32_16x16x32_bf16 v[88:91], v[184:187], v[216:219], 0
	v_mfma_f32_16x16x32_bf16 v[88:91], v[188:191], v[222:225], v[88:91]
	v_mfma_f32_16x16x32_bf16 v[80:83], v[196:199], v[222:225], 0
	v_mfma_f32_16x16x32_bf16 v[80:83], v[192:195], v[216:219], v[80:83]
	v_mfma_f32_16x16x32_bf16 v[64:67], v[192:195], v[226:229], 0
	v_mfma_f32_16x16x32_bf16 v[64:67], v[196:199], v[230:233], v[64:67]
	v_mfma_f32_16x16x32_bf16 v[72:75], v[188:191], v[230:233], 0
	v_mfma_f32_16x16x32_bf16 v[72:75], v[184:187], v[226:229], v[72:75]
	v_mfma_f32_16x16x32_bf16 v[68:71], v[176:179], v[226:229], 0
	v_mfma_f32_16x16x32_bf16 v[68:71], v[180:183], v[230:233], v[68:71]
	v_mfma_f32_16x16x32_bf16 v[76:79], v[172:175], v[230:233], 0
	v_mfma_f32_16x16x32_bf16 v[76:79], v[168:171], v[226:229], v[76:79]
	s_barrier
	s_add_i32 s55, s46, s28
	v_lshl_add_u64 v[234:235], s[60:61], 0, v[132:133]
	s_mov_b32 m0, s55
	ds_read_b128 v[200:203], v167 offset:16384
	ds_read_b128 v[204:207], v167 offset:17408
	ds_read_b128 v[208:211], v167 offset:18432
	ds_read_b128 v[212:215], v167 offset:19456
	ds_read_b128 v[216:219], v167 offset:20480
	ds_read_b128 v[222:225], v167 offset:21504
	ds_read_b128 v[226:229], v167 offset:22528
	ds_read_b128 v[230:233], v167 offset:23552
	global_load_lds_dwordx4 v[234:235], off
	s_add_i32 m0, s55, 0x2000
	v_lshl_add_u64 v[236:237], s[60:61], 0, v[128:129]
	s_add_u32 s60, s60, s10
	s_addc_u32 s61, s61, s11
	s_add_i32 s55, s47, s28
	global_load_lds_dwordx4 v[236:237], off
	v_lshl_add_u64 v[238:239], s[60:61], 0, v[132:133]
	s_mov_b32 m0, s55
	v_lshl_add_u64 v[240:241], s[60:61], 0, v[128:129]
	global_load_lds_dwordx4 v[238:239], off
	s_add_i32 m0, s55, 0x2000
	v_lshl_add_u64 v[242:243], s[22:23], 0, v[134:135]
	global_load_lds_dwordx4 v[240:241], off
	s_mov_b32 m0, s31
	v_lshl_add_u64 v[244:245], s[22:23], 0, v[130:131]
	global_load_lds_dwordx4 v[242:243], off
	s_mov_b32 m0, s33
	s_nop 0
	global_load_lds_dwordx4 v[244:245], off
	s_waitcnt vmcnt(8)
	s_waitcnt lgkmcnt(0)
	s_barrier
	s_waitcnt lgkmcnt(0)
	v_mfma_f32_16x16x32_bf16 v[60:63], v[168:171], v[200:203], 0
	v_mfma_f32_16x16x32_bf16 v[60:63], v[172:175], v[204:207], v[60:63]
	v_mfma_f32_16x16x32_bf16 v[52:55], v[180:183], v[204:207], 0
	v_mfma_f32_16x16x32_bf16 v[52:55], v[176:179], v[200:203], v[52:55]
	v_mfma_f32_16x16x32_bf16 v[56:59], v[184:187], v[200:203], 0
	v_mfma_f32_16x16x32_bf16 v[56:59], v[188:191], v[204:207], v[56:59]
	v_mfma_f32_16x16x32_bf16 v[48:51], v[196:199], v[204:207], 0
	v_mfma_f32_16x16x32_bf16 v[48:51], v[192:195], v[200:203], v[48:51]
	v_mfma_f32_16x16x32_bf16 v[32:35], v[192:195], v[208:211], 0
	v_mfma_f32_16x16x32_bf16 v[32:35], v[196:199], v[212:215], v[32:35]
	v_mfma_f32_16x16x32_bf16 v[40:43], v[188:191], v[212:215], 0
	v_mfma_f32_16x16x32_bf16 v[40:43], v[184:187], v[208:211], v[40:43]
	v_mfma_f32_16x16x32_bf16 v[36:39], v[176:179], v[208:211], 0
	v_mfma_f32_16x16x32_bf16 v[36:39], v[180:183], v[212:215], v[36:39]
	v_mfma_f32_16x16x32_bf16 v[44:47], v[172:175], v[212:215], 0
	v_mfma_f32_16x16x32_bf16 v[44:47], v[168:171], v[208:211], v[44:47]
	v_mfma_f32_16x16x32_bf16 v[28:31], v[168:171], v[216:219], 0
	v_mfma_f32_16x16x32_bf16 v[28:31], v[172:175], v[222:225], v[28:31]
	v_mfma_f32_16x16x32_bf16 v[20:23], v[180:183], v[222:225], 0
	v_mfma_f32_16x16x32_bf16 v[20:23], v[176:179], v[216:219], v[20:23]
	v_mfma_f32_16x16x32_bf16 v[24:27], v[184:187], v[216:219], 0
	v_mfma_f32_16x16x32_bf16 v[24:27], v[188:191], v[222:225], v[24:27]
	v_mfma_f32_16x16x32_bf16 v[16:19], v[196:199], v[222:225], 0
	v_mfma_f32_16x16x32_bf16 v[16:19], v[192:195], v[216:219], v[16:19]
	v_mfma_f32_16x16x32_bf16 v[0:3], v[192:195], v[226:229], 0
	v_mfma_f32_16x16x32_bf16 v[0:3], v[196:199], v[230:233], v[0:3]
	v_mfma_f32_16x16x32_bf16 v[8:11], v[188:191], v[230:233], 0
	v_mfma_f32_16x16x32_bf16 v[8:11], v[184:187], v[226:229], v[8:11]
	v_mfma_f32_16x16x32_bf16 v[4:7], v[176:179], v[226:229], 0
	v_mfma_f32_16x16x32_bf16 v[4:7], v[180:183], v[230:233], v[4:7]
	v_mfma_f32_16x16x32_bf16 v[12:15], v[172:175], v[230:233], 0
	v_mfma_f32_16x16x32_bf16 v[12:15], v[168:171], v[226:229], v[12:15]
	s_barrier
	s_add_i32 s55, 0, 0x18000
	s_add_i32 s60, 0, 0x1c000
	v_add_u32_e32 v180, s55, v164
	v_add_u32_e32 v196, s60, v164
	ds_read_b128 v[168:171], v180
	ds_read_b128 v[172:175], v180 offset:1024
	ds_read_b128 v[176:179], v180 offset:2048
	ds_read_b128 v[180:183], v180 offset:3072
	ds_read_b128 v[184:187], v196
	ds_read_b128 v[188:191], v196 offset:1024
	ds_read_b128 v[192:195], v196 offset:2048
	ds_read_b128 v[196:199], v196 offset:3072
	s_add_u32 s22, s22, s10
	s_addc_u32 s23, s23, s11
	s_mov_b32 m0, s34
	v_lshl_add_u64 v[246:247], s[22:23], 0, v[134:135]
	ds_read_b128 v[200:203], v167 offset:32768
	ds_read_b128 v[204:207], v167 offset:33792
	ds_read_b128 v[208:211], v167 offset:34816
	ds_read_b128 v[212:215], v167 offset:35840
	ds_read_b128 v[216:219], v167 offset:36864
	ds_read_b128 v[222:225], v167 offset:37888
	ds_read_b128 v[226:229], v167 offset:38912
	ds_read_b128 v[230:233], v167 offset:39936
	global_load_lds_dwordx4 v[246:247], off
	v_lshl_add_u64 v[246:247], s[22:23], 0, v[130:131]
	s_mov_b32 m0, s35
	s_nop 0
	global_load_lds_dwordx4 v[246:247], off
	s_waitcnt vmcnt(8)
	s_waitcnt lgkmcnt(0)
	s_barrier
	s_waitcnt lgkmcnt(0)
	v_mfma_f32_16x16x32_bf16 v[120:123], v[168:171], v[200:203], v[120:123]
	v_mfma_f32_16x16x32_bf16 v[120:123], v[172:175], v[204:207], v[120:123]
	v_mfma_f32_16x16x32_bf16 v[116:119], v[180:183], v[204:207], v[116:119]
	v_mfma_f32_16x16x32_bf16 v[116:119], v[176:179], v[200:203], v[116:119]
	v_mfma_f32_16x16x32_bf16 v[124:127], v[184:187], v[200:203], v[124:127]
	v_mfma_f32_16x16x32_bf16 v[124:127], v[188:191], v[204:207], v[124:127]
	v_mfma_f32_16x16x32_bf16 v[112:115], v[196:199], v[204:207], v[112:115]
	v_mfma_f32_16x16x32_bf16 v[112:115], v[192:195], v[200:203], v[112:115]
	v_mfma_f32_16x16x32_bf16 v[96:99], v[192:195], v[208:211], v[96:99]
	v_mfma_f32_16x16x32_bf16 v[96:99], v[196:199], v[212:215], v[96:99]
	v_mfma_f32_16x16x32_bf16 v[104:107], v[188:191], v[212:215], v[104:107]
	v_mfma_f32_16x16x32_bf16 v[104:107], v[184:187], v[208:211], v[104:107]
	v_mfma_f32_16x16x32_bf16 v[100:103], v[176:179], v[208:211], v[100:103]
	v_mfma_f32_16x16x32_bf16 v[100:103], v[180:183], v[212:215], v[100:103]
	v_mfma_f32_16x16x32_bf16 v[108:111], v[172:175], v[212:215], v[108:111]
	v_mfma_f32_16x16x32_bf16 v[108:111], v[168:171], v[208:211], v[108:111]
	v_mfma_f32_16x16x32_bf16 v[92:95], v[168:171], v[216:219], v[92:95]
	v_mfma_f32_16x16x32_bf16 v[92:95], v[172:175], v[222:225], v[92:95]
	v_mfma_f32_16x16x32_bf16 v[84:87], v[180:183], v[222:225], v[84:87]
	v_mfma_f32_16x16x32_bf16 v[84:87], v[176:179], v[216:219], v[84:87]
	v_mfma_f32_16x16x32_bf16 v[88:91], v[184:187], v[216:219], v[88:91]
	v_mfma_f32_16x16x32_bf16 v[88:91], v[188:191], v[222:225], v[88:91]
	v_mfma_f32_16x16x32_bf16 v[80:83], v[196:199], v[222:225], v[80:83]
	v_mfma_f32_16x16x32_bf16 v[80:83], v[192:195], v[216:219], v[80:83]
	v_mfma_f32_16x16x32_bf16 v[64:67], v[192:195], v[226:229], v[64:67]
	v_mfma_f32_16x16x32_bf16 v[64:67], v[196:199], v[230:233], v[64:67]
	v_mfma_f32_16x16x32_bf16 v[72:75], v[188:191], v[230:233], v[72:75]
	v_mfma_f32_16x16x32_bf16 v[72:75], v[184:187], v[226:229], v[72:75]
	v_mfma_f32_16x16x32_bf16 v[68:71], v[176:179], v[226:229], v[68:71]
	v_mfma_f32_16x16x32_bf16 v[68:71], v[180:183], v[230:233], v[68:71]
	v_mfma_f32_16x16x32_bf16 v[76:79], v[172:175], v[230:233], v[76:79]
	v_mfma_f32_16x16x32_bf16 v[76:79], v[168:171], v[226:229], v[76:79]
	s_barrier
	s_add_i32 s22, s55, s28
	v_lshl_add_u64 v[234:235], v[234:235], 0, s[14:15]
	s_mov_b32 m0, s22
	ds_read_b128 v[200:203], v167 offset:49152
	ds_read_b128 v[204:207], v167 offset:50176
	ds_read_b128 v[208:211], v167 offset:51200
	ds_read_b128 v[212:215], v167 offset:52224
	ds_read_b128 v[216:219], v167 offset:53248
	ds_read_b128 v[222:225], v167 offset:54272
	ds_read_b128 v[226:229], v167 offset:55296
	ds_read_b128 v[230:233], v167 offset:56320
	global_load_lds_dwordx4 v[234:235], off
	v_lshl_add_u64 v[234:235], v[236:237], 0, s[14:15]
	s_add_i32 m0, s22, 0x2000
	s_add_i32 s22, s60, s28
	global_load_lds_dwordx4 v[234:235], off
	v_lshl_add_u64 v[234:235], v[238:239], 0, s[14:15]
	s_mov_b32 m0, s22
	s_nop 0
	global_load_lds_dwordx4 v[234:235], off
	v_lshl_add_u64 v[234:235], v[240:241], 0, s[14:15]
	s_add_i32 m0, s22, 0x2000
	s_nop 0
	global_load_lds_dwordx4 v[234:235], off
	v_lshl_add_u64 v[234:235], v[242:243], 0, s[14:15]
	s_mov_b32 m0, s39
	s_nop 0
	global_load_lds_dwordx4 v[234:235], off
	v_lshl_add_u64 v[234:235], v[244:245], 0, s[14:15]
	s_mov_b32 m0, s40
	s_nop 0
	global_load_lds_dwordx4 v[234:235], off
	s_waitcnt vmcnt(8)
	s_waitcnt lgkmcnt(0)
	s_barrier
	s_waitcnt lgkmcnt(0)
	v_mfma_f32_16x16x32_bf16 v[60:63], v[168:171], v[200:203], v[60:63]
	v_mfma_f32_16x16x32_bf16 v[60:63], v[172:175], v[204:207], v[60:63]
	v_mfma_f32_16x16x32_bf16 v[52:55], v[180:183], v[204:207], v[52:55]
	v_mfma_f32_16x16x32_bf16 v[52:55], v[176:179], v[200:203], v[52:55]
	v_mfma_f32_16x16x32_bf16 v[56:59], v[184:187], v[200:203], v[56:59]
	v_mfma_f32_16x16x32_bf16 v[56:59], v[188:191], v[204:207], v[56:59]
	v_mfma_f32_16x16x32_bf16 v[48:51], v[196:199], v[204:207], v[48:51]
	v_mfma_f32_16x16x32_bf16 v[48:51], v[192:195], v[200:203], v[48:51]
	v_mfma_f32_16x16x32_bf16 v[32:35], v[192:195], v[208:211], v[32:35]
	v_mfma_f32_16x16x32_bf16 v[32:35], v[196:199], v[212:215], v[32:35]
	v_mfma_f32_16x16x32_bf16 v[40:43], v[188:191], v[212:215], v[40:43]
	v_mfma_f32_16x16x32_bf16 v[40:43], v[184:187], v[208:211], v[40:43]
	v_mfma_f32_16x16x32_bf16 v[36:39], v[176:179], v[208:211], v[36:39]
	v_mfma_f32_16x16x32_bf16 v[36:39], v[180:183], v[212:215], v[36:39]
	v_mfma_f32_16x16x32_bf16 v[44:47], v[172:175], v[212:215], v[44:47]
	v_mfma_f32_16x16x32_bf16 v[44:47], v[168:171], v[208:211], v[44:47]
	v_mfma_f32_16x16x32_bf16 v[28:31], v[168:171], v[216:219], v[28:31]
	v_mfma_f32_16x16x32_bf16 v[28:31], v[172:175], v[222:225], v[28:31]
	v_mfma_f32_16x16x32_bf16 v[20:23], v[180:183], v[222:225], v[20:23]
	v_mfma_f32_16x16x32_bf16 v[20:23], v[176:179], v[216:219], v[20:23]
	v_mfma_f32_16x16x32_bf16 v[24:27], v[184:187], v[216:219], v[24:27]
	v_mfma_f32_16x16x32_bf16 v[24:27], v[188:191], v[222:225], v[24:27]
	v_mfma_f32_16x16x32_bf16 v[16:19], v[196:199], v[222:225], v[16:19]
	v_mfma_f32_16x16x32_bf16 v[16:19], v[192:195], v[216:219], v[16:19]
	v_mfma_f32_16x16x32_bf16 v[0:3], v[192:195], v[226:229], v[0:3]
	v_mfma_f32_16x16x32_bf16 v[0:3], v[196:199], v[230:233], v[0:3]
	v_mfma_f32_16x16x32_bf16 v[8:11], v[188:191], v[230:233], v[8:11]
	v_mfma_f32_16x16x32_bf16 v[8:11], v[184:187], v[226:229], v[8:11]
	v_mfma_f32_16x16x32_bf16 v[4:7], v[176:179], v[226:229], v[4:7]
	v_mfma_f32_16x16x32_bf16 v[4:7], v[180:183], v[230:233], v[4:7]
	v_mfma_f32_16x16x32_bf16 v[12:15], v[172:175], v[230:233], v[12:15]
	v_mfma_f32_16x16x32_bf16 v[12:15], v[168:171], v[226:229], v[12:15]
	s_barrier
	s_add_u32 s20, s20, 0x100
	s_addc_u32 s21, s21, 0
	s_add_u32 s52, s52, 0x100
	s_addc_u32 s53, s53, 0
	s_cmp_ge_i32 s54, s41
	s_mov_b32 s22, s54
	s_cbranch_scc1 .Lpeel_exit_142

.Lpeel_exit_142:
.LBB0_143:
	s_and_b64 vcc, exec, s[16:17]
	s_cbranch_vccz .LBB0_145
	s_barrier

.LBB0_226:
	v_mov_b32_e32 v201, 0
	s_andn2_b64 vcc, exec, s[16:17]
	v_mov_b32_e32 v200, 0
	v_mov_b32_e32 v203, 0
	v_mov_b32_e32 v202, 0
	v_mov_b32_e32 v205, 0
	v_mov_b32_e32 v204, 0
	v_mov_b32_e32 v207, 0
	v_mov_b32_e32 v206, 0
	v_mov_b32_e32 v195, 0
	v_mov_b32_e32 v194, 0
	v_mov_b32_e32 v193, 0
	v_mov_b32_e32 v192, 0
	v_mov_b32_e32 v191, 0
	v_mov_b32_e32 v190, 0
	v_mov_b32_e32 v189, 0
	v_mov_b32_e32 v188, 0
	v_mov_b32_e32 v179, 0
	v_mov_b32_e32 v178, 0
	v_mov_b32_e32 v177, 0
	v_mov_b32_e32 v176, 0
	v_mov_b32_e32 v175, 0
	v_mov_b32_e32 v174, 0
	v_mov_b32_e32 v173, 0
	v_mov_b32_e32 v172, 0
	v_mov_b32_e32 v161, 0
	v_mov_b32_e32 v160, 0
	v_mov_b32_e32 v159, 0
	v_mov_b32_e32 v158, 0
	v_mov_b32_e32 v157, 0
	v_mov_b32_e32 v156, 0
	v_mov_b32_e32 v155, 0
	v_mov_b32_e32 v154, 0
	v_mov_b32_e32 v211, 0
	v_mov_b32_e32 v210, 0
	v_mov_b32_e32 v209, 0
	v_mov_b32_e32 v208, 0
	v_mov_b32_e32 v199, 0
	v_mov_b32_e32 v198, 0
	v_mov_b32_e32 v197, 0
	v_mov_b32_e32 v196, 0
	v_mov_b32_e32 v187, 0
	v_mov_b32_e32 v186, 0
	v_mov_b32_e32 v185, 0
	v_mov_b32_e32 v184, 0
	v_mov_b32_e32 v183, 0
	v_mov_b32_e32 v182, 0
	v_mov_b32_e32 v181, 0
	v_mov_b32_e32 v180, 0
	v_mov_b32_e32 v171, 0
	v_mov_b32_e32 v170, 0
	v_mov_b32_e32 v169, 0
	v_mov_b32_e32 v168, 0
	v_mov_b32_e32 v167, 0
	v_mov_b32_e32 v166, 0
	v_mov_b32_e32 v165, 0
	v_mov_b32_e32 v164, 0
	v_mov_b32_e32 v153, 0
	v_mov_b32_e32 v152, 0
	v_mov_b32_e32 v151, 0
	v_mov_b32_e32 v150, 0
	v_mov_b32_e32 v149, 0
	v_mov_b32_e32 v148, 0
	v_mov_b32_e32 v147, 0
	v_mov_b32_e32 v146, 0
	v_mov_b32_e32 v145, 0
	v_mov_b32_e32 v144, 0
	v_mov_b32_e32 v143, 0
	v_mov_b32_e32 v142, 0
	v_mov_b32_e32 v127, 0
	v_mov_b32_e32 v126, 0
	v_mov_b32_e32 v125, 0
	v_mov_b32_e32 v124, 0
	v_mov_b32_e32 v115, 0
	v_mov_b32_e32 v114, 0
	v_mov_b32_e32 v113, 0
	v_mov_b32_e32 v112, 0
	v_mov_b32_e32 v111, 0
	v_mov_b32_e32 v110, 0
	v_mov_b32_e32 v109, 0
	v_mov_b32_e32 v108, 0
	v_mov_b32_e32 v99, 0
	v_mov_b32_e32 v98, 0
	v_mov_b32_e32 v97, 0
	v_mov_b32_e32 v96, 0
	v_mov_b32_e32 v95, 0
	v_mov_b32_e32 v94, 0
	v_mov_b32_e32 v93, 0
	v_mov_b32_e32 v92, 0
	v_mov_b32_e32 v83, 0
	v_mov_b32_e32 v82, 0
	v_mov_b32_e32 v81, 0
	v_mov_b32_e32 v80, 0
	v_mov_b32_e32 v79, 0
	v_mov_b32_e32 v78, 0
	v_mov_b32_e32 v77, 0
	v_mov_b32_e32 v76, 0
	v_mov_b32_e32 v123, 0
	v_mov_b32_e32 v122, 0
	v_mov_b32_e32 v121, 0
	v_mov_b32_e32 v120, 0
	v_mov_b32_e32 v119, 0
	v_mov_b32_e32 v118, 0
	v_mov_b32_e32 v117, 0
	v_mov_b32_e32 v116, 0
	v_mov_b32_e32 v107, 0
	v_mov_b32_e32 v106, 0
	v_mov_b32_e32 v105, 0
	v_mov_b32_e32 v104, 0
	v_mov_b32_e32 v103, 0
	v_mov_b32_e32 v102, 0
	v_mov_b32_e32 v101, 0
	v_mov_b32_e32 v100, 0
	v_mov_b32_e32 v91, 0
	v_mov_b32_e32 v90, 0
	v_mov_b32_e32 v89, 0
	v_mov_b32_e32 v88, 0
	v_mov_b32_e32 v87, 0
	v_mov_b32_e32 v86, 0
	v_mov_b32_e32 v85, 0
	v_mov_b32_e32 v84, 0
	v_mov_b32_e32 v75, 0
	v_mov_b32_e32 v74, 0
	v_mov_b32_e32 v73, 0
	v_mov_b32_e32 v72, 0
	v_mov_b32_e32 v71, 0
	v_mov_b32_e32 v70, 0
	v_mov_b32_e32 v69, 0
	v_mov_b32_e32 v68, 0
	s_cbranch_vccnz .LBB0_230
	s_add_u32 s24, s24, 0xc000
	s_addc_u32 s25, s25, 0
	s_add_u32 s60, s26, 0x10000
	s_addc_u32 s61, s27, 0
	s_mov_b32 s26, 0
	s_waitcnt lgkmcnt(0)
	ds_read_b128 v[140:143], v219
	ds_read_b128 v[144:147], v219 offset:1024
	ds_read_b128 v[148:151], v219 offset:2048
	ds_read_b128 v[152:155], v219 offset:3072
	ds_read_b128 v[156:159], v221
	ds_read_b128 v[164:167], v221 offset:1024
	ds_read_b128 v[168:171], v221 offset:2048
	ds_read_b128 v[172:175], v221 offset:3072
	s_add_i32 s62, s26, 2
	s_add_u32 s27, s24, 0x4000
	s_addc_u32 s28, s25, 0
	s_cmp_eq_u32 s46, s26
	s_cselect_b32 s30, s0, s27
	s_cselect_b32 s31, s1, s28
	s_cselect_b32 s28, s22, s60
	s_cselect_b32 s29, s23, s61
	s_add_u32 s26, s30, 0x8000
	s_addc_u32 s27, s31, 0
	v_lshl_add_u64 v[160:161], s[24:25], 0, v[132:133]
	s_add_i32 m0, s38, 0xc000
	ds_read_b128 v[176:179], v222
	ds_read_b128 v[180:183], v222 offset:1024
	ds_read_b128 v[184:187], v222 offset:2048
	ds_read_b128 v[188:191], v222 offset:3072
	ds_read_b128 v[192:195], v222 offset:4096
	ds_read_b128 v[196:199], v222 offset:5120
	ds_read_b128 v[200:203], v222 offset:6144
	ds_read_b128 v[204:207], v222 offset:7168
	global_load_lds_dwordx4 v[160:161], off
	v_lshl_add_u64 v[160:161], s[24:25], 0, v[134:135]
	s_add_i32 m0, s38, 0xe000
	s_nop 0
	global_load_lds_dwordx4 v[160:161], off
	s_waitcnt vmcnt(8)
	s_waitcnt lgkmcnt(0)
	s_barrier
	s_waitcnt lgkmcnt(0)
	v_mfma_f32_16x16x32_bf16 v[124:127], v[140:143], v[176:179], 0
	v_mfma_f32_16x16x32_bf16 v[124:127], v[144:147], v[180:183], v[124:127]
	v_mfma_f32_16x16x32_bf16 v[120:123], v[152:155], v[180:183], 0
	v_mfma_f32_16x16x32_bf16 v[120:123], v[148:151], v[176:179], v[120:123]
	v_mfma_f32_16x16x32_bf16 v[108:111], v[156:159], v[176:179], 0
	v_mfma_f32_16x16x32_bf16 v[108:111], v[164:167], v[180:183], v[108:111]
	v_mfma_f32_16x16x32_bf16 v[100:103], v[172:175], v[180:183], 0
	v_mfma_f32_16x16x32_bf16 v[100:103], v[168:171], v[176:179], v[100:103]
	v_mfma_f32_16x16x32_bf16 v[84:87], v[168:171], v[184:187], 0
	v_mfma_f32_16x16x32_bf16 v[84:87], v[172:175], v[188:191], v[84:87]
	v_mfma_f32_16x16x32_bf16 v[92:95], v[164:167], v[188:191], 0
	v_mfma_f32_16x16x32_bf16 v[92:95], v[156:159], v[184:187], v[92:95]
	v_mfma_f32_16x16x32_bf16 v[112:115], v[148:151], v[184:187], 0
	v_mfma_f32_16x16x32_bf16 v[112:115], v[152:155], v[188:191], v[112:115]
	v_mfma_f32_16x16x32_bf16 v[116:119], v[144:147], v[188:191], 0
	v_mfma_f32_16x16x32_bf16 v[116:119], v[140:143], v[184:187], v[116:119]
	v_mfma_f32_16x16x32_bf16 v[104:107], v[140:143], v[192:195], 0
	v_mfma_f32_16x16x32_bf16 v[104:107], v[144:147], v[196:199], v[104:107]
	v_mfma_f32_16x16x32_bf16 v[96:99], v[152:155], v[196:199], 0
	v_mfma_f32_16x16x32_bf16 v[96:99], v[148:151], v[192:195], v[96:99]
	v_mfma_f32_16x16x32_bf16 v[76:79], v[156:159], v[192:195], 0
	v_mfma_f32_16x16x32_bf16 v[76:79], v[164:167], v[196:199], v[76:79]
	v_mfma_f32_16x16x32_bf16 v[72:75], v[172:175], v[196:199], 0
	v_mfma_f32_16x16x32_bf16 v[72:75], v[168:171], v[192:195], v[72:75]
	v_mfma_f32_16x16x32_bf16 v[64:67], v[168:171], v[200:203], 0
	v_mfma_f32_16x16x32_bf16 v[64:67], v[172:175], v[204:207], v[64:67]
	v_mfma_f32_16x16x32_bf16 v[68:71], v[164:167], v[204:207], 0
	v_mfma_f32_16x16x32_bf16 v[68:71], v[156:159], v[200:203], v[68:71]
	v_mfma_f32_16x16x32_bf16 v[80:83], v[148:151], v[200:203], 0
	v_mfma_f32_16x16x32_bf16 v[80:83], v[152:155], v[204:207], v[80:83]
	v_mfma_f32_16x16x32_bf16 v[88:91], v[144:147], v[204:207], 0
	v_mfma_f32_16x16x32_bf16 v[88:91], v[140:143], v[200:203], v[88:91]
	s_barrier
	s_add_i32 s63, s50, s37
	v_lshl_add_u64 v[160:161], s[28:29], 0, v[128:129]
	s_mov_b32 m0, s63
	ds_read_b128 v[176:179], v222 offset:16384
	ds_read_b128 v[180:183], v222 offset:17408
	ds_read_b128 v[184:187], v222 offset:18432
	ds_read_b128 v[188:191], v222 offset:19456
	ds_read_b128 v[192:195], v222 offset:20480
	ds_read_b128 v[196:199], v222 offset:21504
	ds_read_b128 v[200:203], v222 offset:22528
	ds_read_b128 v[204:207], v222 offset:23552
	global_load_lds_dwordx4 v[160:161], off
	s_add_i32 m0, s63, 0x2000
	s_add_u32 s64, s28, 0x4000
	v_lshl_add_u64 v[160:161], s[28:29], 0, v[130:131]
	s_addc_u32 s65, s29, 0
	s_add_i32 s63, s51, s37
	global_load_lds_dwordx4 v[160:161], off
	v_lshl_add_u64 v[160:161], s[64:65], 0, v[128:129]
	s_mov_b32 m0, s63
	s_nop 0
	global_load_lds_dwordx4 v[160:161], off
	v_lshl_add_u64 v[160:161], s[64:65], 0, v[130:131]
	s_add_i32 m0, s63, 0x2000
	s_nop 0
	global_load_lds_dwordx4 v[160:161], off
	v_lshl_add_u64 v[160:161], s[30:31], 0, v[128:129]
	s_mov_b32 m0, s38
	s_nop 0
	global_load_lds_dwordx4 v[160:161], off
	v_lshl_add_u64 v[160:161], s[30:31], 0, v[130:131]
	s_mov_b32 m0, s39
	s_nop 0
	global_load_lds_dwordx4 v[160:161], off
	s_waitcnt vmcnt(8)
	s_waitcnt lgkmcnt(0)
	s_barrier
	s_waitcnt lgkmcnt(0)
	v_mfma_f32_16x16x32_bf16 v[60:63], v[140:143], v[176:179], 0
	v_mfma_f32_16x16x32_bf16 v[60:63], v[144:147], v[180:183], v[60:63]
	v_mfma_f32_16x16x32_bf16 v[56:59], v[152:155], v[180:183], 0
	v_mfma_f32_16x16x32_bf16 v[56:59], v[148:151], v[176:179], v[56:59]
	v_mfma_f32_16x16x32_bf16 v[44:47], v[156:159], v[176:179], 0
	v_mfma_f32_16x16x32_bf16 v[44:47], v[164:167], v[180:183], v[44:47]
	v_mfma_f32_16x16x32_bf16 v[36:39], v[172:175], v[180:183], 0
	v_mfma_f32_16x16x32_bf16 v[36:39], v[168:171], v[176:179], v[36:39]
	v_mfma_f32_16x16x32_bf16 v[20:23], v[168:171], v[184:187], 0
	v_mfma_f32_16x16x32_bf16 v[20:23], v[172:175], v[188:191], v[20:23]
	v_mfma_f32_16x16x32_bf16 v[28:31], v[164:167], v[188:191], 0
	v_mfma_f32_16x16x32_bf16 v[28:31], v[156:159], v[184:187], v[28:31]
	v_mfma_f32_16x16x32_bf16 v[48:51], v[148:151], v[184:187], 0
	v_mfma_f32_16x16x32_bf16 v[48:51], v[152:155], v[188:191], v[48:51]
	v_mfma_f32_16x16x32_bf16 v[52:55], v[144:147], v[188:191], 0
	v_mfma_f32_16x16x32_bf16 v[52:55], v[140:143], v[184:187], v[52:55]
	v_mfma_f32_16x16x32_bf16 v[40:43], v[140:143], v[192:195], 0
	v_mfma_f32_16x16x32_bf16 v[40:43], v[144:147], v[196:199], v[40:43]
	v_mfma_f32_16x16x32_bf16 v[32:35], v[152:155], v[196:199], 0
	v_mfma_f32_16x16x32_bf16 v[32:35], v[148:151], v[192:195], v[32:35]
	v_mfma_f32_16x16x32_bf16 v[12:15], v[156:159], v[192:195], 0
	v_mfma_f32_16x16x32_bf16 v[12:15], v[164:167], v[196:199], v[12:15]
	v_mfma_f32_16x16x32_bf16 v[8:11], v[172:175], v[196:199], 0
	v_mfma_f32_16x16x32_bf16 v[8:11], v[168:171], v[192:195], v[8:11]
	v_mfma_f32_16x16x32_bf16 v[0:3], v[168:171], v[200:203], 0
	v_mfma_f32_16x16x32_bf16 v[0:3], v[172:175], v[204:207], v[0:3]
	v_mfma_f32_16x16x32_bf16 v[4:7], v[164:167], v[204:207], 0
	v_mfma_f32_16x16x32_bf16 v[4:7], v[156:159], v[200:203], v[4:7]
	v_mfma_f32_16x16x32_bf16 v[16:19], v[148:151], v[200:203], 0
	v_mfma_f32_16x16x32_bf16 v[16:19], v[152:155], v[204:207], v[16:19]
	v_mfma_f32_16x16x32_bf16 v[24:27], v[144:147], v[204:207], 0
	v_mfma_f32_16x16x32_bf16 v[24:27], v[140:143], v[200:203], v[24:27]
	s_barrier
	s_add_i32 s63, 0, 0x18000
	s_add_i32 s64, 0, 0x1c000
	v_add_u32_e32 v152, s63, v217
	v_add_u32_e32 v160, s64, v217
	ds_read_b128 v[140:143], v152
	ds_read_b128 v[144:147], v152 offset:1024
	ds_read_b128 v[148:151], v152 offset:2048
	ds_read_b128 v[152:155], v152 offset:3072
	ds_read_b128 v[156:159], v160
	ds_read_b128 v[164:167], v160 offset:1024
	ds_read_b128 v[168:171], v160 offset:2048
	ds_read_b128 v[172:175], v160 offset:3072
	s_add_u32 s30, s30, 0x4000
	s_addc_u32 s31, s31, 0
	s_mov_b32 m0, s40
	v_lshl_add_u64 v[160:161], s[30:31], 0, v[128:129]
	ds_read_b128 v[176:179], v222 offset:32768
	ds_read_b128 v[180:183], v222 offset:33792
	ds_read_b128 v[184:187], v222 offset:34816
	ds_read_b128 v[188:191], v222 offset:35840
	ds_read_b128 v[192:195], v222 offset:36864
	ds_read_b128 v[196:199], v222 offset:37888
	ds_read_b128 v[200:203], v222 offset:38912
	ds_read_b128 v[204:207], v222 offset:39936
	global_load_lds_dwordx4 v[160:161], off
	v_lshl_add_u64 v[160:161], s[30:31], 0, v[130:131]
	s_mov_b32 m0, s41
	s_nop 0
	global_load_lds_dwordx4 v[160:161], off
	s_waitcnt vmcnt(8)
	s_waitcnt lgkmcnt(0)
	s_barrier
	s_waitcnt lgkmcnt(0)
	v_mfma_f32_16x16x32_bf16 v[124:127], v[140:143], v[176:179], v[124:127]
	v_mfma_f32_16x16x32_bf16 v[124:127], v[144:147], v[180:183], v[124:127]
	v_mfma_f32_16x16x32_bf16 v[120:123], v[152:155], v[180:183], v[120:123]
	v_mfma_f32_16x16x32_bf16 v[120:123], v[148:151], v[176:179], v[120:123]
	v_mfma_f32_16x16x32_bf16 v[108:111], v[156:159], v[176:179], v[108:111]
	v_mfma_f32_16x16x32_bf16 v[108:111], v[164:167], v[180:183], v[108:111]
	v_mfma_f32_16x16x32_bf16 v[100:103], v[172:175], v[180:183], v[100:103]
	v_mfma_f32_16x16x32_bf16 v[100:103], v[168:171], v[176:179], v[100:103]
	v_mfma_f32_16x16x32_bf16 v[84:87], v[168:171], v[184:187], v[84:87]
	v_mfma_f32_16x16x32_bf16 v[84:87], v[172:175], v[188:191], v[84:87]
	v_mfma_f32_16x16x32_bf16 v[92:95], v[164:167], v[188:191], v[92:95]
	v_mfma_f32_16x16x32_bf16 v[92:95], v[156:159], v[184:187], v[92:95]
	v_mfma_f32_16x16x32_bf16 v[112:115], v[148:151], v[184:187], v[112:115]
	v_mfma_f32_16x16x32_bf16 v[112:115], v[152:155], v[188:191], v[112:115]
	v_mfma_f32_16x16x32_bf16 v[116:119], v[144:147], v[188:191], v[116:119]
	v_mfma_f32_16x16x32_bf16 v[116:119], v[140:143], v[184:187], v[116:119]
	v_mfma_f32_16x16x32_bf16 v[104:107], v[140:143], v[192:195], v[104:107]
	v_mfma_f32_16x16x32_bf16 v[104:107], v[144:147], v[196:199], v[104:107]
	v_mfma_f32_16x16x32_bf16 v[96:99], v[152:155], v[196:199], v[96:99]
	v_mfma_f32_16x16x32_bf16 v[96:99], v[148:151], v[192:195], v[96:99]
	v_mfma_f32_16x16x32_bf16 v[76:79], v[156:159], v[192:195], v[76:79]
	v_mfma_f32_16x16x32_bf16 v[76:79], v[164:167], v[196:199], v[76:79]
	v_mfma_f32_16x16x32_bf16 v[72:75], v[172:175], v[196:199], v[72:75]
	v_mfma_f32_16x16x32_bf16 v[72:75], v[168:171], v[192:195], v[72:75]
	v_mfma_f32_16x16x32_bf16 v[64:67], v[168:171], v[200:203], v[64:67]
	v_mfma_f32_16x16x32_bf16 v[64:67], v[172:175], v[204:207], v[64:67]
	v_mfma_f32_16x16x32_bf16 v[68:71], v[164:167], v[204:207], v[68:71]
	v_mfma_f32_16x16x32_bf16 v[68:71], v[156:159], v[200:203], v[68:71]
	v_mfma_f32_16x16x32_bf16 v[80:83], v[148:151], v[200:203], v[80:83]
	v_mfma_f32_16x16x32_bf16 v[80:83], v[152:155], v[204:207], v[80:83]
	v_mfma_f32_16x16x32_bf16 v[88:91], v[144:147], v[204:207], v[88:91]
	v_mfma_f32_16x16x32_bf16 v[88:91], v[140:143], v[200:203], v[88:91]
	s_barrier
	s_add_u32 s30, s28, 0x8000
	s_addc_u32 s31, s29, 0
	s_add_i32 s63, s63, s37
	v_lshl_add_u64 v[160:161], s[30:31], 0, v[128:129]
	s_mov_b32 m0, s63
	ds_read_b128 v[176:179], v222 offset:49152
	ds_read_b128 v[180:183], v222 offset:50176
	ds_read_b128 v[184:187], v222 offset:51200
	ds_read_b128 v[188:191], v222 offset:52224
	ds_read_b128 v[192:195], v222 offset:53248
	ds_read_b128 v[196:199], v222 offset:54272
	ds_read_b128 v[200:203], v222 offset:55296
	ds_read_b128 v[204:207], v222 offset:56320
	global_load_lds_dwordx4 v[160:161], off
	s_add_i32 m0, s63, 0x2000
	s_add_u32 s28, s28, 0xc000
	v_lshl_add_u64 v[160:161], s[30:31], 0, v[130:131]
	s_addc_u32 s29, s29, 0
	s_add_i32 s30, s64, s37
	global_load_lds_dwordx4 v[160:161], off
	v_lshl_add_u64 v[160:161], s[28:29], 0, v[128:129]
	s_mov_b32 m0, s30
	s_nop 0
	global_load_lds_dwordx4 v[160:161], off
	v_lshl_add_u64 v[160:161], s[28:29], 0, v[130:131]
	s_add_i32 m0, s30, 0x2000
	s_nop 0
	global_load_lds_dwordx4 v[160:161], off
	v_lshl_add_u64 v[160:161], s[26:27], 0, v[128:129]
	s_mov_b32 m0, s44
	s_nop 0
	global_load_lds_dwordx4 v[160:161], off
	v_lshl_add_u64 v[160:161], s[26:27], 0, v[130:131]
	s_mov_b32 m0, s45
	s_nop 0
	global_load_lds_dwordx4 v[160:161], off
	s_waitcnt vmcnt(8)
	s_waitcnt lgkmcnt(0)
	s_barrier
	s_waitcnt lgkmcnt(0)
	v_mfma_f32_16x16x32_bf16 v[60:63], v[140:143], v[176:179], v[60:63]
	v_mfma_f32_16x16x32_bf16 v[60:63], v[144:147], v[180:183], v[60:63]
	v_mfma_f32_16x16x32_bf16 v[56:59], v[152:155], v[180:183], v[56:59]
	v_mfma_f32_16x16x32_bf16 v[56:59], v[148:151], v[176:179], v[56:59]
	v_mfma_f32_16x16x32_bf16 v[44:47], v[156:159], v[176:179], v[44:47]
	v_mfma_f32_16x16x32_bf16 v[44:47], v[164:167], v[180:183], v[44:47]
	v_mfma_f32_16x16x32_bf16 v[36:39], v[172:175], v[180:183], v[36:39]
	v_mfma_f32_16x16x32_bf16 v[36:39], v[168:171], v[176:179], v[36:39]
	v_mfma_f32_16x16x32_bf16 v[20:23], v[168:171], v[184:187], v[20:23]
	v_mfma_f32_16x16x32_bf16 v[20:23], v[172:175], v[188:191], v[20:23]
	v_mfma_f32_16x16x32_bf16 v[28:31], v[164:167], v[188:191], v[28:31]
	v_mfma_f32_16x16x32_bf16 v[28:31], v[156:159], v[184:187], v[28:31]
	v_mfma_f32_16x16x32_bf16 v[48:51], v[148:151], v[184:187], v[48:51]
	v_mfma_f32_16x16x32_bf16 v[48:51], v[152:155], v[188:191], v[48:51]
	v_mfma_f32_16x16x32_bf16 v[52:55], v[144:147], v[188:191], v[52:55]
	v_mfma_f32_16x16x32_bf16 v[52:55], v[140:143], v[184:187], v[52:55]
	v_mfma_f32_16x16x32_bf16 v[40:43], v[140:143], v[192:195], v[40:43]
	v_mfma_f32_16x16x32_bf16 v[40:43], v[144:147], v[196:199], v[40:43]
	v_mfma_f32_16x16x32_bf16 v[32:35], v[152:155], v[196:199], v[32:35]
	v_mfma_f32_16x16x32_bf16 v[32:35], v[148:151], v[192:195], v[32:35]
	v_mfma_f32_16x16x32_bf16 v[12:15], v[156:159], v[192:195], v[12:15]
	v_mfma_f32_16x16x32_bf16 v[12:15], v[164:167], v[196:199], v[12:15]
	v_mfma_f32_16x16x32_bf16 v[8:11], v[172:175], v[196:199], v[8:11]
	v_mfma_f32_16x16x32_bf16 v[8:11], v[168:171], v[192:195], v[8:11]
	v_mfma_f32_16x16x32_bf16 v[0:3], v[168:171], v[200:203], v[0:3]
	v_mfma_f32_16x16x32_bf16 v[0:3], v[172:175], v[204:207], v[0:3]
	v_mfma_f32_16x16x32_bf16 v[4:7], v[164:167], v[204:207], v[4:7]
	v_mfma_f32_16x16x32_bf16 v[4:7], v[156:159], v[200:203], v[4:7]
	v_mfma_f32_16x16x32_bf16 v[16:19], v[148:151], v[200:203], v[16:19]
	v_mfma_f32_16x16x32_bf16 v[16:19], v[152:155], v[204:207], v[16:19]
	v_mfma_f32_16x16x32_bf16 v[24:27], v[144:147], v[204:207], v[24:27]
	v_mfma_f32_16x16x32_bf16 v[24:27], v[140:143], v[200:203], v[24:27]
	s_barrier
	s_add_u32 s24, s24, 0x10000
	s_addc_u32 s25, s25, 0
	s_add_u32 s60, s60, 0x10000
	s_addc_u32 s61, s61, 0
	s_cmp_ge_i32 s62, s43
	s_mov_b32 s26, s62
	s_cbranch_scc1 .Lpeel_exit_228

.Lpeel_exit_228:
	v_pk_mul_f32 v[200:201], v[126:127], 0.5 op_sel_hi:[1,0]
	v_pk_mul_f32 v[202:203], v[124:125], 0.5 op_sel_hi:[1,0]
	v_pk_mul_f32 v[204:205], v[122:123], 0.5 op_sel_hi:[1,0]
	v_pk_mul_f32 v[206:207], v[120:121], 0.5 op_sel_hi:[1,0]
	v_pk_mul_f32 v[210:211], v[110:111], 0.5 op_sel_hi:[1,0]
	v_pk_mul_f32 v[208:209], v[108:109], 0.5 op_sel_hi:[1,0]
	v_pk_mul_f32 v[198:199], v[102:103], 0.5 op_sel_hi:[1,0]
	v_pk_mul_f32 v[196:197], v[100:101], 0.5 op_sel_hi:[1,0]
	v_pk_mul_f32 v[194:195], v[118:119], 0.5 op_sel_hi:[1,0]
	v_pk_mul_f32 v[192:193], v[116:117], 0.5 op_sel_hi:[1,0]
	v_pk_mul_f32 v[190:191], v[114:115], 0.5 op_sel_hi:[1,0]
	v_pk_mul_f32 v[188:189], v[112:113], 0.5 op_sel_hi:[1,0]
	v_pk_mul_f32 v[186:187], v[94:95], 0.5 op_sel_hi:[1,0]
	v_pk_mul_f32 v[184:185], v[92:93], 0.5 op_sel_hi:[1,0]
	v_pk_mul_f32 v[182:183], v[86:87], 0.5 op_sel_hi:[1,0]
	v_pk_mul_f32 v[180:181], v[84:85], 0.5 op_sel_hi:[1,0]
	v_pk_mul_f32 v[178:179], v[106:107], 0.5 op_sel_hi:[1,0]
	v_pk_mul_f32 v[176:177], v[104:105], 0.5 op_sel_hi:[1,0]
	v_pk_mul_f32 v[174:175], v[98:99], 0.5 op_sel_hi:[1,0]
	v_pk_mul_f32 v[172:173], v[96:97], 0.5 op_sel_hi:[1,0]
	v_pk_mul_f32 v[170:171], v[78:79], 0.5 op_sel_hi:[1,0]
	v_pk_mul_f32 v[168:169], v[76:77], 0.5 op_sel_hi:[1,0]
	v_pk_mul_f32 v[166:167], v[74:75], 0.5 op_sel_hi:[1,0]
	v_pk_mul_f32 v[164:165], v[72:73], 0.5 op_sel_hi:[1,0]
	v_pk_mul_f32 v[160:161], v[90:91], 0.5 op_sel_hi:[1,0]
	v_pk_mul_f32 v[158:159], v[88:89], 0.5 op_sel_hi:[1,0]
	v_pk_mul_f32 v[156:157], v[82:83], 0.5 op_sel_hi:[1,0]
	v_pk_mul_f32 v[154:155], v[80:81], 0.5 op_sel_hi:[1,0]
	v_pk_mul_f32 v[152:153], v[70:71], 0.5 op_sel_hi:[1,0]
	v_pk_mul_f32 v[150:151], v[68:69], 0.5 op_sel_hi:[1,0]
	v_pk_mul_f32 v[148:149], v[66:67], 0.5 op_sel_hi:[1,0]
	v_pk_mul_f32 v[146:147], v[64:65], 0.5 op_sel_hi:[1,0]
	v_pk_mul_f32 v[144:145], v[62:63], 0.5 op_sel_hi:[1,0]
	v_pk_mul_f32 v[142:143], v[60:61], 0.5 op_sel_hi:[1,0]
	v_pk_mul_f32 v[126:127], v[58:59], 0.5 op_sel_hi:[1,0]
	v_pk_mul_f32 v[124:125], v[56:57], 0.5 op_sel_hi:[1,0]
	v_pk_mul_f32 v[122:123], v[46:47], 0.5 op_sel_hi:[1,0]
	v_pk_mul_f32 v[120:121], v[44:45], 0.5 op_sel_hi:[1,0]
	v_pk_mul_f32 v[118:119], v[38:39], 0.5 op_sel_hi:[1,0]
	v_pk_mul_f32 v[116:117], v[36:37], 0.5 op_sel_hi:[1,0]
	v_pk_mul_f32 v[114:115], v[54:55], 0.5 op_sel_hi:[1,0]
	v_pk_mul_f32 v[112:113], v[52:53], 0.5 op_sel_hi:[1,0]
	v_pk_mul_f32 v[110:111], v[50:51], 0.5 op_sel_hi:[1,0]
	v_pk_mul_f32 v[108:109], v[48:49], 0.5 op_sel_hi:[1,0]
	v_pk_mul_f32 v[106:107], v[30:31], 0.5 op_sel_hi:[1,0]
	v_pk_mul_f32 v[104:105], v[28:29], 0.5 op_sel_hi:[1,0]
	v_pk_mul_f32 v[102:103], v[22:23], 0.5 op_sel_hi:[1,0]
	v_pk_mul_f32 v[100:101], v[20:21], 0.5 op_sel_hi:[1,0]
	v_pk_mul_f32 v[98:99], v[42:43], 0.5 op_sel_hi:[1,0]
	v_pk_mul_f32 v[96:97], v[40:41], 0.5 op_sel_hi:[1,0]
	v_pk_mul_f32 v[94:95], v[34:35], 0.5 op_sel_hi:[1,0]
	v_pk_mul_f32 v[92:93], v[32:33], 0.5 op_sel_hi:[1,0]
	v_pk_mul_f32 v[90:91], v[14:15], 0.5 op_sel_hi:[1,0]
	v_pk_mul_f32 v[88:89], v[12:13], 0.5 op_sel_hi:[1,0]
	v_pk_mul_f32 v[86:87], v[10:11], 0.5 op_sel_hi:[1,0]
	v_pk_mul_f32 v[84:85], v[8:9], 0.5 op_sel_hi:[1,0]
	v_pk_mul_f32 v[82:83], v[26:27], 0.5 op_sel_hi:[1,0]
	v_pk_mul_f32 v[80:81], v[24:25], 0.5 op_sel_hi:[1,0]
	v_pk_mul_f32 v[78:79], v[18:19], 0.5 op_sel_hi:[1,0]
	v_pk_mul_f32 v[76:77], v[16:17], 0.5 op_sel_hi:[1,0]
	v_pk_mul_f32 v[74:75], v[6:7], 0.5 op_sel_hi:[1,0]
	v_pk_mul_f32 v[72:73], v[4:5], 0.5 op_sel_hi:[1,0]
	v_pk_mul_f32 v[70:71], v[2:3], 0.5 op_sel_hi:[1,0]
	v_pk_mul_f32 v[68:69], v[0:1], 0.5 op_sel_hi:[1,0]

.Lzskip_2:
	s_add_u32 s0, s52, 0x80
	s_addc_u32 s1, s53, 0
	s_add_u32 s33, s50, 0x100
	s_addc_u32 s52, s51, 0
	s_mov_b32 s50, 0
	ds_read_b128 v[128:131], v222
	ds_read_b128 v[132:135], v222 offset:1024
	ds_read_b128 v[136:139], v222 offset:2048
	ds_read_b128 v[140:143], v222 offset:3072
	ds_read_b128 v[144:147], v223
	ds_read_b128 v[148:151], v223 offset:1024
	ds_read_b128 v[152:155], v223 offset:2048
	ds_read_b128 v[156:159], v223 offset:3072
	s_add_i32 s53, s50, 2
	s_add_u32 s54, s0, 0x80
	s_addc_u32 s51, s1, 0
	s_cmp_eq_u32 s78, s50
	s_cselect_b32 s50, s46, s54
	s_cselect_b32 s51, s47, s51
	s_cselect_b32 s55, s49, s52
	s_cselect_b32 s54, s48, s33
	v_lshl_add_u64 v[160:161], s[0:1], 0, v[176:177]
	s_add_i32 m0, s71, 0xc000
	ds_read_b128 v[184:187], v224
	ds_read_b128 v[188:191], v224 offset:1024
	ds_read_b128 v[192:195], v224 offset:2048
	ds_read_b128 v[196:199], v224 offset:3072
	ds_read_b128 v[200:203], v224 offset:4096
	ds_read_b128 v[204:207], v224 offset:5120
	ds_read_b128 v[208:211], v224 offset:6144
	ds_read_b128 v[212:215], v224 offset:7168
	global_load_lds_dwordx4 v[160:161], off
	v_lshl_add_u64 v[160:161], s[0:1], 0, v[178:179]
	s_add_i32 m0, s71, 0xe000
	s_nop 0
	global_load_lds_dwordx4 v[160:161], off
	s_waitcnt vmcnt(8)
	s_waitcnt lgkmcnt(0)
	s_barrier
	s_waitcnt lgkmcnt(0)
	v_mfma_f32_16x16x32_bf16 v[124:127], v[128:131], v[184:187], 0
	v_mfma_f32_16x16x32_bf16 v[124:127], v[132:135], v[188:191], v[124:127]
	v_mfma_f32_16x16x32_bf16 v[120:123], v[140:143], v[188:191], 0
	v_mfma_f32_16x16x32_bf16 v[120:123], v[136:139], v[184:187], v[120:123]
	v_mfma_f32_16x16x32_bf16 v[116:119], v[144:147], v[184:187], 0
	v_mfma_f32_16x16x32_bf16 v[116:119], v[148:151], v[188:191], v[116:119]
	v_mfma_f32_16x16x32_bf16 v[112:115], v[156:159], v[188:191], 0
	v_mfma_f32_16x16x32_bf16 v[112:115], v[152:155], v[184:187], v[112:115]
	v_mfma_f32_16x16x32_bf16 v[96:99], v[152:155], v[192:195], 0
	v_mfma_f32_16x16x32_bf16 v[96:99], v[156:159], v[196:199], v[96:99]
	v_mfma_f32_16x16x32_bf16 v[100:103], v[148:151], v[196:199], 0
	v_mfma_f32_16x16x32_bf16 v[100:103], v[144:147], v[192:195], v[100:103]
	v_mfma_f32_16x16x32_bf16 v[104:107], v[136:139], v[192:195], 0
	v_mfma_f32_16x16x32_bf16 v[104:107], v[140:143], v[196:199], v[104:107]
	v_mfma_f32_16x16x32_bf16 v[108:111], v[132:135], v[196:199], 0
	v_mfma_f32_16x16x32_bf16 v[108:111], v[128:131], v[192:195], v[108:111]
	v_mfma_f32_16x16x32_bf16 v[92:95], v[128:131], v[200:203], 0
	v_mfma_f32_16x16x32_bf16 v[92:95], v[132:135], v[204:207], v[92:95]
	v_mfma_f32_16x16x32_bf16 v[88:91], v[140:143], v[204:207], 0
	v_mfma_f32_16x16x32_bf16 v[88:91], v[136:139], v[200:203], v[88:91]
	v_mfma_f32_16x16x32_bf16 v[84:87], v[144:147], v[200:203], 0
	v_mfma_f32_16x16x32_bf16 v[84:87], v[148:151], v[204:207], v[84:87]
	v_mfma_f32_16x16x32_bf16 v[80:83], v[156:159], v[204:207], 0
	v_mfma_f32_16x16x32_bf16 v[80:83], v[152:155], v[200:203], v[80:83]
	v_mfma_f32_16x16x32_bf16 v[64:67], v[152:155], v[208:211], 0
	v_mfma_f32_16x16x32_bf16 v[64:67], v[156:159], v[212:215], v[64:67]
	v_mfma_f32_16x16x32_bf16 v[68:71], v[148:151], v[212:215], 0
	v_mfma_f32_16x16x32_bf16 v[68:71], v[144:147], v[208:211], v[68:71]
	v_mfma_f32_16x16x32_bf16 v[72:75], v[136:139], v[208:211], 0
	v_mfma_f32_16x16x32_bf16 v[72:75], v[140:143], v[212:215], v[72:75]
	v_mfma_f32_16x16x32_bf16 v[76:79], v[132:135], v[212:215], 0
	v_mfma_f32_16x16x32_bf16 v[76:79], v[128:131], v[208:211], v[76:79]
	s_barrier
	s_add_i32 s60, s82, s70
	v_lshl_add_u64 v[160:161], s[54:55], 0, v[166:167]
	s_mov_b32 m0, s60
	ds_read_b128 v[184:187], v224 offset:16384
	ds_read_b128 v[188:191], v224 offset:17408
	ds_read_b128 v[192:195], v224 offset:18432
	ds_read_b128 v[196:199], v224 offset:19456
	ds_read_b128 v[200:203], v224 offset:20480
	ds_read_b128 v[204:207], v224 offset:21504
	ds_read_b128 v[208:211], v224 offset:22528
	ds_read_b128 v[212:215], v224 offset:23552
	global_load_lds_dwordx4 v[160:161], off
	s_add_i32 m0, s60, 0x2000
	v_lshl_add_u64 v[216:217], s[54:55], 0, v[170:171]
	s_add_u32 s54, s54, s10
	s_addc_u32 s55, s55, s11
	s_add_i32 s60, s83, s70
	global_load_lds_dwordx4 v[216:217], off
	v_lshl_add_u64 v[218:219], s[54:55], 0, v[166:167]
	s_mov_b32 m0, s60
	v_lshl_add_u64 v[230:231], s[54:55], 0, v[170:171]
	global_load_lds_dwordx4 v[218:219], off
	s_add_i32 m0, s60, 0x2000
	v_lshl_add_u64 v[232:233], s[50:51], 0, v[164:165]
	global_load_lds_dwordx4 v[230:231], off
	s_mov_b32 m0, s71
	v_lshl_add_u64 v[234:235], s[50:51], 0, v[168:169]
	global_load_lds_dwordx4 v[232:233], off
	s_mov_b32 m0, s72
	s_nop 0
	global_load_lds_dwordx4 v[234:235], off
	s_waitcnt vmcnt(8)
	s_waitcnt lgkmcnt(0)
	s_barrier
	s_waitcnt lgkmcnt(0)
	v_mfma_f32_16x16x32_bf16 v[60:63], v[128:131], v[184:187], 0
	v_mfma_f32_16x16x32_bf16 v[60:63], v[132:135], v[188:191], v[60:63]
	v_mfma_f32_16x16x32_bf16 v[56:59], v[140:143], v[188:191], 0
	v_mfma_f32_16x16x32_bf16 v[56:59], v[136:139], v[184:187], v[56:59]
	v_mfma_f32_16x16x32_bf16 v[52:55], v[144:147], v[184:187], 0
	v_mfma_f32_16x16x32_bf16 v[52:55], v[148:151], v[188:191], v[52:55]
	v_mfma_f32_16x16x32_bf16 v[48:51], v[156:159], v[188:191], 0
	v_mfma_f32_16x16x32_bf16 v[48:51], v[152:155], v[184:187], v[48:51]
	v_mfma_f32_16x16x32_bf16 v[32:35], v[152:155], v[192:195], 0
	v_mfma_f32_16x16x32_bf16 v[32:35], v[156:159], v[196:199], v[32:35]
	v_mfma_f32_16x16x32_bf16 v[36:39], v[148:151], v[196:199], 0
	v_mfma_f32_16x16x32_bf16 v[36:39], v[144:147], v[192:195], v[36:39]
	v_mfma_f32_16x16x32_bf16 v[40:43], v[136:139], v[192:195], 0
	v_mfma_f32_16x16x32_bf16 v[40:43], v[140:143], v[196:199], v[40:43]
	v_mfma_f32_16x16x32_bf16 v[44:47], v[132:135], v[196:199], 0
	v_mfma_f32_16x16x32_bf16 v[44:47], v[128:131], v[192:195], v[44:47]
	v_mfma_f32_16x16x32_bf16 v[28:31], v[128:131], v[200:203], 0
	v_mfma_f32_16x16x32_bf16 v[28:31], v[132:135], v[204:207], v[28:31]
	v_mfma_f32_16x16x32_bf16 v[24:27], v[140:143], v[204:207], 0
	v_mfma_f32_16x16x32_bf16 v[24:27], v[136:139], v[200:203], v[24:27]
	v_mfma_f32_16x16x32_bf16 v[20:23], v[144:147], v[200:203], 0
	v_mfma_f32_16x16x32_bf16 v[20:23], v[148:151], v[204:207], v[20:23]
	v_mfma_f32_16x16x32_bf16 v[16:19], v[156:159], v[204:207], 0
	v_mfma_f32_16x16x32_bf16 v[16:19], v[152:155], v[200:203], v[16:19]
	v_mfma_f32_16x16x32_bf16 v[0:3], v[152:155], v[208:211], 0
	v_mfma_f32_16x16x32_bf16 v[0:3], v[156:159], v[212:215], v[0:3]
	v_mfma_f32_16x16x32_bf16 v[4:7], v[148:151], v[212:215], 0
	v_mfma_f32_16x16x32_bf16 v[4:7], v[144:147], v[208:211], v[4:7]
	v_mfma_f32_16x16x32_bf16 v[8:11], v[136:139], v[208:211], 0
	v_mfma_f32_16x16x32_bf16 v[8:11], v[140:143], v[212:215], v[8:11]
	v_mfma_f32_16x16x32_bf16 v[12:15], v[132:135], v[212:215], 0
	v_mfma_f32_16x16x32_bf16 v[12:15], v[128:131], v[208:211], v[12:15]
	s_barrier
	s_add_i32 s54, 0, 0x18000
	s_add_i32 s55, 0, 0x1c000
	v_add_u32_e32 v140, s54, v221
	v_add_u32_e32 v156, s55, v221
	ds_read_b128 v[128:131], v140
	ds_read_b128 v[132:135], v140 offset:1024
	ds_read_b128 v[136:139], v140 offset:2048
	ds_read_b128 v[140:143], v140 offset:3072
	ds_read_b128 v[144:147], v156
	ds_read_b128 v[148:151], v156 offset:1024
	ds_read_b128 v[152:155], v156 offset:2048
	ds_read_b128 v[156:159], v156 offset:3072
	s_add_u32 s50, s50, s10
	s_addc_u32 s51, s51, s11
	s_mov_b32 m0, s73
	v_lshl_add_u64 v[236:237], s[50:51], 0, v[164:165]
	ds_read_b128 v[184:187], v224 offset:32768
	ds_read_b128 v[188:191], v224 offset:33792
	ds_read_b128 v[192:195], v224 offset:34816
	ds_read_b128 v[196:199], v224 offset:35840
	ds_read_b128 v[200:203], v224 offset:36864
	ds_read_b128 v[204:207], v224 offset:37888
	ds_read_b128 v[208:211], v224 offset:38912
	ds_read_b128 v[212:215], v224 offset:39936
	global_load_lds_dwordx4 v[236:237], off
	v_lshl_add_u64 v[236:237], s[50:51], 0, v[168:169]
	s_mov_b32 m0, s74
	s_nop 0
	global_load_lds_dwordx4 v[236:237], off
	s_waitcnt vmcnt(8)
	s_waitcnt lgkmcnt(0)
	s_barrier
	s_waitcnt lgkmcnt(0)
	v_mfma_f32_16x16x32_bf16 v[124:127], v[128:131], v[184:187], v[124:127]
	v_mfma_f32_16x16x32_bf16 v[124:127], v[132:135], v[188:191], v[124:127]
	v_mfma_f32_16x16x32_bf16 v[120:123], v[140:143], v[188:191], v[120:123]
	v_mfma_f32_16x16x32_bf16 v[120:123], v[136:139], v[184:187], v[120:123]
	v_mfma_f32_16x16x32_bf16 v[116:119], v[144:147], v[184:187], v[116:119]
	v_mfma_f32_16x16x32_bf16 v[116:119], v[148:151], v[188:191], v[116:119]
	v_mfma_f32_16x16x32_bf16 v[112:115], v[156:159], v[188:191], v[112:115]
	v_mfma_f32_16x16x32_bf16 v[112:115], v[152:155], v[184:187], v[112:115]
	v_mfma_f32_16x16x32_bf16 v[96:99], v[152:155], v[192:195], v[96:99]
	v_mfma_f32_16x16x32_bf16 v[96:99], v[156:159], v[196:199], v[96:99]
	v_mfma_f32_16x16x32_bf16 v[100:103], v[148:151], v[196:199], v[100:103]
	v_mfma_f32_16x16x32_bf16 v[100:103], v[144:147], v[192:195], v[100:103]
	v_mfma_f32_16x16x32_bf16 v[104:107], v[136:139], v[192:195], v[104:107]
	v_mfma_f32_16x16x32_bf16 v[104:107], v[140:143], v[196:199], v[104:107]
	v_mfma_f32_16x16x32_bf16 v[108:111], v[132:135], v[196:199], v[108:111]
	v_mfma_f32_16x16x32_bf16 v[108:111], v[128:131], v[192:195], v[108:111]
	v_mfma_f32_16x16x32_bf16 v[92:95], v[128:131], v[200:203], v[92:95]
	v_mfma_f32_16x16x32_bf16 v[92:95], v[132:135], v[204:207], v[92:95]
	v_mfma_f32_16x16x32_bf16 v[88:91], v[140:143], v[204:207], v[88:91]
	v_mfma_f32_16x16x32_bf16 v[88:91], v[136:139], v[200:203], v[88:91]
	v_mfma_f32_16x16x32_bf16 v[84:87], v[144:147], v[200:203], v[84:87]
	v_mfma_f32_16x16x32_bf16 v[84:87], v[148:151], v[204:207], v[84:87]
	v_mfma_f32_16x16x32_bf16 v[80:83], v[156:159], v[204:207], v[80:83]
	v_mfma_f32_16x16x32_bf16 v[80:83], v[152:155], v[200:203], v[80:83]
	v_mfma_f32_16x16x32_bf16 v[64:67], v[152:155], v[208:211], v[64:67]
	v_mfma_f32_16x16x32_bf16 v[64:67], v[156:159], v[212:215], v[64:67]
	v_mfma_f32_16x16x32_bf16 v[68:71], v[148:151], v[212:215], v[68:71]
	v_mfma_f32_16x16x32_bf16 v[68:71], v[144:147], v[208:211], v[68:71]
	v_mfma_f32_16x16x32_bf16 v[72:75], v[136:139], v[208:211], v[72:75]
	v_mfma_f32_16x16x32_bf16 v[72:75], v[140:143], v[212:215], v[72:75]
	v_mfma_f32_16x16x32_bf16 v[76:79], v[132:135], v[212:215], v[76:79]
	v_mfma_f32_16x16x32_bf16 v[76:79], v[128:131], v[208:211], v[76:79]
	s_barrier
	s_add_i32 s50, s54, s70
	v_lshl_add_u64 v[160:161], v[160:161], 0, s[36:37]
	s_mov_b32 m0, s50
	ds_read_b128 v[184:187], v224 offset:49152
	ds_read_b128 v[188:191], v224 offset:50176
	ds_read_b128 v[192:195], v224 offset:51200
	ds_read_b128 v[196:199], v224 offset:52224
	ds_read_b128 v[200:203], v224 offset:53248
	ds_read_b128 v[204:207], v224 offset:54272
	ds_read_b128 v[208:211], v224 offset:55296
	ds_read_b128 v[212:215], v224 offset:56320
	global_load_lds_dwordx4 v[160:161], off
	v_lshl_add_u64 v[160:161], v[216:217], 0, s[36:37]
	s_add_i32 m0, s50, 0x2000
	s_add_i32 s50, s55, s70
	global_load_lds_dwordx4 v[160:161], off
	v_lshl_add_u64 v[160:161], v[218:219], 0, s[36:37]
	s_mov_b32 m0, s50
	s_nop 0
	global_load_lds_dwordx4 v[160:161], off
	v_lshl_add_u64 v[160:161], v[230:231], 0, s[36:37]
	s_add_i32 m0, s50, 0x2000
	s_nop 0
	global_load_lds_dwordx4 v[160:161], off
	v_lshl_add_u64 v[160:161], v[232:233], 0, s[36:37]
	s_mov_b32 m0, s76
	s_nop 0
	global_load_lds_dwordx4 v[160:161], off
	v_lshl_add_u64 v[160:161], v[234:235], 0, s[36:37]
	s_mov_b32 m0, s77
	s_nop 0
	global_load_lds_dwordx4 v[160:161], off
	s_waitcnt vmcnt(8)
	s_waitcnt lgkmcnt(0)
	s_barrier
	s_waitcnt lgkmcnt(0)
	v_mfma_f32_16x16x32_bf16 v[60:63], v[128:131], v[184:187], v[60:63]
	v_mfma_f32_16x16x32_bf16 v[60:63], v[132:135], v[188:191], v[60:63]
	v_mfma_f32_16x16x32_bf16 v[56:59], v[140:143], v[188:191], v[56:59]
	v_mfma_f32_16x16x32_bf16 v[56:59], v[136:139], v[184:187], v[56:59]
	v_mfma_f32_16x16x32_bf16 v[52:55], v[144:147], v[184:187], v[52:55]
	v_mfma_f32_16x16x32_bf16 v[52:55], v[148:151], v[188:191], v[52:55]
	v_mfma_f32_16x16x32_bf16 v[48:51], v[156:159], v[188:191], v[48:51]
	v_mfma_f32_16x16x32_bf16 v[48:51], v[152:155], v[184:187], v[48:51]
	v_mfma_f32_16x16x32_bf16 v[32:35], v[152:155], v[192:195], v[32:35]
	v_mfma_f32_16x16x32_bf16 v[32:35], v[156:159], v[196:199], v[32:35]
	v_mfma_f32_16x16x32_bf16 v[36:39], v[148:151], v[196:199], v[36:39]
	v_mfma_f32_16x16x32_bf16 v[36:39], v[144:147], v[192:195], v[36:39]
	v_mfma_f32_16x16x32_bf16 v[40:43], v[136:139], v[192:195], v[40:43]
	v_mfma_f32_16x16x32_bf16 v[40:43], v[140:143], v[196:199], v[40:43]
	v_mfma_f32_16x16x32_bf16 v[44:47], v[132:135], v[196:199], v[44:47]
	v_mfma_f32_16x16x32_bf16 v[44:47], v[128:131], v[192:195], v[44:47]
	v_mfma_f32_16x16x32_bf16 v[28:31], v[128:131], v[200:203], v[28:31]
	v_mfma_f32_16x16x32_bf16 v[28:31], v[132:135], v[204:207], v[28:31]
	v_mfma_f32_16x16x32_bf16 v[24:27], v[140:143], v[204:207], v[24:27]
	v_mfma_f32_16x16x32_bf16 v[24:27], v[136:139], v[200:203], v[24:27]
	v_mfma_f32_16x16x32_bf16 v[20:23], v[144:147], v[200:203], v[20:23]
	v_mfma_f32_16x16x32_bf16 v[20:23], v[148:151], v[204:207], v[20:23]
	v_mfma_f32_16x16x32_bf16 v[16:19], v[156:159], v[204:207], v[16:19]
	v_mfma_f32_16x16x32_bf16 v[16:19], v[152:155], v[200:203], v[16:19]
	v_mfma_f32_16x16x32_bf16 v[0:3], v[152:155], v[208:211], v[0:3]
	v_mfma_f32_16x16x32_bf16 v[0:3], v[156:159], v[212:215], v[0:3]
	v_mfma_f32_16x16x32_bf16 v[4:7], v[148:151], v[212:215], v[4:7]
	v_mfma_f32_16x16x32_bf16 v[4:7], v[144:147], v[208:211], v[4:7]
	v_mfma_f32_16x16x32_bf16 v[8:11], v[136:139], v[208:211], v[8:11]
	v_mfma_f32_16x16x32_bf16 v[8:11], v[140:143], v[212:215], v[8:11]
	v_mfma_f32_16x16x32_bf16 v[12:15], v[132:135], v[212:215], v[12:15]
	v_mfma_f32_16x16x32_bf16 v[12:15], v[128:131], v[208:211], v[12:15]
	s_barrier
	s_add_u32 s0, s0, 0x100
	s_addc_u32 s1, s1, 0
	s_add_u32 s33, s33, 0x100
	s_addc_u32 s52, s52, 0
	s_cmp_ge_i32 s53, s75
	s_mov_b32 s50, s53
	s_cbranch_scc1 .Lpeel_exit_323

.Lpeel_exit_323:
.LBB0_324:
	s_and_b64 vcc, exec, s[40:41]
	s_cbranch_vccz .LBB0_326
	s_barrier

.Lzskip_3:
	s_add_u32 s30, s30, 0x80
	s_addc_u32 s31, s31, 0
	s_add_u32 s62, s34, 0x100
	s_addc_u32 s63, s35, 0
	s_mov_b32 s34, 0
	ds_read_b128 v[144:147], v157
	ds_read_b128 v[148:151], v157 offset:1024
	ds_read_b128 v[164:167], v157 offset:2048
	ds_read_b128 v[168:171], v157 offset:3072
	ds_read_b128 v[172:175], v158
	ds_read_b128 v[176:179], v158 offset:1024
	ds_read_b128 v[180:183], v158 offset:2048
	ds_read_b128 v[184:187], v158 offset:3072
	s_add_i32 s64, s34, 2
	s_add_u32 s65, s30, 0x80
	s_addc_u32 s35, s31, 0
	s_cmp_eq_u32 s49, s34
	s_cselect_b32 s34, s2, s65
	s_cselect_b32 s35, s3, s35
	s_cselect_b32 s67, s29, s63
	s_cselect_b32 s66, s28, s62
	v_lshl_add_u64 v[152:153], s[30:31], 0, v[136:137]
	s_add_i32 m0, s41, 0xc000
	ds_read_b128 v[188:191], v159
	ds_read_b128 v[192:195], v159 offset:1024
	ds_read_b128 v[196:199], v159 offset:2048
	ds_read_b128 v[200:203], v159 offset:3072
	ds_read_b128 v[204:207], v159 offset:4096
	ds_read_b128 v[208:211], v159 offset:5120
	ds_read_b128 v[212:215], v159 offset:6144
	ds_read_b128 v[216:219], v159 offset:7168
	global_load_lds_dwordx4 v[152:153], off
	v_lshl_add_u64 v[152:153], s[30:31], 0, v[138:139]
	s_add_i32 m0, s41, 0xe000
	s_nop 0
	global_load_lds_dwordx4 v[152:153], off
	s_waitcnt vmcnt(8)
	s_waitcnt lgkmcnt(0)
	s_barrier
	s_waitcnt lgkmcnt(0)
	v_mfma_f32_16x16x32_bf16 v[120:123], v[144:147], v[188:191], 0
	v_mfma_f32_16x16x32_bf16 v[120:123], v[148:151], v[192:195], v[120:123]
	v_mfma_f32_16x16x32_bf16 v[124:127], v[168:171], v[192:195], 0
	v_mfma_f32_16x16x32_bf16 v[124:127], v[164:167], v[188:191], v[124:127]
	v_mfma_f32_16x16x32_bf16 v[116:119], v[172:175], v[188:191], 0
	v_mfma_f32_16x16x32_bf16 v[116:119], v[176:179], v[192:195], v[116:119]
	v_mfma_f32_16x16x32_bf16 v[112:115], v[184:187], v[192:195], 0
	v_mfma_f32_16x16x32_bf16 v[112:115], v[180:183], v[188:191], v[112:115]
	v_mfma_f32_16x16x32_bf16 v[96:99], v[180:183], v[196:199], 0
	v_mfma_f32_16x16x32_bf16 v[96:99], v[184:187], v[200:203], v[96:99]
	v_mfma_f32_16x16x32_bf16 v[100:103], v[176:179], v[200:203], 0
	v_mfma_f32_16x16x32_bf16 v[100:103], v[172:175], v[196:199], v[100:103]
	v_mfma_f32_16x16x32_bf16 v[104:107], v[164:167], v[196:199], 0
	v_mfma_f32_16x16x32_bf16 v[104:107], v[168:171], v[200:203], v[104:107]
	v_mfma_f32_16x16x32_bf16 v[108:111], v[148:151], v[200:203], 0
	v_mfma_f32_16x16x32_bf16 v[108:111], v[144:147], v[196:199], v[108:111]
	v_mfma_f32_16x16x32_bf16 v[92:95], v[144:147], v[204:207], 0
	v_mfma_f32_16x16x32_bf16 v[92:95], v[148:151], v[208:211], v[92:95]
	v_mfma_f32_16x16x32_bf16 v[88:91], v[168:171], v[208:211], 0
	v_mfma_f32_16x16x32_bf16 v[88:91], v[164:167], v[204:207], v[88:91]
	v_mfma_f32_16x16x32_bf16 v[84:87], v[172:175], v[204:207], 0
	v_mfma_f32_16x16x32_bf16 v[84:87], v[176:179], v[208:211], v[84:87]
	v_mfma_f32_16x16x32_bf16 v[80:83], v[184:187], v[208:211], 0
	v_mfma_f32_16x16x32_bf16 v[80:83], v[180:183], v[204:207], v[80:83]
	v_mfma_f32_16x16x32_bf16 v[64:67], v[180:183], v[212:215], 0
	v_mfma_f32_16x16x32_bf16 v[64:67], v[184:187], v[216:219], v[64:67]
	v_mfma_f32_16x16x32_bf16 v[68:71], v[176:179], v[216:219], 0
	v_mfma_f32_16x16x32_bf16 v[68:71], v[172:175], v[212:215], v[68:71]
	v_mfma_f32_16x16x32_bf16 v[72:75], v[164:167], v[212:215], 0
	v_mfma_f32_16x16x32_bf16 v[72:75], v[168:171], v[216:219], v[72:75]
	v_mfma_f32_16x16x32_bf16 v[76:79], v[148:151], v[216:219], 0
	v_mfma_f32_16x16x32_bf16 v[76:79], v[144:147], v[212:215], v[76:79]
	s_barrier
	s_add_i32 s65, s52, s40
	v_lshl_add_u64 v[152:153], s[66:67], 0, v[130:131]
	s_mov_b32 m0, s65
	ds_read_b128 v[188:191], v159 offset:16384
	ds_read_b128 v[192:195], v159 offset:17408
	ds_read_b128 v[196:199], v159 offset:18432
	ds_read_b128 v[200:203], v159 offset:19456
	ds_read_b128 v[204:207], v159 offset:20480
	ds_read_b128 v[208:211], v159 offset:21504
	ds_read_b128 v[212:215], v159 offset:22528
	ds_read_b128 v[216:219], v159 offset:23552
	global_load_lds_dwordx4 v[152:153], off
	s_add_i32 m0, s65, 0x2000
	v_lshl_add_u64 v[160:161], s[66:67], 0, v[134:135]
	s_add_u32 s66, s66, s8
	s_addc_u32 s67, s67, s9
	s_add_i32 s65, s53, s40
	global_load_lds_dwordx4 v[160:161], off
	v_lshl_add_u64 v[222:223], s[66:67], 0, v[130:131]
	s_mov_b32 m0, s65
	v_lshl_add_u64 v[224:225], s[66:67], 0, v[134:135]
	global_load_lds_dwordx4 v[222:223], off
	s_add_i32 m0, s65, 0x2000
	v_lshl_add_u64 v[226:227], s[34:35], 0, v[128:129]
	global_load_lds_dwordx4 v[224:225], off
	s_mov_b32 m0, s41
	v_lshl_add_u64 v[228:229], s[34:35], 0, v[132:133]
	global_load_lds_dwordx4 v[226:227], off
	s_mov_b32 m0, s42
	s_nop 0
	global_load_lds_dwordx4 v[228:229], off
	s_waitcnt vmcnt(8)
	s_waitcnt lgkmcnt(0)
	s_barrier
	s_waitcnt lgkmcnt(0)
	v_mfma_f32_16x16x32_bf16 v[60:63], v[144:147], v[188:191], 0
	v_mfma_f32_16x16x32_bf16 v[60:63], v[148:151], v[192:195], v[60:63]
	v_mfma_f32_16x16x32_bf16 v[56:59], v[168:171], v[192:195], 0
	v_mfma_f32_16x16x32_bf16 v[56:59], v[164:167], v[188:191], v[56:59]
	v_mfma_f32_16x16x32_bf16 v[52:55], v[172:175], v[188:191], 0
	v_mfma_f32_16x16x32_bf16 v[52:55], v[176:179], v[192:195], v[52:55]
	v_mfma_f32_16x16x32_bf16 v[48:51], v[184:187], v[192:195], 0
	v_mfma_f32_16x16x32_bf16 v[48:51], v[180:183], v[188:191], v[48:51]
	v_mfma_f32_16x16x32_bf16 v[32:35], v[180:183], v[196:199], 0
	v_mfma_f32_16x16x32_bf16 v[32:35], v[184:187], v[200:203], v[32:35]
	v_mfma_f32_16x16x32_bf16 v[36:39], v[176:179], v[200:203], 0
	v_mfma_f32_16x16x32_bf16 v[36:39], v[172:175], v[196:199], v[36:39]
	v_mfma_f32_16x16x32_bf16 v[40:43], v[164:167], v[196:199], 0
	v_mfma_f32_16x16x32_bf16 v[40:43], v[168:171], v[200:203], v[40:43]
	v_mfma_f32_16x16x32_bf16 v[44:47], v[148:151], v[200:203], 0
	v_mfma_f32_16x16x32_bf16 v[44:47], v[144:147], v[196:199], v[44:47]
	v_mfma_f32_16x16x32_bf16 v[28:31], v[144:147], v[204:207], 0
	v_mfma_f32_16x16x32_bf16 v[28:31], v[148:151], v[208:211], v[28:31]
	v_mfma_f32_16x16x32_bf16 v[24:27], v[168:171], v[208:211], 0
	v_mfma_f32_16x16x32_bf16 v[24:27], v[164:167], v[204:207], v[24:27]
	v_mfma_f32_16x16x32_bf16 v[20:23], v[172:175], v[204:207], 0
	v_mfma_f32_16x16x32_bf16 v[20:23], v[176:179], v[208:211], v[20:23]
	v_mfma_f32_16x16x32_bf16 v[16:19], v[184:187], v[208:211], 0
	v_mfma_f32_16x16x32_bf16 v[16:19], v[180:183], v[204:207], v[16:19]
	v_mfma_f32_16x16x32_bf16 v[0:3], v[180:183], v[212:215], 0
	v_mfma_f32_16x16x32_bf16 v[0:3], v[184:187], v[216:219], v[0:3]
	v_mfma_f32_16x16x32_bf16 v[4:7], v[176:179], v[216:219], 0
	v_mfma_f32_16x16x32_bf16 v[4:7], v[172:175], v[212:215], v[4:7]
	v_mfma_f32_16x16x32_bf16 v[8:11], v[164:167], v[212:215], 0
	v_mfma_f32_16x16x32_bf16 v[8:11], v[168:171], v[216:219], v[8:11]
	v_mfma_f32_16x16x32_bf16 v[12:15], v[148:151], v[216:219], 0
	v_mfma_f32_16x16x32_bf16 v[12:15], v[144:147], v[212:215], v[12:15]
	s_barrier
	s_add_i32 s65, 0, 0x18000
	s_add_i32 s66, 0, 0x1c000
	v_add_u32_e32 v168, s65, v155
	v_add_u32_e32 v184, s66, v155
	ds_read_b128 v[144:147], v168
	ds_read_b128 v[148:151], v168 offset:1024
	ds_read_b128 v[164:167], v168 offset:2048
	ds_read_b128 v[168:171], v168 offset:3072
	ds_read_b128 v[172:175], v184
	ds_read_b128 v[176:179], v184 offset:1024
	ds_read_b128 v[180:183], v184 offset:2048
	ds_read_b128 v[184:187], v184 offset:3072
	s_add_u32 s34, s34, s8
	s_addc_u32 s35, s35, s9
	s_mov_b32 m0, s43
	v_lshl_add_u64 v[230:231], s[34:35], 0, v[128:129]
	ds_read_b128 v[188:191], v159 offset:32768
	ds_read_b128 v[192:195], v159 offset:33792
	ds_read_b128 v[196:199], v159 offset:34816
	ds_read_b128 v[200:203], v159 offset:35840
	ds_read_b128 v[204:207], v159 offset:36864
	ds_read_b128 v[208:211], v159 offset:37888
	ds_read_b128 v[212:215], v159 offset:38912
	ds_read_b128 v[216:219], v159 offset:39936
	global_load_lds_dwordx4 v[230:231], off
	v_lshl_add_u64 v[230:231], s[34:35], 0, v[132:133]
	s_mov_b32 m0, s44
	s_nop 0
	global_load_lds_dwordx4 v[230:231], off
	s_waitcnt vmcnt(8)
	s_waitcnt lgkmcnt(0)
	s_barrier
	s_waitcnt lgkmcnt(0)
	v_mfma_f32_16x16x32_bf16 v[120:123], v[144:147], v[188:191], v[120:123]
	v_mfma_f32_16x16x32_bf16 v[120:123], v[148:151], v[192:195], v[120:123]
	v_mfma_f32_16x16x32_bf16 v[124:127], v[168:171], v[192:195], v[124:127]
	v_mfma_f32_16x16x32_bf16 v[124:127], v[164:167], v[188:191], v[124:127]
	v_mfma_f32_16x16x32_bf16 v[116:119], v[172:175], v[188:191], v[116:119]
	v_mfma_f32_16x16x32_bf16 v[116:119], v[176:179], v[192:195], v[116:119]
	v_mfma_f32_16x16x32_bf16 v[112:115], v[184:187], v[192:195], v[112:115]
	v_mfma_f32_16x16x32_bf16 v[112:115], v[180:183], v[188:191], v[112:115]
	v_mfma_f32_16x16x32_bf16 v[96:99], v[180:183], v[196:199], v[96:99]
	v_mfma_f32_16x16x32_bf16 v[96:99], v[184:187], v[200:203], v[96:99]
	v_mfma_f32_16x16x32_bf16 v[100:103], v[176:179], v[200:203], v[100:103]
	v_mfma_f32_16x16x32_bf16 v[100:103], v[172:175], v[196:199], v[100:103]
	v_mfma_f32_16x16x32_bf16 v[104:107], v[164:167], v[196:199], v[104:107]
	v_mfma_f32_16x16x32_bf16 v[104:107], v[168:171], v[200:203], v[104:107]
	v_mfma_f32_16x16x32_bf16 v[108:111], v[148:151], v[200:203], v[108:111]
	v_mfma_f32_16x16x32_bf16 v[108:111], v[144:147], v[196:199], v[108:111]
	v_mfma_f32_16x16x32_bf16 v[92:95], v[144:147], v[204:207], v[92:95]
	v_mfma_f32_16x16x32_bf16 v[92:95], v[148:151], v[208:211], v[92:95]
	v_mfma_f32_16x16x32_bf16 v[88:91], v[168:171], v[208:211], v[88:91]
	v_mfma_f32_16x16x32_bf16 v[88:91], v[164:167], v[204:207], v[88:91]
	v_mfma_f32_16x16x32_bf16 v[84:87], v[172:175], v[204:207], v[84:87]
	v_mfma_f32_16x16x32_bf16 v[84:87], v[176:179], v[208:211], v[84:87]
	v_mfma_f32_16x16x32_bf16 v[80:83], v[184:187], v[208:211], v[80:83]
	v_mfma_f32_16x16x32_bf16 v[80:83], v[180:183], v[204:207], v[80:83]
	v_mfma_f32_16x16x32_bf16 v[64:67], v[180:183], v[212:215], v[64:67]
	v_mfma_f32_16x16x32_bf16 v[64:67], v[184:187], v[216:219], v[64:67]
	v_mfma_f32_16x16x32_bf16 v[68:71], v[176:179], v[216:219], v[68:71]
	v_mfma_f32_16x16x32_bf16 v[68:71], v[172:175], v[212:215], v[68:71]
	v_mfma_f32_16x16x32_bf16 v[72:75], v[164:167], v[212:215], v[72:75]
	v_mfma_f32_16x16x32_bf16 v[72:75], v[168:171], v[216:219], v[72:75]
	v_mfma_f32_16x16x32_bf16 v[76:79], v[148:151], v[216:219], v[76:79]
	v_mfma_f32_16x16x32_bf16 v[76:79], v[144:147], v[212:215], v[76:79]
	s_barrier
	s_add_i32 s34, s65, s40
	v_lshl_add_u64 v[152:153], v[152:153], 0, s[14:15]
	s_mov_b32 m0, s34
	ds_read_b128 v[188:191], v159 offset:49152
	ds_read_b128 v[192:195], v159 offset:50176
	ds_read_b128 v[196:199], v159 offset:51200
	ds_read_b128 v[200:203], v159 offset:52224
	ds_read_b128 v[204:207], v159 offset:53248
	ds_read_b128 v[208:211], v159 offset:54272
	ds_read_b128 v[212:215], v159 offset:55296
	ds_read_b128 v[216:219], v159 offset:56320
	global_load_lds_dwordx4 v[152:153], off
	v_lshl_add_u64 v[152:153], v[160:161], 0, s[14:15]
	s_add_i32 m0, s34, 0x2000
	s_add_i32 s34, s66, s40
	global_load_lds_dwordx4 v[152:153], off
	v_lshl_add_u64 v[152:153], v[222:223], 0, s[14:15]
	s_mov_b32 m0, s34
	s_nop 0
	global_load_lds_dwordx4 v[152:153], off
	v_lshl_add_u64 v[152:153], v[224:225], 0, s[14:15]
	s_add_i32 m0, s34, 0x2000
	s_nop 0
	global_load_lds_dwordx4 v[152:153], off
	v_lshl_add_u64 v[152:153], v[226:227], 0, s[14:15]
	s_mov_b32 m0, s46
	s_nop 0
	global_load_lds_dwordx4 v[152:153], off
	v_lshl_add_u64 v[152:153], v[228:229], 0, s[14:15]
	s_mov_b32 m0, s47
	s_nop 0
	global_load_lds_dwordx4 v[152:153], off
	s_waitcnt vmcnt(8)
	s_waitcnt lgkmcnt(0)
	s_barrier
	s_waitcnt lgkmcnt(0)
	v_mfma_f32_16x16x32_bf16 v[60:63], v[144:147], v[188:191], v[60:63]
	v_mfma_f32_16x16x32_bf16 v[60:63], v[148:151], v[192:195], v[60:63]
	v_mfma_f32_16x16x32_bf16 v[56:59], v[168:171], v[192:195], v[56:59]
	v_mfma_f32_16x16x32_bf16 v[56:59], v[164:167], v[188:191], v[56:59]
	v_mfma_f32_16x16x32_bf16 v[52:55], v[172:175], v[188:191], v[52:55]
	v_mfma_f32_16x16x32_bf16 v[52:55], v[176:179], v[192:195], v[52:55]
	v_mfma_f32_16x16x32_bf16 v[48:51], v[184:187], v[192:195], v[48:51]
	v_mfma_f32_16x16x32_bf16 v[48:51], v[180:183], v[188:191], v[48:51]
	v_mfma_f32_16x16x32_bf16 v[32:35], v[180:183], v[196:199], v[32:35]
	v_mfma_f32_16x16x32_bf16 v[32:35], v[184:187], v[200:203], v[32:35]
	v_mfma_f32_16x16x32_bf16 v[36:39], v[176:179], v[200:203], v[36:39]
	v_mfma_f32_16x16x32_bf16 v[36:39], v[172:175], v[196:199], v[36:39]
	v_mfma_f32_16x16x32_bf16 v[40:43], v[164:167], v[196:199], v[40:43]
	v_mfma_f32_16x16x32_bf16 v[40:43], v[168:171], v[200:203], v[40:43]
	v_mfma_f32_16x16x32_bf16 v[44:47], v[148:151], v[200:203], v[44:47]
	v_mfma_f32_16x16x32_bf16 v[44:47], v[144:147], v[196:199], v[44:47]
	v_mfma_f32_16x16x32_bf16 v[28:31], v[144:147], v[204:207], v[28:31]
	v_mfma_f32_16x16x32_bf16 v[28:31], v[148:151], v[208:211], v[28:31]
	v_mfma_f32_16x16x32_bf16 v[24:27], v[168:171], v[208:211], v[24:27]
	v_mfma_f32_16x16x32_bf16 v[24:27], v[164:167], v[204:207], v[24:27]
	v_mfma_f32_16x16x32_bf16 v[20:23], v[172:175], v[204:207], v[20:23]
	v_mfma_f32_16x16x32_bf16 v[20:23], v[176:179], v[208:211], v[20:23]
	v_mfma_f32_16x16x32_bf16 v[16:19], v[184:187], v[208:211], v[16:19]
	v_mfma_f32_16x16x32_bf16 v[16:19], v[180:183], v[204:207], v[16:19]
	v_mfma_f32_16x16x32_bf16 v[0:3], v[180:183], v[212:215], v[0:3]
	v_mfma_f32_16x16x32_bf16 v[0:3], v[184:187], v[216:219], v[0:3]
	v_mfma_f32_16x16x32_bf16 v[4:7], v[176:179], v[216:219], v[4:7]
	v_mfma_f32_16x16x32_bf16 v[4:7], v[172:175], v[212:215], v[4:7]
	v_mfma_f32_16x16x32_bf16 v[8:11], v[164:167], v[212:215], v[8:11]
	v_mfma_f32_16x16x32_bf16 v[8:11], v[168:171], v[216:219], v[8:11]
	v_mfma_f32_16x16x32_bf16 v[12:15], v[148:151], v[216:219], v[12:15]
	v_mfma_f32_16x16x32_bf16 v[12:15], v[144:147], v[212:215], v[12:15]
	s_barrier
	s_add_u32 s30, s30, 0x100
	s_addc_u32 s31, s31, 0
	s_add_u32 s62, s62, 0x100
	s_addc_u32 s63, s63, 0
	s_cmp_ge_i32 s64, s48
	s_mov_b32 s34, s64
	s_cbranch_scc1 .Lpeel_exit_592

.Lpeel_exit_592:
.LBB0_593:
	s_and_b64 vcc, exec, s[18:19]
	s_cbranch_vccz .LBB0_595
	s_barrier

.Lzskip_4:
	s_add_u32 s24, s24, 0x80
	s_addc_u32 s25, s25, 0
	s_add_u32 s52, s26, 0x100
	s_addc_u32 s53, s27, 0
	s_mov_b32 s26, 0
	ds_read_b128 v[128:131], v181
	ds_read_b128 v[132:135], v181 offset:1024
	ds_read_b128 v[136:139], v181 offset:2048
	ds_read_b128 v[140:143], v181 offset:3072
	ds_read_b128 v[144:147], v182
	ds_read_b128 v[148:151], v182 offset:1024
	ds_read_b128 v[168:171], v182 offset:2048
	ds_read_b128 v[172:175], v182 offset:3072
	s_add_i32 s54, s26, 2
	s_add_u32 s55, s24, 0x80
	s_addc_u32 s27, s25, 0
	s_cmp_eq_u32 s43, s26
	s_cselect_b32 s26, s2, s55
	s_cselect_b32 s27, s3, s27
	s_cselect_b32 s61, s23, s53
	s_cselect_b32 s60, s22, s52
	v_lshl_add_u64 v[176:177], s[24:25], 0, v[160:161]
	s_add_i32 m0, s35, 0xc000
	ds_read_b128 v[184:187], v183
	ds_read_b128 v[188:191], v183 offset:1024
	ds_read_b128 v[192:195], v183 offset:2048
	ds_read_b128 v[196:199], v183 offset:3072
	ds_read_b128 v[200:203], v183 offset:4096
	ds_read_b128 v[204:207], v183 offset:5120
	ds_read_b128 v[208:211], v183 offset:6144
	ds_read_b128 v[212:215], v183 offset:7168
	global_load_lds_dwordx4 v[176:177], off
	v_lshl_add_u64 v[176:177], s[24:25], 0, v[162:163]
	s_add_i32 m0, s35, 0xe000
	s_nop 0
	global_load_lds_dwordx4 v[176:177], off
	s_waitcnt vmcnt(8)
	s_waitcnt lgkmcnt(0)
	s_barrier
	s_waitcnt lgkmcnt(0)
	v_mfma_f32_16x16x32_bf16 v[120:123], v[128:131], v[184:187], 0
	v_mfma_f32_16x16x32_bf16 v[120:123], v[132:135], v[188:191], v[120:123]
	v_mfma_f32_16x16x32_bf16 v[124:127], v[140:143], v[188:191], 0
	v_mfma_f32_16x16x32_bf16 v[124:127], v[136:139], v[184:187], v[124:127]
	v_mfma_f32_16x16x32_bf16 v[116:119], v[144:147], v[184:187], 0
	v_mfma_f32_16x16x32_bf16 v[116:119], v[148:151], v[188:191], v[116:119]
	v_mfma_f32_16x16x32_bf16 v[112:115], v[172:175], v[188:191], 0
	v_mfma_f32_16x16x32_bf16 v[112:115], v[168:171], v[184:187], v[112:115]
	v_mfma_f32_16x16x32_bf16 v[96:99], v[168:171], v[192:195], 0
	v_mfma_f32_16x16x32_bf16 v[96:99], v[172:175], v[196:199], v[96:99]
	v_mfma_f32_16x16x32_bf16 v[100:103], v[148:151], v[196:199], 0
	v_mfma_f32_16x16x32_bf16 v[100:103], v[144:147], v[192:195], v[100:103]
	v_mfma_f32_16x16x32_bf16 v[104:107], v[136:139], v[192:195], 0
	v_mfma_f32_16x16x32_bf16 v[104:107], v[140:143], v[196:199], v[104:107]
	v_mfma_f32_16x16x32_bf16 v[108:111], v[132:135], v[196:199], 0
	v_mfma_f32_16x16x32_bf16 v[108:111], v[128:131], v[192:195], v[108:111]
	v_mfma_f32_16x16x32_bf16 v[92:95], v[128:131], v[200:203], 0
	v_mfma_f32_16x16x32_bf16 v[92:95], v[132:135], v[204:207], v[92:95]
	v_mfma_f32_16x16x32_bf16 v[88:91], v[140:143], v[204:207], 0
	v_mfma_f32_16x16x32_bf16 v[88:91], v[136:139], v[200:203], v[88:91]
	v_mfma_f32_16x16x32_bf16 v[84:87], v[144:147], v[200:203], 0
	v_mfma_f32_16x16x32_bf16 v[84:87], v[148:151], v[204:207], v[84:87]
	v_mfma_f32_16x16x32_bf16 v[80:83], v[172:175], v[204:207], 0
	v_mfma_f32_16x16x32_bf16 v[80:83], v[168:171], v[200:203], v[80:83]
	v_mfma_f32_16x16x32_bf16 v[64:67], v[168:171], v[208:211], 0
	v_mfma_f32_16x16x32_bf16 v[64:67], v[172:175], v[212:215], v[64:67]
	v_mfma_f32_16x16x32_bf16 v[68:71], v[148:151], v[212:215], 0
	v_mfma_f32_16x16x32_bf16 v[68:71], v[144:147], v[208:211], v[68:71]
	v_mfma_f32_16x16x32_bf16 v[72:75], v[136:139], v[208:211], 0
	v_mfma_f32_16x16x32_bf16 v[72:75], v[140:143], v[212:215], v[72:75]
	v_mfma_f32_16x16x32_bf16 v[76:79], v[132:135], v[212:215], 0
	v_mfma_f32_16x16x32_bf16 v[76:79], v[128:131], v[208:211], v[76:79]
	s_barrier
	s_add_i32 s55, s46, s34
	v_lshl_add_u64 v[176:177], s[60:61], 0, v[154:155]
	s_mov_b32 m0, s55
	ds_read_b128 v[184:187], v183 offset:16384
	ds_read_b128 v[188:191], v183 offset:17408
	ds_read_b128 v[192:195], v183 offset:18432
	ds_read_b128 v[196:199], v183 offset:19456
	ds_read_b128 v[200:203], v183 offset:20480
	ds_read_b128 v[204:207], v183 offset:21504
	ds_read_b128 v[208:211], v183 offset:22528
	ds_read_b128 v[212:215], v183 offset:23552
	global_load_lds_dwordx4 v[176:177], off
	s_add_i32 m0, s55, 0x2000
	v_lshl_add_u64 v[216:217], s[60:61], 0, v[158:159]
	s_add_u32 s60, s60, s8
	s_addc_u32 s61, s61, s9
	s_add_i32 s55, s47, s34
	global_load_lds_dwordx4 v[216:217], off
	v_lshl_add_u64 v[218:219], s[60:61], 0, v[154:155]
	s_mov_b32 m0, s55
	v_lshl_add_u64 v[222:223], s[60:61], 0, v[158:159]
	global_load_lds_dwordx4 v[218:219], off
	s_add_i32 m0, s55, 0x2000
	v_lshl_add_u64 v[224:225], s[26:27], 0, v[152:153]
	global_load_lds_dwordx4 v[222:223], off
	s_mov_b32 m0, s35
	v_lshl_add_u64 v[226:227], s[26:27], 0, v[156:157]
	global_load_lds_dwordx4 v[224:225], off
	s_mov_b32 m0, s36
	s_nop 0
	global_load_lds_dwordx4 v[226:227], off
	s_waitcnt vmcnt(8)
	s_waitcnt lgkmcnt(0)
	s_barrier
	s_waitcnt lgkmcnt(0)
	v_mfma_f32_16x16x32_bf16 v[60:63], v[128:131], v[184:187], 0
	v_mfma_f32_16x16x32_bf16 v[60:63], v[132:135], v[188:191], v[60:63]
	v_mfma_f32_16x16x32_bf16 v[56:59], v[140:143], v[188:191], 0
	v_mfma_f32_16x16x32_bf16 v[56:59], v[136:139], v[184:187], v[56:59]
	v_mfma_f32_16x16x32_bf16 v[52:55], v[144:147], v[184:187], 0
	v_mfma_f32_16x16x32_bf16 v[52:55], v[148:151], v[188:191], v[52:55]
	v_mfma_f32_16x16x32_bf16 v[48:51], v[172:175], v[188:191], 0
	v_mfma_f32_16x16x32_bf16 v[48:51], v[168:171], v[184:187], v[48:51]
	v_mfma_f32_16x16x32_bf16 v[32:35], v[168:171], v[192:195], 0
	v_mfma_f32_16x16x32_bf16 v[32:35], v[172:175], v[196:199], v[32:35]
	v_mfma_f32_16x16x32_bf16 v[36:39], v[148:151], v[196:199], 0
	v_mfma_f32_16x16x32_bf16 v[36:39], v[144:147], v[192:195], v[36:39]
	v_mfma_f32_16x16x32_bf16 v[40:43], v[136:139], v[192:195], 0
	v_mfma_f32_16x16x32_bf16 v[40:43], v[140:143], v[196:199], v[40:43]
	v_mfma_f32_16x16x32_bf16 v[44:47], v[132:135], v[196:199], 0
	v_mfma_f32_16x16x32_bf16 v[44:47], v[128:131], v[192:195], v[44:47]
	v_mfma_f32_16x16x32_bf16 v[28:31], v[128:131], v[200:203], 0
	v_mfma_f32_16x16x32_bf16 v[28:31], v[132:135], v[204:207], v[28:31]
	v_mfma_f32_16x16x32_bf16 v[24:27], v[140:143], v[204:207], 0
	v_mfma_f32_16x16x32_bf16 v[24:27], v[136:139], v[200:203], v[24:27]
	v_mfma_f32_16x16x32_bf16 v[20:23], v[144:147], v[200:203], 0
	v_mfma_f32_16x16x32_bf16 v[20:23], v[148:151], v[204:207], v[20:23]
	v_mfma_f32_16x16x32_bf16 v[16:19], v[172:175], v[204:207], 0
	v_mfma_f32_16x16x32_bf16 v[16:19], v[168:171], v[200:203], v[16:19]
	v_mfma_f32_16x16x32_bf16 v[0:3], v[168:171], v[208:211], 0
	v_mfma_f32_16x16x32_bf16 v[0:3], v[172:175], v[212:215], v[0:3]
	v_mfma_f32_16x16x32_bf16 v[4:7], v[148:151], v[212:215], 0
	v_mfma_f32_16x16x32_bf16 v[4:7], v[144:147], v[208:211], v[4:7]
	v_mfma_f32_16x16x32_bf16 v[8:11], v[136:139], v[208:211], 0
	v_mfma_f32_16x16x32_bf16 v[8:11], v[140:143], v[212:215], v[8:11]
	v_mfma_f32_16x16x32_bf16 v[12:15], v[132:135], v[212:215], 0
	v_mfma_f32_16x16x32_bf16 v[12:15], v[128:131], v[208:211], v[12:15]
	s_barrier
	s_add_i32 s55, 0, 0x18000
	s_add_i32 s60, 0, 0x1c000
	v_add_u32_e32 v140, s55, v179
	v_add_u32_e32 v172, s60, v179
	ds_read_b128 v[128:131], v140
	ds_read_b128 v[132:135], v140 offset:1024
	ds_read_b128 v[136:139], v140 offset:2048
	ds_read_b128 v[140:143], v140 offset:3072
	ds_read_b128 v[144:147], v172
	ds_read_b128 v[148:151], v172 offset:1024
	ds_read_b128 v[168:171], v172 offset:2048
	ds_read_b128 v[172:175], v172 offset:3072
	s_add_u32 s26, s26, s8
	s_addc_u32 s27, s27, s9
	s_mov_b32 m0, s37
	v_lshl_add_u64 v[228:229], s[26:27], 0, v[152:153]
	ds_read_b128 v[184:187], v183 offset:32768
	ds_read_b128 v[188:191], v183 offset:33792
	ds_read_b128 v[192:195], v183 offset:34816
	ds_read_b128 v[196:199], v183 offset:35840
	ds_read_b128 v[200:203], v183 offset:36864
	ds_read_b128 v[204:207], v183 offset:37888
	ds_read_b128 v[208:211], v183 offset:38912
	ds_read_b128 v[212:215], v183 offset:39936
	global_load_lds_dwordx4 v[228:229], off
	v_lshl_add_u64 v[228:229], s[26:27], 0, v[156:157]
	s_mov_b32 m0, s38
	s_nop 0
	global_load_lds_dwordx4 v[228:229], off
	s_waitcnt vmcnt(8)
	s_waitcnt lgkmcnt(0)
	s_barrier
	s_waitcnt lgkmcnt(0)
	v_mfma_f32_16x16x32_bf16 v[120:123], v[128:131], v[184:187], v[120:123]
	v_mfma_f32_16x16x32_bf16 v[120:123], v[132:135], v[188:191], v[120:123]
	v_mfma_f32_16x16x32_bf16 v[124:127], v[140:143], v[188:191], v[124:127]
	v_mfma_f32_16x16x32_bf16 v[124:127], v[136:139], v[184:187], v[124:127]
	v_mfma_f32_16x16x32_bf16 v[116:119], v[144:147], v[184:187], v[116:119]
	v_mfma_f32_16x16x32_bf16 v[116:119], v[148:151], v[188:191], v[116:119]
	v_mfma_f32_16x16x32_bf16 v[112:115], v[172:175], v[188:191], v[112:115]
	v_mfma_f32_16x16x32_bf16 v[112:115], v[168:171], v[184:187], v[112:115]
	v_mfma_f32_16x16x32_bf16 v[96:99], v[168:171], v[192:195], v[96:99]
	v_mfma_f32_16x16x32_bf16 v[96:99], v[172:175], v[196:199], v[96:99]
	v_mfma_f32_16x16x32_bf16 v[100:103], v[148:151], v[196:199], v[100:103]
	v_mfma_f32_16x16x32_bf16 v[100:103], v[144:147], v[192:195], v[100:103]
	v_mfma_f32_16x16x32_bf16 v[104:107], v[136:139], v[192:195], v[104:107]
	v_mfma_f32_16x16x32_bf16 v[104:107], v[140:143], v[196:199], v[104:107]
	v_mfma_f32_16x16x32_bf16 v[108:111], v[132:135], v[196:199], v[108:111]
	v_mfma_f32_16x16x32_bf16 v[108:111], v[128:131], v[192:195], v[108:111]
	v_mfma_f32_16x16x32_bf16 v[92:95], v[128:131], v[200:203], v[92:95]
	v_mfma_f32_16x16x32_bf16 v[92:95], v[132:135], v[204:207], v[92:95]
	v_mfma_f32_16x16x32_bf16 v[88:91], v[140:143], v[204:207], v[88:91]
	v_mfma_f32_16x16x32_bf16 v[88:91], v[136:139], v[200:203], v[88:91]
	v_mfma_f32_16x16x32_bf16 v[84:87], v[144:147], v[200:203], v[84:87]
	v_mfma_f32_16x16x32_bf16 v[84:87], v[148:151], v[204:207], v[84:87]
	v_mfma_f32_16x16x32_bf16 v[80:83], v[172:175], v[204:207], v[80:83]
	v_mfma_f32_16x16x32_bf16 v[80:83], v[168:171], v[200:203], v[80:83]
	v_mfma_f32_16x16x32_bf16 v[64:67], v[168:171], v[208:211], v[64:67]
	v_mfma_f32_16x16x32_bf16 v[64:67], v[172:175], v[212:215], v[64:67]
	v_mfma_f32_16x16x32_bf16 v[68:71], v[148:151], v[212:215], v[68:71]
	v_mfma_f32_16x16x32_bf16 v[68:71], v[144:147], v[208:211], v[68:71]
	v_mfma_f32_16x16x32_bf16 v[72:75], v[136:139], v[208:211], v[72:75]
	v_mfma_f32_16x16x32_bf16 v[72:75], v[140:143], v[212:215], v[72:75]
	v_mfma_f32_16x16x32_bf16 v[76:79], v[132:135], v[212:215], v[76:79]
	v_mfma_f32_16x16x32_bf16 v[76:79], v[128:131], v[208:211], v[76:79]
	s_barrier
	s_add_i32 s26, s55, s34
	v_lshl_add_u64 v[176:177], v[176:177], 0, s[16:17]
	s_mov_b32 m0, s26
	ds_read_b128 v[184:187], v183 offset:49152
	ds_read_b128 v[188:191], v183 offset:50176
	ds_read_b128 v[192:195], v183 offset:51200
	ds_read_b128 v[196:199], v183 offset:52224
	ds_read_b128 v[200:203], v183 offset:53248
	ds_read_b128 v[204:207], v183 offset:54272
	ds_read_b128 v[208:211], v183 offset:55296
	ds_read_b128 v[212:215], v183 offset:56320
	global_load_lds_dwordx4 v[176:177], off
	v_lshl_add_u64 v[176:177], v[216:217], 0, s[16:17]
	s_add_i32 m0, s26, 0x2000
	s_add_i32 s26, s60, s34
	global_load_lds_dwordx4 v[176:177], off
	v_lshl_add_u64 v[176:177], v[218:219], 0, s[16:17]
	s_mov_b32 m0, s26
	s_nop 0
	global_load_lds_dwordx4 v[176:177], off
	v_lshl_add_u64 v[176:177], v[222:223], 0, s[16:17]
	s_add_i32 m0, s26, 0x2000
	s_nop 0
	global_load_lds_dwordx4 v[176:177], off
	v_lshl_add_u64 v[176:177], v[224:225], 0, s[16:17]
	s_mov_b32 m0, s40
	s_nop 0
	global_load_lds_dwordx4 v[176:177], off
	v_lshl_add_u64 v[176:177], v[226:227], 0, s[16:17]
	s_mov_b32 m0, s41
	s_nop 0
	global_load_lds_dwordx4 v[176:177], off
	s_waitcnt vmcnt(8)
	s_waitcnt lgkmcnt(0)
	s_barrier
	s_waitcnt lgkmcnt(0)
	v_mfma_f32_16x16x32_bf16 v[60:63], v[128:131], v[184:187], v[60:63]
	v_mfma_f32_16x16x32_bf16 v[60:63], v[132:135], v[188:191], v[60:63]
	v_mfma_f32_16x16x32_bf16 v[56:59], v[140:143], v[188:191], v[56:59]
	v_mfma_f32_16x16x32_bf16 v[56:59], v[136:139], v[184:187], v[56:59]
	v_mfma_f32_16x16x32_bf16 v[52:55], v[144:147], v[184:187], v[52:55]
	v_mfma_f32_16x16x32_bf16 v[52:55], v[148:151], v[188:191], v[52:55]
	v_mfma_f32_16x16x32_bf16 v[48:51], v[172:175], v[188:191], v[48:51]
	v_mfma_f32_16x16x32_bf16 v[48:51], v[168:171], v[184:187], v[48:51]
	v_mfma_f32_16x16x32_bf16 v[32:35], v[168:171], v[192:195], v[32:35]
	v_mfma_f32_16x16x32_bf16 v[32:35], v[172:175], v[196:199], v[32:35]
	v_mfma_f32_16x16x32_bf16 v[36:39], v[148:151], v[196:199], v[36:39]
	v_mfma_f32_16x16x32_bf16 v[36:39], v[144:147], v[192:195], v[36:39]
	v_mfma_f32_16x16x32_bf16 v[40:43], v[136:139], v[192:195], v[40:43]
	v_mfma_f32_16x16x32_bf16 v[40:43], v[140:143], v[196:199], v[40:43]
	v_mfma_f32_16x16x32_bf16 v[44:47], v[132:135], v[196:199], v[44:47]
	v_mfma_f32_16x16x32_bf16 v[44:47], v[128:131], v[192:195], v[44:47]
	v_mfma_f32_16x16x32_bf16 v[28:31], v[128:131], v[200:203], v[28:31]
	v_mfma_f32_16x16x32_bf16 v[28:31], v[132:135], v[204:207], v[28:31]
	v_mfma_f32_16x16x32_bf16 v[24:27], v[140:143], v[204:207], v[24:27]
	v_mfma_f32_16x16x32_bf16 v[24:27], v[136:139], v[200:203], v[24:27]
	v_mfma_f32_16x16x32_bf16 v[20:23], v[144:147], v[200:203], v[20:23]
	v_mfma_f32_16x16x32_bf16 v[20:23], v[148:151], v[204:207], v[20:23]
	v_mfma_f32_16x16x32_bf16 v[16:19], v[172:175], v[204:207], v[16:19]
	v_mfma_f32_16x16x32_bf16 v[16:19], v[168:171], v[200:203], v[16:19]
	v_mfma_f32_16x16x32_bf16 v[0:3], v[168:171], v[208:211], v[0:3]
	v_mfma_f32_16x16x32_bf16 v[0:3], v[172:175], v[212:215], v[0:3]
	v_mfma_f32_16x16x32_bf16 v[4:7], v[148:151], v[212:215], v[4:7]
	v_mfma_f32_16x16x32_bf16 v[4:7], v[144:147], v[208:211], v[4:7]
	v_mfma_f32_16x16x32_bf16 v[8:11], v[136:139], v[208:211], v[8:11]
	v_mfma_f32_16x16x32_bf16 v[8:11], v[140:143], v[212:215], v[8:11]
	v_mfma_f32_16x16x32_bf16 v[12:15], v[132:135], v[212:215], v[12:15]
	v_mfma_f32_16x16x32_bf16 v[12:15], v[128:131], v[208:211], v[12:15]
	s_barrier
	s_add_u32 s24, s24, 0x100
	s_addc_u32 s25, s25, 0
	s_add_u32 s52, s52, 0x100
	s_addc_u32 s53, s53, 0
	s_cmp_ge_i32 s54, s42
	s_mov_b32 s26, s54
	s_cbranch_scc1 .Lpeel_exit_763

.Lpeel_exit_763:
.LBB0_764:
	s_and_b64 vcc, exec, s[20:21]
	s_cbranch_vccz .LBB0_766
	s_barrier

.Lzskip_5:
	s_add_u32 s28, s28, 0x80
	s_addc_u32 s29, s29, 0
	s_add_u32 s60, s30, 0x100
	s_addc_u32 s61, s31, 0
	s_mov_b32 s30, 0
	ds_read_b128 v[112:115], v209
	ds_read_b128 v[116:119], v209 offset:1024
	ds_read_b128 v[120:123], v209 offset:2048
	ds_read_b128 v[128:131], v209 offset:3072
	ds_read_b128 v[144:147], v210
	ds_read_b128 v[148:151], v210 offset:1024
	ds_read_b128 v[152:155], v210 offset:2048
	ds_read_b128 v[156:159], v210 offset:3072
	s_add_i32 s62, s30, 2
	s_add_u32 s63, s28, 0x80
	s_addc_u32 s31, s29, 0
	s_cmp_eq_u32 s46, s30
	s_cselect_b32 s30, s4, s63
	s_cselect_b32 s31, s5, s31
	s_cselect_b32 s65, s27, s61
	s_cselect_b32 s64, s26, s60
	v_lshl_add_u64 v[204:205], s[28:29], 0, v[180:181]
	s_add_i32 m0, s38, 0xc000
	ds_read_b128 v[160:163], v211
	ds_read_b128 v[164:167], v211 offset:1024
	ds_read_b128 v[168:171], v211 offset:2048
	ds_read_b128 v[172:175], v211 offset:3072
	ds_read_b128 v[188:191], v211 offset:4096
	ds_read_b128 v[192:195], v211 offset:5120
	ds_read_b128 v[196:199], v211 offset:6144
	ds_read_b128 v[200:203], v211 offset:7168
	global_load_lds_dwordx4 v[204:205], off
	v_lshl_add_u64 v[204:205], s[28:29], 0, v[182:183]
	s_add_i32 m0, s38, 0xe000
	s_nop 0
	global_load_lds_dwordx4 v[204:205], off
	s_waitcnt vmcnt(8)
	s_waitcnt lgkmcnt(0)
	s_barrier
	s_waitcnt lgkmcnt(0)
	v_mfma_f32_16x16x32_bf16 v[136:139], v[112:115], v[160:163], 0
	v_mfma_f32_16x16x32_bf16 v[136:139], v[116:119], v[164:167], v[136:139]
	v_mfma_f32_16x16x32_bf16 v[140:143], v[128:131], v[164:167], 0
	v_mfma_f32_16x16x32_bf16 v[140:143], v[120:123], v[160:163], v[140:143]
	v_mfma_f32_16x16x32_bf16 v[132:135], v[144:147], v[160:163], 0
	v_mfma_f32_16x16x32_bf16 v[132:135], v[148:151], v[164:167], v[132:135]
	v_mfma_f32_16x16x32_bf16 v[124:127], v[156:159], v[164:167], 0
	v_mfma_f32_16x16x32_bf16 v[124:127], v[152:155], v[160:163], v[124:127]
	v_mfma_f32_16x16x32_bf16 v[96:99], v[152:155], v[168:171], 0
	v_mfma_f32_16x16x32_bf16 v[96:99], v[156:159], v[172:175], v[96:99]
	v_mfma_f32_16x16x32_bf16 v[100:103], v[148:151], v[172:175], 0
	v_mfma_f32_16x16x32_bf16 v[100:103], v[144:147], v[168:171], v[100:103]
	v_mfma_f32_16x16x32_bf16 v[104:107], v[120:123], v[168:171], 0
	v_mfma_f32_16x16x32_bf16 v[104:107], v[128:131], v[172:175], v[104:107]
	v_mfma_f32_16x16x32_bf16 v[108:111], v[116:119], v[172:175], 0
	v_mfma_f32_16x16x32_bf16 v[108:111], v[112:115], v[168:171], v[108:111]
	v_mfma_f32_16x16x32_bf16 v[92:95], v[112:115], v[188:191], 0
	v_mfma_f32_16x16x32_bf16 v[92:95], v[116:119], v[192:195], v[92:95]
	v_mfma_f32_16x16x32_bf16 v[88:91], v[128:131], v[192:195], 0
	v_mfma_f32_16x16x32_bf16 v[88:91], v[120:123], v[188:191], v[88:91]
	v_mfma_f32_16x16x32_bf16 v[84:87], v[144:147], v[188:191], 0
	v_mfma_f32_16x16x32_bf16 v[84:87], v[148:151], v[192:195], v[84:87]
	v_mfma_f32_16x16x32_bf16 v[80:83], v[156:159], v[192:195], 0
	v_mfma_f32_16x16x32_bf16 v[80:83], v[152:155], v[188:191], v[80:83]
	v_mfma_f32_16x16x32_bf16 v[64:67], v[152:155], v[196:199], 0
	v_mfma_f32_16x16x32_bf16 v[64:67], v[156:159], v[200:203], v[64:67]
	v_mfma_f32_16x16x32_bf16 v[68:71], v[148:151], v[200:203], 0
	v_mfma_f32_16x16x32_bf16 v[68:71], v[144:147], v[196:199], v[68:71]
	v_mfma_f32_16x16x32_bf16 v[72:75], v[120:123], v[196:199], 0
	v_mfma_f32_16x16x32_bf16 v[72:75], v[128:131], v[200:203], v[72:75]
	v_mfma_f32_16x16x32_bf16 v[76:79], v[116:119], v[200:203], 0
	v_mfma_f32_16x16x32_bf16 v[76:79], v[112:115], v[196:199], v[76:79]
	s_barrier
	s_add_i32 s63, s50, s37
	v_lshl_add_u64 v[204:205], s[64:65], 0, v[176:177]
	s_mov_b32 m0, s63
	ds_read_b128 v[160:163], v211 offset:16384
	ds_read_b128 v[164:167], v211 offset:17408
	ds_read_b128 v[168:171], v211 offset:18432
	ds_read_b128 v[172:175], v211 offset:19456
	ds_read_b128 v[188:191], v211 offset:20480
	ds_read_b128 v[192:195], v211 offset:21504
	ds_read_b128 v[196:199], v211 offset:22528
	ds_read_b128 v[200:203], v211 offset:23552
	global_load_lds_dwordx4 v[204:205], off
	s_add_i32 m0, s63, 0x2000
	v_lshl_add_u64 v[214:215], s[64:65], 0, v[178:179]
	s_add_u32 s64, s64, s10
	s_addc_u32 s65, s65, s11
	s_add_i32 s63, s51, s37
	global_load_lds_dwordx4 v[214:215], off
	v_lshl_add_u64 v[216:217], s[64:65], 0, v[176:177]
	s_mov_b32 m0, s63
	v_lshl_add_u64 v[218:219], s[64:65], 0, v[178:179]
	global_load_lds_dwordx4 v[216:217], off
	s_add_i32 m0, s63, 0x2000
	v_lshl_add_u64 v[222:223], s[30:31], 0, v[176:177]
	global_load_lds_dwordx4 v[218:219], off
	s_mov_b32 m0, s38
	v_lshl_add_u64 v[224:225], s[30:31], 0, v[178:179]
	global_load_lds_dwordx4 v[222:223], off
	s_mov_b32 m0, s39
	s_nop 0
	global_load_lds_dwordx4 v[224:225], off
	s_waitcnt vmcnt(8)
	s_waitcnt lgkmcnt(0)
	s_barrier
	s_waitcnt lgkmcnt(0)
	v_mfma_f32_16x16x32_bf16 v[60:63], v[112:115], v[160:163], 0
	v_mfma_f32_16x16x32_bf16 v[60:63], v[116:119], v[164:167], v[60:63]
	v_mfma_f32_16x16x32_bf16 v[56:59], v[128:131], v[164:167], 0
	v_mfma_f32_16x16x32_bf16 v[56:59], v[120:123], v[160:163], v[56:59]
	v_mfma_f32_16x16x32_bf16 v[52:55], v[144:147], v[160:163], 0
	v_mfma_f32_16x16x32_bf16 v[52:55], v[148:151], v[164:167], v[52:55]
	v_mfma_f32_16x16x32_bf16 v[48:51], v[156:159], v[164:167], 0
	v_mfma_f32_16x16x32_bf16 v[48:51], v[152:155], v[160:163], v[48:51]
	v_mfma_f32_16x16x32_bf16 v[32:35], v[152:155], v[168:171], 0
	v_mfma_f32_16x16x32_bf16 v[32:35], v[156:159], v[172:175], v[32:35]
	v_mfma_f32_16x16x32_bf16 v[36:39], v[148:151], v[172:175], 0
	v_mfma_f32_16x16x32_bf16 v[36:39], v[144:147], v[168:171], v[36:39]
	v_mfma_f32_16x16x32_bf16 v[40:43], v[120:123], v[168:171], 0
	v_mfma_f32_16x16x32_bf16 v[40:43], v[128:131], v[172:175], v[40:43]
	v_mfma_f32_16x16x32_bf16 v[44:47], v[116:119], v[172:175], 0
	v_mfma_f32_16x16x32_bf16 v[44:47], v[112:115], v[168:171], v[44:47]
	v_mfma_f32_16x16x32_bf16 v[28:31], v[112:115], v[188:191], 0
	v_mfma_f32_16x16x32_bf16 v[28:31], v[116:119], v[192:195], v[28:31]
	v_mfma_f32_16x16x32_bf16 v[24:27], v[128:131], v[192:195], 0
	v_mfma_f32_16x16x32_bf16 v[24:27], v[120:123], v[188:191], v[24:27]
	v_mfma_f32_16x16x32_bf16 v[20:23], v[144:147], v[188:191], 0
	v_mfma_f32_16x16x32_bf16 v[20:23], v[148:151], v[192:195], v[20:23]
	v_mfma_f32_16x16x32_bf16 v[16:19], v[156:159], v[192:195], 0
	v_mfma_f32_16x16x32_bf16 v[16:19], v[152:155], v[188:191], v[16:19]
	v_mfma_f32_16x16x32_bf16 v[0:3], v[152:155], v[196:199], 0
	v_mfma_f32_16x16x32_bf16 v[0:3], v[156:159], v[200:203], v[0:3]
	v_mfma_f32_16x16x32_bf16 v[4:7], v[148:151], v[200:203], 0
	v_mfma_f32_16x16x32_bf16 v[4:7], v[144:147], v[196:199], v[4:7]
	v_mfma_f32_16x16x32_bf16 v[8:11], v[120:123], v[196:199], 0
	v_mfma_f32_16x16x32_bf16 v[8:11], v[128:131], v[200:203], v[8:11]
	v_mfma_f32_16x16x32_bf16 v[12:15], v[116:119], v[200:203], 0
	v_mfma_f32_16x16x32_bf16 v[12:15], v[112:115], v[196:199], v[12:15]
	s_barrier
	s_add_i32 s63, 0, 0x18000
	s_add_i32 s64, 0, 0x1c000
	v_add_u32_e32 v128, s63, v207
	v_add_u32_e32 v156, s64, v207
	ds_read_b128 v[112:115], v128
	ds_read_b128 v[116:119], v128 offset:1024
	ds_read_b128 v[120:123], v128 offset:2048
	ds_read_b128 v[128:131], v128 offset:3072
	ds_read_b128 v[144:147], v156
	ds_read_b128 v[148:151], v156 offset:1024
	ds_read_b128 v[152:155], v156 offset:2048
	ds_read_b128 v[156:159], v156 offset:3072
	s_add_u32 s30, s30, s10
	s_addc_u32 s31, s31, s11
	s_mov_b32 m0, s40
	v_lshl_add_u64 v[226:227], s[30:31], 0, v[176:177]
	ds_read_b128 v[160:163], v211 offset:32768
	ds_read_b128 v[164:167], v211 offset:33792
	ds_read_b128 v[168:171], v211 offset:34816
	ds_read_b128 v[172:175], v211 offset:35840
	ds_read_b128 v[188:191], v211 offset:36864
	ds_read_b128 v[192:195], v211 offset:37888
	ds_read_b128 v[196:199], v211 offset:38912
	ds_read_b128 v[200:203], v211 offset:39936
	global_load_lds_dwordx4 v[226:227], off
	v_lshl_add_u64 v[226:227], s[30:31], 0, v[178:179]
	s_mov_b32 m0, s41
	s_nop 0
	global_load_lds_dwordx4 v[226:227], off
	s_waitcnt vmcnt(8)
	s_waitcnt lgkmcnt(0)
	s_barrier
	s_waitcnt lgkmcnt(0)
	v_mfma_f32_16x16x32_bf16 v[136:139], v[112:115], v[160:163], v[136:139]
	v_mfma_f32_16x16x32_bf16 v[136:139], v[116:119], v[164:167], v[136:139]
	v_mfma_f32_16x16x32_bf16 v[140:143], v[128:131], v[164:167], v[140:143]
	v_mfma_f32_16x16x32_bf16 v[140:143], v[120:123], v[160:163], v[140:143]
	v_mfma_f32_16x16x32_bf16 v[132:135], v[144:147], v[160:163], v[132:135]
	v_mfma_f32_16x16x32_bf16 v[132:135], v[148:151], v[164:167], v[132:135]
	v_mfma_f32_16x16x32_bf16 v[124:127], v[156:159], v[164:167], v[124:127]
	v_mfma_f32_16x16x32_bf16 v[124:127], v[152:155], v[160:163], v[124:127]
	v_mfma_f32_16x16x32_bf16 v[96:99], v[152:155], v[168:171], v[96:99]
	v_mfma_f32_16x16x32_bf16 v[96:99], v[156:159], v[172:175], v[96:99]
	v_mfma_f32_16x16x32_bf16 v[100:103], v[148:151], v[172:175], v[100:103]
	v_mfma_f32_16x16x32_bf16 v[100:103], v[144:147], v[168:171], v[100:103]
	v_mfma_f32_16x16x32_bf16 v[104:107], v[120:123], v[168:171], v[104:107]
	v_mfma_f32_16x16x32_bf16 v[104:107], v[128:131], v[172:175], v[104:107]
	v_mfma_f32_16x16x32_bf16 v[108:111], v[116:119], v[172:175], v[108:111]
	v_mfma_f32_16x16x32_bf16 v[108:111], v[112:115], v[168:171], v[108:111]
	v_mfma_f32_16x16x32_bf16 v[92:95], v[112:115], v[188:191], v[92:95]
	v_mfma_f32_16x16x32_bf16 v[92:95], v[116:119], v[192:195], v[92:95]
	v_mfma_f32_16x16x32_bf16 v[88:91], v[128:131], v[192:195], v[88:91]
	v_mfma_f32_16x16x32_bf16 v[88:91], v[120:123], v[188:191], v[88:91]
	v_mfma_f32_16x16x32_bf16 v[84:87], v[144:147], v[188:191], v[84:87]
	v_mfma_f32_16x16x32_bf16 v[84:87], v[148:151], v[192:195], v[84:87]
	v_mfma_f32_16x16x32_bf16 v[80:83], v[156:159], v[192:195], v[80:83]
	v_mfma_f32_16x16x32_bf16 v[80:83], v[152:155], v[188:191], v[80:83]
	v_mfma_f32_16x16x32_bf16 v[64:67], v[152:155], v[196:199], v[64:67]
	v_mfma_f32_16x16x32_bf16 v[64:67], v[156:159], v[200:203], v[64:67]
	v_mfma_f32_16x16x32_bf16 v[68:71], v[148:151], v[200:203], v[68:71]
	v_mfma_f32_16x16x32_bf16 v[68:71], v[144:147], v[196:199], v[68:71]
	v_mfma_f32_16x16x32_bf16 v[72:75], v[120:123], v[196:199], v[72:75]
	v_mfma_f32_16x16x32_bf16 v[72:75], v[128:131], v[200:203], v[72:75]
	v_mfma_f32_16x16x32_bf16 v[76:79], v[116:119], v[200:203], v[76:79]
	v_mfma_f32_16x16x32_bf16 v[76:79], v[112:115], v[196:199], v[76:79]
	s_barrier
	s_add_i32 s30, s63, s37
	v_lshl_add_u64 v[204:205], v[204:205], 0, s[18:19]
	s_mov_b32 m0, s30
	ds_read_b128 v[160:163], v211 offset:49152
	ds_read_b128 v[164:167], v211 offset:50176
	ds_read_b128 v[168:171], v211 offset:51200
	ds_read_b128 v[172:175], v211 offset:52224
	ds_read_b128 v[188:191], v211 offset:53248
	ds_read_b128 v[192:195], v211 offset:54272
	ds_read_b128 v[196:199], v211 offset:55296
	ds_read_b128 v[200:203], v211 offset:56320
	global_load_lds_dwordx4 v[204:205], off
	v_lshl_add_u64 v[204:205], v[214:215], 0, s[18:19]
	s_add_i32 m0, s30, 0x2000
	s_add_i32 s30, s64, s37
	global_load_lds_dwordx4 v[204:205], off
	v_lshl_add_u64 v[204:205], v[216:217], 0, s[18:19]
	s_mov_b32 m0, s30
	s_nop 0
	global_load_lds_dwordx4 v[204:205], off
	v_lshl_add_u64 v[204:205], v[218:219], 0, s[18:19]
	s_add_i32 m0, s30, 0x2000
	s_nop 0
	global_load_lds_dwordx4 v[204:205], off
	v_lshl_add_u64 v[204:205], v[222:223], 0, s[18:19]
	s_mov_b32 m0, s43
	s_nop 0
	global_load_lds_dwordx4 v[204:205], off
	v_lshl_add_u64 v[204:205], v[224:225], 0, s[18:19]
	s_mov_b32 m0, s44
	s_nop 0
	global_load_lds_dwordx4 v[204:205], off
	s_waitcnt vmcnt(8)
	s_waitcnt lgkmcnt(0)
	s_barrier
	s_waitcnt lgkmcnt(0)
	v_mfma_f32_16x16x32_bf16 v[60:63], v[112:115], v[160:163], v[60:63]
	v_mfma_f32_16x16x32_bf16 v[60:63], v[116:119], v[164:167], v[60:63]
	v_mfma_f32_16x16x32_bf16 v[56:59], v[128:131], v[164:167], v[56:59]
	v_mfma_f32_16x16x32_bf16 v[56:59], v[120:123], v[160:163], v[56:59]
	v_mfma_f32_16x16x32_bf16 v[52:55], v[144:147], v[160:163], v[52:55]
	v_mfma_f32_16x16x32_bf16 v[52:55], v[148:151], v[164:167], v[52:55]
	v_mfma_f32_16x16x32_bf16 v[48:51], v[156:159], v[164:167], v[48:51]
	v_mfma_f32_16x16x32_bf16 v[48:51], v[152:155], v[160:163], v[48:51]
	v_mfma_f32_16x16x32_bf16 v[32:35], v[152:155], v[168:171], v[32:35]
	v_mfma_f32_16x16x32_bf16 v[32:35], v[156:159], v[172:175], v[32:35]
	v_mfma_f32_16x16x32_bf16 v[36:39], v[148:151], v[172:175], v[36:39]
	v_mfma_f32_16x16x32_bf16 v[36:39], v[144:147], v[168:171], v[36:39]
	v_mfma_f32_16x16x32_bf16 v[40:43], v[120:123], v[168:171], v[40:43]
	v_mfma_f32_16x16x32_bf16 v[40:43], v[128:131], v[172:175], v[40:43]
	v_mfma_f32_16x16x32_bf16 v[44:47], v[116:119], v[172:175], v[44:47]
	v_mfma_f32_16x16x32_bf16 v[44:47], v[112:115], v[168:171], v[44:47]
	v_mfma_f32_16x16x32_bf16 v[28:31], v[112:115], v[188:191], v[28:31]
	v_mfma_f32_16x16x32_bf16 v[28:31], v[116:119], v[192:195], v[28:31]
	v_mfma_f32_16x16x32_bf16 v[24:27], v[128:131], v[192:195], v[24:27]
	v_mfma_f32_16x16x32_bf16 v[24:27], v[120:123], v[188:191], v[24:27]
	v_mfma_f32_16x16x32_bf16 v[20:23], v[144:147], v[188:191], v[20:23]
	v_mfma_f32_16x16x32_bf16 v[20:23], v[148:151], v[192:195], v[20:23]
	v_mfma_f32_16x16x32_bf16 v[16:19], v[156:159], v[192:195], v[16:19]
	v_mfma_f32_16x16x32_bf16 v[16:19], v[152:155], v[188:191], v[16:19]
	v_mfma_f32_16x16x32_bf16 v[0:3], v[152:155], v[196:199], v[0:3]
	v_mfma_f32_16x16x32_bf16 v[0:3], v[156:159], v[200:203], v[0:3]
	v_mfma_f32_16x16x32_bf16 v[4:7], v[148:151], v[200:203], v[4:7]
	v_mfma_f32_16x16x32_bf16 v[4:7], v[144:147], v[196:199], v[4:7]
	v_mfma_f32_16x16x32_bf16 v[8:11], v[120:123], v[196:199], v[8:11]
	v_mfma_f32_16x16x32_bf16 v[8:11], v[128:131], v[200:203], v[8:11]
	v_mfma_f32_16x16x32_bf16 v[12:15], v[116:119], v[200:203], v[12:15]
	v_mfma_f32_16x16x32_bf16 v[12:15], v[112:115], v[196:199], v[12:15]
	s_barrier
	s_add_u32 s28, s28, 0x100
	s_addc_u32 s29, s29, 0
	s_add_u32 s60, s60, 0x100
	s_addc_u32 s61, s61, 0
	s_cmp_ge_i32 s62, s45
	s_mov_b32 s30, s62
	s_cbranch_scc1 .Lpeel_exit_849

.Lpeel_exit_849:
.LBB0_850:
	s_and_b64 vcc, exec, s[22:23]
	s_cbranch_vccz .LBB0_852
	s_barrier

.Lzskip_6:
	s_add_u32 s30, s30, 0x80
	s_addc_u32 s31, s31, 0
	s_add_u32 s66, s34, 0x100
	s_addc_u32 s67, s35, 0
	s_mov_b32 s34, 0
	ds_read_b128 v[164:167], v157
	ds_read_b128 v[168:171], v157 offset:1024
	ds_read_b128 v[172:175], v157 offset:2048
	ds_read_b128 v[176:179], v157 offset:3072
	ds_read_b128 v[180:183], v162
	ds_read_b128 v[184:187], v162 offset:1024
	ds_read_b128 v[188:191], v162 offset:2048
	ds_read_b128 v[192:195], v162 offset:3072
	s_add_i32 s68, s34, 2
	s_add_u32 s69, s30, 0x80
	s_addc_u32 s35, s31, 0
	s_cmp_eq_u32 s49, s34
	s_cselect_b32 s34, s2, s69
	s_cselect_b32 s35, s3, s35
	s_cselect_b32 s71, s29, s67
	s_cselect_b32 s70, s28, s66
	v_lshl_add_u64 v[230:231], s[30:31], 0, v[136:137]
	s_add_i32 m0, s41, 0xc000
	ds_read_b128 v[196:199], v163
	ds_read_b128 v[200:203], v163 offset:1024
	ds_read_b128 v[204:207], v163 offset:2048
	ds_read_b128 v[208:211], v163 offset:3072
	ds_read_b128 v[212:215], v163 offset:4096
	ds_read_b128 v[216:219], v163 offset:5120
	ds_read_b128 v[222:225], v163 offset:6144
	ds_read_b128 v[226:229], v163 offset:7168
	global_load_lds_dwordx4 v[230:231], off
	v_lshl_add_u64 v[230:231], s[30:31], 0, v[138:139]
	s_add_i32 m0, s41, 0xe000
	s_nop 0
	global_load_lds_dwordx4 v[230:231], off
	s_waitcnt vmcnt(8)
	s_waitcnt lgkmcnt(0)
	s_barrier
	s_waitcnt lgkmcnt(0)
	v_mfma_f32_16x16x32_bf16 v[120:123], v[164:167], v[196:199], 0
	v_mfma_f32_16x16x32_bf16 v[120:123], v[168:171], v[200:203], v[120:123]
	v_mfma_f32_16x16x32_bf16 v[124:127], v[176:179], v[200:203], 0
	v_mfma_f32_16x16x32_bf16 v[124:127], v[172:175], v[196:199], v[124:127]
	v_mfma_f32_16x16x32_bf16 v[116:119], v[180:183], v[196:199], 0
	v_mfma_f32_16x16x32_bf16 v[116:119], v[184:187], v[200:203], v[116:119]
	v_mfma_f32_16x16x32_bf16 v[112:115], v[192:195], v[200:203], 0
	v_mfma_f32_16x16x32_bf16 v[112:115], v[188:191], v[196:199], v[112:115]
	v_mfma_f32_16x16x32_bf16 v[96:99], v[188:191], v[204:207], 0
	v_mfma_f32_16x16x32_bf16 v[96:99], v[192:195], v[208:211], v[96:99]
	v_mfma_f32_16x16x32_bf16 v[100:103], v[184:187], v[208:211], 0
	v_mfma_f32_16x16x32_bf16 v[100:103], v[180:183], v[204:207], v[100:103]
	v_mfma_f32_16x16x32_bf16 v[104:107], v[172:175], v[204:207], 0
	v_mfma_f32_16x16x32_bf16 v[104:107], v[176:179], v[208:211], v[104:107]
	v_mfma_f32_16x16x32_bf16 v[108:111], v[168:171], v[208:211], 0
	v_mfma_f32_16x16x32_bf16 v[108:111], v[164:167], v[204:207], v[108:111]
	v_mfma_f32_16x16x32_bf16 v[92:95], v[164:167], v[212:215], 0
	v_mfma_f32_16x16x32_bf16 v[92:95], v[168:171], v[216:219], v[92:95]
	v_mfma_f32_16x16x32_bf16 v[88:91], v[176:179], v[216:219], 0
	v_mfma_f32_16x16x32_bf16 v[88:91], v[172:175], v[212:215], v[88:91]
	v_mfma_f32_16x16x32_bf16 v[84:87], v[180:183], v[212:215], 0
	v_mfma_f32_16x16x32_bf16 v[84:87], v[184:187], v[216:219], v[84:87]
	v_mfma_f32_16x16x32_bf16 v[80:83], v[192:195], v[216:219], 0
	v_mfma_f32_16x16x32_bf16 v[80:83], v[188:191], v[212:215], v[80:83]
	v_mfma_f32_16x16x32_bf16 v[64:67], v[188:191], v[222:225], 0
	v_mfma_f32_16x16x32_bf16 v[64:67], v[192:195], v[226:229], v[64:67]
	v_mfma_f32_16x16x32_bf16 v[68:71], v[184:187], v[226:229], 0
	v_mfma_f32_16x16x32_bf16 v[68:71], v[180:183], v[222:225], v[68:71]
	v_mfma_f32_16x16x32_bf16 v[72:75], v[172:175], v[222:225], 0
	v_mfma_f32_16x16x32_bf16 v[72:75], v[176:179], v[226:229], v[72:75]
	v_mfma_f32_16x16x32_bf16 v[76:79], v[168:171], v[226:229], 0
	v_mfma_f32_16x16x32_bf16 v[76:79], v[164:167], v[222:225], v[76:79]
	s_barrier
	s_add_i32 s69, s52, s40
	v_lshl_add_u64 v[230:231], s[70:71], 0, v[130:131]
	s_mov_b32 m0, s69
	ds_read_b128 v[196:199], v163 offset:16384
	ds_read_b128 v[200:203], v163 offset:17408
	ds_read_b128 v[204:207], v163 offset:18432
	ds_read_b128 v[208:211], v163 offset:19456
	ds_read_b128 v[212:215], v163 offset:20480
	ds_read_b128 v[216:219], v163 offset:21504
	ds_read_b128 v[222:225], v163 offset:22528
	ds_read_b128 v[226:229], v163 offset:23552
	global_load_lds_dwordx4 v[230:231], off
	s_add_i32 m0, s69, 0x2000
	v_lshl_add_u64 v[232:233], s[70:71], 0, v[134:135]
	s_add_u32 s70, s70, s6
	s_addc_u32 s71, s71, s7
	s_add_i32 s69, s53, s40
	global_load_lds_dwordx4 v[232:233], off
	v_lshl_add_u64 v[234:235], s[70:71], 0, v[130:131]
	s_mov_b32 m0, s69
	v_lshl_add_u64 v[236:237], s[70:71], 0, v[134:135]
	global_load_lds_dwordx4 v[234:235], off
	s_add_i32 m0, s69, 0x2000
	v_lshl_add_u64 v[238:239], s[34:35], 0, v[128:129]
	global_load_lds_dwordx4 v[236:237], off
	s_mov_b32 m0, s41
	v_lshl_add_u64 v[240:241], s[34:35], 0, v[132:133]
	global_load_lds_dwordx4 v[238:239], off
	s_mov_b32 m0, s42
	s_nop 0
	global_load_lds_dwordx4 v[240:241], off
	s_waitcnt vmcnt(8)
	s_waitcnt lgkmcnt(0)
	s_barrier
	s_waitcnt lgkmcnt(0)
	v_mfma_f32_16x16x32_bf16 v[60:63], v[164:167], v[196:199], 0
	v_mfma_f32_16x16x32_bf16 v[60:63], v[168:171], v[200:203], v[60:63]
	v_mfma_f32_16x16x32_bf16 v[56:59], v[176:179], v[200:203], 0
	v_mfma_f32_16x16x32_bf16 v[56:59], v[172:175], v[196:199], v[56:59]
	v_mfma_f32_16x16x32_bf16 v[52:55], v[180:183], v[196:199], 0
	v_mfma_f32_16x16x32_bf16 v[52:55], v[184:187], v[200:203], v[52:55]
	v_mfma_f32_16x16x32_bf16 v[48:51], v[192:195], v[200:203], 0
	v_mfma_f32_16x16x32_bf16 v[48:51], v[188:191], v[196:199], v[48:51]
	v_mfma_f32_16x16x32_bf16 v[32:35], v[188:191], v[204:207], 0
	v_mfma_f32_16x16x32_bf16 v[32:35], v[192:195], v[208:211], v[32:35]
	v_mfma_f32_16x16x32_bf16 v[36:39], v[184:187], v[208:211], 0
	v_mfma_f32_16x16x32_bf16 v[36:39], v[180:183], v[204:207], v[36:39]
	v_mfma_f32_16x16x32_bf16 v[40:43], v[172:175], v[204:207], 0
	v_mfma_f32_16x16x32_bf16 v[40:43], v[176:179], v[208:211], v[40:43]
	v_mfma_f32_16x16x32_bf16 v[44:47], v[168:171], v[208:211], 0
	v_mfma_f32_16x16x32_bf16 v[44:47], v[164:167], v[204:207], v[44:47]
	v_mfma_f32_16x16x32_bf16 v[28:31], v[164:167], v[212:215], 0
	v_mfma_f32_16x16x32_bf16 v[28:31], v[168:171], v[216:219], v[28:31]
	v_mfma_f32_16x16x32_bf16 v[24:27], v[176:179], v[216:219], 0
	v_mfma_f32_16x16x32_bf16 v[24:27], v[172:175], v[212:215], v[24:27]
	v_mfma_f32_16x16x32_bf16 v[20:23], v[180:183], v[212:215], 0
	v_mfma_f32_16x16x32_bf16 v[20:23], v[184:187], v[216:219], v[20:23]
	v_mfma_f32_16x16x32_bf16 v[16:19], v[192:195], v[216:219], 0
	v_mfma_f32_16x16x32_bf16 v[16:19], v[188:191], v[212:215], v[16:19]
	v_mfma_f32_16x16x32_bf16 v[0:3], v[188:191], v[222:225], 0
	v_mfma_f32_16x16x32_bf16 v[0:3], v[192:195], v[226:229], v[0:3]
	v_mfma_f32_16x16x32_bf16 v[4:7], v[184:187], v[226:229], 0
	v_mfma_f32_16x16x32_bf16 v[4:7], v[180:183], v[222:225], v[4:7]
	v_mfma_f32_16x16x32_bf16 v[8:11], v[172:175], v[222:225], 0
	v_mfma_f32_16x16x32_bf16 v[8:11], v[176:179], v[226:229], v[8:11]
	v_mfma_f32_16x16x32_bf16 v[12:15], v[168:171], v[226:229], 0
	v_mfma_f32_16x16x32_bf16 v[12:15], v[164:167], v[222:225], v[12:15]
	s_barrier
	s_add_i32 s69, 0, 0x18000
	s_add_i32 s70, 0, 0x1c000
	v_add_u32_e32 v176, s69, v154
	v_add_u32_e32 v192, s70, v154
	ds_read_b128 v[164:167], v176
	ds_read_b128 v[168:171], v176 offset:1024
	ds_read_b128 v[172:175], v176 offset:2048
	ds_read_b128 v[176:179], v176 offset:3072
	ds_read_b128 v[180:183], v192
	ds_read_b128 v[184:187], v192 offset:1024
	ds_read_b128 v[188:191], v192 offset:2048
	ds_read_b128 v[192:195], v192 offset:3072
	s_add_u32 s34, s34, s6
	s_addc_u32 s35, s35, s7
	s_mov_b32 m0, s43
	v_lshl_add_u64 v[242:243], s[34:35], 0, v[128:129]
	ds_read_b128 v[196:199], v163 offset:32768
	ds_read_b128 v[200:203], v163 offset:33792
	ds_read_b128 v[204:207], v163 offset:34816
	ds_read_b128 v[208:211], v163 offset:35840
	ds_read_b128 v[212:215], v163 offset:36864
	ds_read_b128 v[216:219], v163 offset:37888
	ds_read_b128 v[222:225], v163 offset:38912
	ds_read_b128 v[226:229], v163 offset:39936
	global_load_lds_dwordx4 v[242:243], off
	v_lshl_add_u64 v[242:243], s[34:35], 0, v[132:133]
	s_mov_b32 m0, s44
	s_nop 0
	global_load_lds_dwordx4 v[242:243], off
	s_waitcnt vmcnt(8)
	s_waitcnt lgkmcnt(0)
	s_barrier
	s_waitcnt lgkmcnt(0)
	v_mfma_f32_16x16x32_bf16 v[120:123], v[164:167], v[196:199], v[120:123]
	v_mfma_f32_16x16x32_bf16 v[120:123], v[168:171], v[200:203], v[120:123]
	v_mfma_f32_16x16x32_bf16 v[124:127], v[176:179], v[200:203], v[124:127]
	v_mfma_f32_16x16x32_bf16 v[124:127], v[172:175], v[196:199], v[124:127]
	v_mfma_f32_16x16x32_bf16 v[116:119], v[180:183], v[196:199], v[116:119]
	v_mfma_f32_16x16x32_bf16 v[116:119], v[184:187], v[200:203], v[116:119]
	v_mfma_f32_16x16x32_bf16 v[112:115], v[192:195], v[200:203], v[112:115]
	v_mfma_f32_16x16x32_bf16 v[112:115], v[188:191], v[196:199], v[112:115]
	v_mfma_f32_16x16x32_bf16 v[96:99], v[188:191], v[204:207], v[96:99]
	v_mfma_f32_16x16x32_bf16 v[96:99], v[192:195], v[208:211], v[96:99]
	v_mfma_f32_16x16x32_bf16 v[100:103], v[184:187], v[208:211], v[100:103]
	v_mfma_f32_16x16x32_bf16 v[100:103], v[180:183], v[204:207], v[100:103]
	v_mfma_f32_16x16x32_bf16 v[104:107], v[172:175], v[204:207], v[104:107]
	v_mfma_f32_16x16x32_bf16 v[104:107], v[176:179], v[208:211], v[104:107]
	v_mfma_f32_16x16x32_bf16 v[108:111], v[168:171], v[208:211], v[108:111]
	v_mfma_f32_16x16x32_bf16 v[108:111], v[164:167], v[204:207], v[108:111]
	v_mfma_f32_16x16x32_bf16 v[92:95], v[164:167], v[212:215], v[92:95]
	v_mfma_f32_16x16x32_bf16 v[92:95], v[168:171], v[216:219], v[92:95]
	v_mfma_f32_16x16x32_bf16 v[88:91], v[176:179], v[216:219], v[88:91]
	v_mfma_f32_16x16x32_bf16 v[88:91], v[172:175], v[212:215], v[88:91]
	v_mfma_f32_16x16x32_bf16 v[84:87], v[180:183], v[212:215], v[84:87]
	v_mfma_f32_16x16x32_bf16 v[84:87], v[184:187], v[216:219], v[84:87]
	v_mfma_f32_16x16x32_bf16 v[80:83], v[192:195], v[216:219], v[80:83]
	v_mfma_f32_16x16x32_bf16 v[80:83], v[188:191], v[212:215], v[80:83]
	v_mfma_f32_16x16x32_bf16 v[64:67], v[188:191], v[222:225], v[64:67]
	v_mfma_f32_16x16x32_bf16 v[64:67], v[192:195], v[226:229], v[64:67]
	v_mfma_f32_16x16x32_bf16 v[68:71], v[184:187], v[226:229], v[68:71]
	v_mfma_f32_16x16x32_bf16 v[68:71], v[180:183], v[222:225], v[68:71]
	v_mfma_f32_16x16x32_bf16 v[72:75], v[172:175], v[222:225], v[72:75]
	v_mfma_f32_16x16x32_bf16 v[72:75], v[176:179], v[226:229], v[72:75]
	v_mfma_f32_16x16x32_bf16 v[76:79], v[168:171], v[226:229], v[76:79]
	v_mfma_f32_16x16x32_bf16 v[76:79], v[164:167], v[222:225], v[76:79]
	s_barrier
	s_add_i32 s34, s69, s40
	v_lshl_add_u64 v[230:231], v[230:231], 0, s[12:13]
	s_mov_b32 m0, s34
	ds_read_b128 v[196:199], v163 offset:49152
	ds_read_b128 v[200:203], v163 offset:50176
	ds_read_b128 v[204:207], v163 offset:51200
	ds_read_b128 v[208:211], v163 offset:52224
	ds_read_b128 v[212:215], v163 offset:53248
	ds_read_b128 v[216:219], v163 offset:54272
	ds_read_b128 v[222:225], v163 offset:55296
	ds_read_b128 v[226:229], v163 offset:56320
	global_load_lds_dwordx4 v[230:231], off
	v_lshl_add_u64 v[230:231], v[232:233], 0, s[12:13]
	s_add_i32 m0, s34, 0x2000
	s_add_i32 s34, s70, s40
	global_load_lds_dwordx4 v[230:231], off
	v_lshl_add_u64 v[230:231], v[234:235], 0, s[12:13]
	s_mov_b32 m0, s34
	s_nop 0
	global_load_lds_dwordx4 v[230:231], off
	v_lshl_add_u64 v[230:231], v[236:237], 0, s[12:13]
	s_add_i32 m0, s34, 0x2000
	s_nop 0
	global_load_lds_dwordx4 v[230:231], off
	v_lshl_add_u64 v[230:231], v[238:239], 0, s[12:13]
	s_mov_b32 m0, s46
	s_nop 0
	global_load_lds_dwordx4 v[230:231], off
	v_lshl_add_u64 v[230:231], v[240:241], 0, s[12:13]
	s_mov_b32 m0, s47
	s_nop 0
	global_load_lds_dwordx4 v[230:231], off
	s_waitcnt vmcnt(8)
	s_waitcnt lgkmcnt(0)
	s_barrier
	s_waitcnt lgkmcnt(0)
	v_mfma_f32_16x16x32_bf16 v[60:63], v[164:167], v[196:199], v[60:63]
	v_mfma_f32_16x16x32_bf16 v[60:63], v[168:171], v[200:203], v[60:63]
	v_mfma_f32_16x16x32_bf16 v[56:59], v[176:179], v[200:203], v[56:59]
	v_mfma_f32_16x16x32_bf16 v[56:59], v[172:175], v[196:199], v[56:59]
	v_mfma_f32_16x16x32_bf16 v[52:55], v[180:183], v[196:199], v[52:55]
	v_mfma_f32_16x16x32_bf16 v[52:55], v[184:187], v[200:203], v[52:55]
	v_mfma_f32_16x16x32_bf16 v[48:51], v[192:195], v[200:203], v[48:51]
	v_mfma_f32_16x16x32_bf16 v[48:51], v[188:191], v[196:199], v[48:51]
	v_mfma_f32_16x16x32_bf16 v[32:35], v[188:191], v[204:207], v[32:35]
	v_mfma_f32_16x16x32_bf16 v[32:35], v[192:195], v[208:211], v[32:35]
	v_mfma_f32_16x16x32_bf16 v[36:39], v[184:187], v[208:211], v[36:39]
	v_mfma_f32_16x16x32_bf16 v[36:39], v[180:183], v[204:207], v[36:39]
	v_mfma_f32_16x16x32_bf16 v[40:43], v[172:175], v[204:207], v[40:43]
	v_mfma_f32_16x16x32_bf16 v[40:43], v[176:179], v[208:211], v[40:43]
	v_mfma_f32_16x16x32_bf16 v[44:47], v[168:171], v[208:211], v[44:47]
	v_mfma_f32_16x16x32_bf16 v[44:47], v[164:167], v[204:207], v[44:47]
	v_mfma_f32_16x16x32_bf16 v[28:31], v[164:167], v[212:215], v[28:31]
	v_mfma_f32_16x16x32_bf16 v[28:31], v[168:171], v[216:219], v[28:31]
	v_mfma_f32_16x16x32_bf16 v[24:27], v[176:179], v[216:219], v[24:27]
	v_mfma_f32_16x16x32_bf16 v[24:27], v[172:175], v[212:215], v[24:27]
	v_mfma_f32_16x16x32_bf16 v[20:23], v[180:183], v[212:215], v[20:23]
	v_mfma_f32_16x16x32_bf16 v[20:23], v[184:187], v[216:219], v[20:23]
	v_mfma_f32_16x16x32_bf16 v[16:19], v[192:195], v[216:219], v[16:19]
	v_mfma_f32_16x16x32_bf16 v[16:19], v[188:191], v[212:215], v[16:19]
	v_mfma_f32_16x16x32_bf16 v[0:3], v[188:191], v[222:225], v[0:3]
	v_mfma_f32_16x16x32_bf16 v[0:3], v[192:195], v[226:229], v[0:3]
	v_mfma_f32_16x16x32_bf16 v[4:7], v[184:187], v[226:229], v[4:7]
	v_mfma_f32_16x16x32_bf16 v[4:7], v[180:183], v[222:225], v[4:7]
	v_mfma_f32_16x16x32_bf16 v[8:11], v[172:175], v[222:225], v[8:11]
	v_mfma_f32_16x16x32_bf16 v[8:11], v[176:179], v[226:229], v[8:11]
	v_mfma_f32_16x16x32_bf16 v[12:15], v[168:171], v[226:229], v[12:15]
	v_mfma_f32_16x16x32_bf16 v[12:15], v[164:167], v[222:225], v[12:15]
	s_barrier
	s_add_u32 s30, s30, 0x100
	s_addc_u32 s31, s31, 0
	s_add_u32 s66, s66, 0x100
	s_addc_u32 s67, s67, 0
	s_cmp_ge_i32 s68, s48
	s_mov_b32 s34, s68
	s_cbranch_scc1 .Lpeel_exit_949

.Lzskip_7:
	s_add_u32 s2, s6, 0x80
	s_addc_u32 s3, s7, 0
	s_add_u32 s6, s4, 0x100
	s_addc_u32 s7, s5, 0
	s_mov_b32 s4, 0
	ds_read_b128 v[170:173], v139
	ds_read_b128 v[174:177], v139 offset:1024
	ds_read_b128 v[178:181], v139 offset:2048
	ds_read_b128 v[182:185], v139 offset:3072
	ds_read_b128 v[186:189], v165
	ds_read_b128 v[190:193], v165 offset:1024
	ds_read_b128 v[194:197], v165 offset:2048
	ds_read_b128 v[198:201], v165 offset:3072
	s_add_i32 s8, s4, 2
	s_add_u32 s9, s2, 0x80
	s_addc_u32 s5, s3, 0
	s_cmp_eq_u32 s52, s4
	s_cselect_b32 s4, s30, s9
	s_cselect_b32 s5, s31, s5
	s_cselect_b32 s11, s35, s7
	s_cselect_b32 s10, s34, s6
	v_lshl_add_u64 v[218:219], s[2:3], 0, v[156:157]
	s_add_i32 m0, s42, 0xc000
	ds_read_b128 v[202:205], v166
	ds_read_b128 v[206:209], v166 offset:1024
	ds_read_b128 v[210:213], v166 offset:2048
	ds_read_b128 v[214:217], v166 offset:3072
	ds_read_b128 v[222:225], v166 offset:4096
	ds_read_b128 v[226:229], v166 offset:5120
	ds_read_b128 v[230:233], v166 offset:6144
	ds_read_b128 v[234:237], v166 offset:7168
	global_load_lds_dwordx4 v[218:219], off
	v_lshl_add_u64 v[218:219], s[2:3], 0, v[158:159]
	s_add_i32 m0, s42, 0xe000
	s_nop 0
	global_load_lds_dwordx4 v[218:219], off
	s_waitcnt vmcnt(8)
	s_waitcnt lgkmcnt(0)
	s_barrier
	s_waitcnt lgkmcnt(0)
	v_mfma_f32_16x16x32_bf16 v[124:127], v[170:173], v[202:205], 0
	v_mfma_f32_16x16x32_bf16 v[124:127], v[174:177], v[206:209], v[124:127]
	v_mfma_f32_16x16x32_bf16 v[120:123], v[182:185], v[206:209], 0
	v_mfma_f32_16x16x32_bf16 v[120:123], v[178:181], v[202:205], v[120:123]
	v_mfma_f32_16x16x32_bf16 v[116:119], v[186:189], v[202:205], 0
	v_mfma_f32_16x16x32_bf16 v[116:119], v[190:193], v[206:209], v[116:119]
	v_mfma_f32_16x16x32_bf16 v[112:115], v[198:201], v[206:209], 0
	v_mfma_f32_16x16x32_bf16 v[112:115], v[194:197], v[202:205], v[112:115]
	v_mfma_f32_16x16x32_bf16 v[96:99], v[194:197], v[210:213], 0
	v_mfma_f32_16x16x32_bf16 v[96:99], v[198:201], v[214:217], v[96:99]
	v_mfma_f32_16x16x32_bf16 v[100:103], v[190:193], v[214:217], 0
	v_mfma_f32_16x16x32_bf16 v[100:103], v[186:189], v[210:213], v[100:103]
	v_mfma_f32_16x16x32_bf16 v[104:107], v[178:181], v[210:213], 0
	v_mfma_f32_16x16x32_bf16 v[104:107], v[182:185], v[214:217], v[104:107]
	v_mfma_f32_16x16x32_bf16 v[108:111], v[174:177], v[214:217], 0
	v_mfma_f32_16x16x32_bf16 v[108:111], v[170:173], v[210:213], v[108:111]
	v_mfma_f32_16x16x32_bf16 v[92:95], v[170:173], v[222:225], 0
	v_mfma_f32_16x16x32_bf16 v[92:95], v[174:177], v[226:229], v[92:95]
	v_mfma_f32_16x16x32_bf16 v[88:91], v[182:185], v[226:229], 0
	v_mfma_f32_16x16x32_bf16 v[88:91], v[178:181], v[222:225], v[88:91]
	v_mfma_f32_16x16x32_bf16 v[84:87], v[186:189], v[222:225], 0
	v_mfma_f32_16x16x32_bf16 v[84:87], v[190:193], v[226:229], v[84:87]
	v_mfma_f32_16x16x32_bf16 v[80:83], v[198:201], v[226:229], 0
	v_mfma_f32_16x16x32_bf16 v[80:83], v[194:197], v[222:225], v[80:83]
	v_mfma_f32_16x16x32_bf16 v[64:67], v[194:197], v[230:233], 0
	v_mfma_f32_16x16x32_bf16 v[64:67], v[198:201], v[234:237], v[64:67]
	v_mfma_f32_16x16x32_bf16 v[68:71], v[190:193], v[234:237], 0
	v_mfma_f32_16x16x32_bf16 v[68:71], v[186:189], v[230:233], v[68:71]
	v_mfma_f32_16x16x32_bf16 v[72:75], v[178:181], v[230:233], 0
	v_mfma_f32_16x16x32_bf16 v[72:75], v[182:185], v[234:237], v[72:75]
	v_mfma_f32_16x16x32_bf16 v[76:79], v[174:177], v[234:237], 0
	v_mfma_f32_16x16x32_bf16 v[76:79], v[170:173], v[230:233], v[76:79]
	s_barrier
	s_add_i32 s9, s60, s39
	v_lshl_add_u64 v[218:219], s[10:11], 0, v[132:133]
	s_mov_b32 m0, s9
	ds_read_b128 v[202:205], v166 offset:16384
	ds_read_b128 v[206:209], v166 offset:17408
	ds_read_b128 v[210:213], v166 offset:18432
	ds_read_b128 v[214:217], v166 offset:19456
	ds_read_b128 v[222:225], v166 offset:20480
	ds_read_b128 v[226:229], v166 offset:21504
	ds_read_b128 v[230:233], v166 offset:22528
	ds_read_b128 v[234:237], v166 offset:23552
	global_load_lds_dwordx4 v[218:219], off
	s_add_i32 m0, s9, 0x2000
	v_lshl_add_u64 v[238:239], s[10:11], 0, v[128:129]
	s_add_u32 s10, s10, s18
	s_addc_u32 s11, s11, s19
	s_add_i32 s9, s61, s39
	global_load_lds_dwordx4 v[238:239], off
	v_lshl_add_u64 v[240:241], s[10:11], 0, v[132:133]
	s_mov_b32 m0, s9
	v_lshl_add_u64 v[242:243], s[10:11], 0, v[128:129]
	global_load_lds_dwordx4 v[240:241], off
	s_add_i32 m0, s9, 0x2000
	v_lshl_add_u64 v[244:245], s[4:5], 0, v[134:135]
	global_load_lds_dwordx4 v[242:243], off
	s_mov_b32 m0, s42
	v_lshl_add_u64 v[246:247], s[4:5], 0, v[130:131]
	global_load_lds_dwordx4 v[244:245], off
	s_mov_b32 m0, s43
	s_nop 0
	global_load_lds_dwordx4 v[246:247], off
	s_waitcnt vmcnt(8)
	s_waitcnt lgkmcnt(0)
	s_barrier
	s_waitcnt lgkmcnt(0)
	v_mfma_f32_16x16x32_bf16 v[60:63], v[170:173], v[202:205], 0
	v_mfma_f32_16x16x32_bf16 v[60:63], v[174:177], v[206:209], v[60:63]
	v_mfma_f32_16x16x32_bf16 v[56:59], v[182:185], v[206:209], 0
	v_mfma_f32_16x16x32_bf16 v[56:59], v[178:181], v[202:205], v[56:59]
	v_mfma_f32_16x16x32_bf16 v[52:55], v[186:189], v[202:205], 0
	v_mfma_f32_16x16x32_bf16 v[52:55], v[190:193], v[206:209], v[52:55]
	v_mfma_f32_16x16x32_bf16 v[48:51], v[198:201], v[206:209], 0
	v_mfma_f32_16x16x32_bf16 v[48:51], v[194:197], v[202:205], v[48:51]
	v_mfma_f32_16x16x32_bf16 v[32:35], v[194:197], v[210:213], 0
	v_mfma_f32_16x16x32_bf16 v[32:35], v[198:201], v[214:217], v[32:35]
	v_mfma_f32_16x16x32_bf16 v[36:39], v[190:193], v[214:217], 0
	v_mfma_f32_16x16x32_bf16 v[36:39], v[186:189], v[210:213], v[36:39]
	v_mfma_f32_16x16x32_bf16 v[40:43], v[178:181], v[210:213], 0
	v_mfma_f32_16x16x32_bf16 v[40:43], v[182:185], v[214:217], v[40:43]
	v_mfma_f32_16x16x32_bf16 v[44:47], v[174:177], v[214:217], 0
	v_mfma_f32_16x16x32_bf16 v[44:47], v[170:173], v[210:213], v[44:47]
	v_mfma_f32_16x16x32_bf16 v[28:31], v[170:173], v[222:225], 0
	v_mfma_f32_16x16x32_bf16 v[28:31], v[174:177], v[226:229], v[28:31]
	v_mfma_f32_16x16x32_bf16 v[24:27], v[182:185], v[226:229], 0
	v_mfma_f32_16x16x32_bf16 v[24:27], v[178:181], v[222:225], v[24:27]
	v_mfma_f32_16x16x32_bf16 v[20:23], v[186:189], v[222:225], 0
	v_mfma_f32_16x16x32_bf16 v[20:23], v[190:193], v[226:229], v[20:23]
	v_mfma_f32_16x16x32_bf16 v[16:19], v[198:201], v[226:229], 0
	v_mfma_f32_16x16x32_bf16 v[16:19], v[194:197], v[222:225], v[16:19]
	v_mfma_f32_16x16x32_bf16 v[0:3], v[194:197], v[230:233], 0
	v_mfma_f32_16x16x32_bf16 v[0:3], v[198:201], v[234:237], v[0:3]
	v_mfma_f32_16x16x32_bf16 v[4:7], v[190:193], v[234:237], 0
	v_mfma_f32_16x16x32_bf16 v[4:7], v[186:189], v[230:233], v[4:7]
	v_mfma_f32_16x16x32_bf16 v[8:11], v[178:181], v[230:233], 0
	v_mfma_f32_16x16x32_bf16 v[8:11], v[182:185], v[234:237], v[8:11]
	v_mfma_f32_16x16x32_bf16 v[12:15], v[174:177], v[234:237], 0
	v_mfma_f32_16x16x32_bf16 v[12:15], v[170:173], v[230:233], v[12:15]
	s_barrier
	s_add_i32 s9, 0, 0x18000
	v_add_u32_e32 v169, s9, v164
	s_add_i32 s10, 0, 0x1c000
	ds_read_b128 v[170:173], v169
	ds_read_b128 v[174:177], v169 offset:1024
	ds_read_b128 v[178:181], v169 offset:2048
	ds_read_b128 v[182:185], v169 offset:3072
	v_add_u32_e32 v169, s10, v164
	ds_read_b128 v[186:189], v169
	ds_read_b128 v[190:193], v169 offset:1024
	ds_read_b128 v[194:197], v169 offset:2048
	ds_read_b128 v[198:201], v169 offset:3072
	s_add_u32 s4, s4, s18
	s_addc_u32 s5, s5, s19
	s_mov_b32 m0, s44
	v_lshl_add_u64 v[248:249], s[4:5], 0, v[134:135]
	ds_read_b128 v[202:205], v166 offset:32768
	ds_read_b128 v[206:209], v166 offset:33792
	ds_read_b128 v[210:213], v166 offset:34816
	ds_read_b128 v[214:217], v166 offset:35840
	ds_read_b128 v[222:225], v166 offset:36864
	ds_read_b128 v[226:229], v166 offset:37888
	ds_read_b128 v[230:233], v166 offset:38912
	ds_read_b128 v[234:237], v166 offset:39936
	global_load_lds_dwordx4 v[248:249], off
	v_lshl_add_u64 v[248:249], s[4:5], 0, v[130:131]
	s_mov_b32 m0, s45
	s_nop 0
	global_load_lds_dwordx4 v[248:249], off
	s_waitcnt vmcnt(8)
	s_waitcnt lgkmcnt(0)
	s_barrier
	s_waitcnt lgkmcnt(0)
	v_mfma_f32_16x16x32_bf16 v[124:127], v[170:173], v[202:205], v[124:127]
	v_mfma_f32_16x16x32_bf16 v[124:127], v[174:177], v[206:209], v[124:127]
	v_mfma_f32_16x16x32_bf16 v[120:123], v[182:185], v[206:209], v[120:123]
	v_mfma_f32_16x16x32_bf16 v[120:123], v[178:181], v[202:205], v[120:123]
	v_mfma_f32_16x16x32_bf16 v[116:119], v[186:189], v[202:205], v[116:119]
	v_mfma_f32_16x16x32_bf16 v[116:119], v[190:193], v[206:209], v[116:119]
	v_mfma_f32_16x16x32_bf16 v[112:115], v[198:201], v[206:209], v[112:115]
	v_mfma_f32_16x16x32_bf16 v[112:115], v[194:197], v[202:205], v[112:115]
	v_mfma_f32_16x16x32_bf16 v[96:99], v[194:197], v[210:213], v[96:99]
	v_mfma_f32_16x16x32_bf16 v[96:99], v[198:201], v[214:217], v[96:99]
	v_mfma_f32_16x16x32_bf16 v[100:103], v[190:193], v[214:217], v[100:103]
	v_mfma_f32_16x16x32_bf16 v[100:103], v[186:189], v[210:213], v[100:103]
	v_mfma_f32_16x16x32_bf16 v[104:107], v[178:181], v[210:213], v[104:107]
	v_mfma_f32_16x16x32_bf16 v[104:107], v[182:185], v[214:217], v[104:107]
	v_mfma_f32_16x16x32_bf16 v[108:111], v[174:177], v[214:217], v[108:111]
	v_mfma_f32_16x16x32_bf16 v[108:111], v[170:173], v[210:213], v[108:111]
	v_mfma_f32_16x16x32_bf16 v[92:95], v[170:173], v[222:225], v[92:95]
	v_mfma_f32_16x16x32_bf16 v[92:95], v[174:177], v[226:229], v[92:95]
	v_mfma_f32_16x16x32_bf16 v[88:91], v[182:185], v[226:229], v[88:91]
	v_mfma_f32_16x16x32_bf16 v[88:91], v[178:181], v[222:225], v[88:91]
	v_mfma_f32_16x16x32_bf16 v[84:87], v[186:189], v[222:225], v[84:87]
	v_mfma_f32_16x16x32_bf16 v[84:87], v[190:193], v[226:229], v[84:87]
	v_mfma_f32_16x16x32_bf16 v[80:83], v[198:201], v[226:229], v[80:83]
	v_mfma_f32_16x16x32_bf16 v[80:83], v[194:197], v[222:225], v[80:83]
	v_mfma_f32_16x16x32_bf16 v[64:67], v[194:197], v[230:233], v[64:67]
	v_mfma_f32_16x16x32_bf16 v[64:67], v[198:201], v[234:237], v[64:67]
	v_mfma_f32_16x16x32_bf16 v[68:71], v[190:193], v[234:237], v[68:71]
	v_mfma_f32_16x16x32_bf16 v[68:71], v[186:189], v[230:233], v[68:71]
	v_mfma_f32_16x16x32_bf16 v[72:75], v[178:181], v[230:233], v[72:75]
	v_mfma_f32_16x16x32_bf16 v[72:75], v[182:185], v[234:237], v[72:75]
	v_mfma_f32_16x16x32_bf16 v[76:79], v[174:177], v[234:237], v[76:79]
	v_mfma_f32_16x16x32_bf16 v[76:79], v[170:173], v[230:233], v[76:79]
	s_barrier
	s_add_i32 s4, s9, s39
	v_lshl_add_u64 v[218:219], v[218:219], 0, s[24:25]
	s_mov_b32 m0, s4
	ds_read_b128 v[202:205], v166 offset:49152
	ds_read_b128 v[206:209], v166 offset:50176
	ds_read_b128 v[210:213], v166 offset:51200
	ds_read_b128 v[214:217], v166 offset:52224
	ds_read_b128 v[222:225], v166 offset:53248
	ds_read_b128 v[226:229], v166 offset:54272
	ds_read_b128 v[230:233], v166 offset:55296
	ds_read_b128 v[234:237], v166 offset:56320
	global_load_lds_dwordx4 v[218:219], off
	v_lshl_add_u64 v[218:219], v[238:239], 0, s[24:25]
	s_add_i32 m0, s4, 0x2000
	s_add_i32 s4, s10, s39
	global_load_lds_dwordx4 v[218:219], off
	v_lshl_add_u64 v[218:219], v[240:241], 0, s[24:25]
	s_mov_b32 m0, s4
	s_nop 0
	global_load_lds_dwordx4 v[218:219], off
	v_lshl_add_u64 v[218:219], v[242:243], 0, s[24:25]
	s_add_i32 m0, s4, 0x2000
	s_nop 0
	global_load_lds_dwordx4 v[218:219], off
	v_lshl_add_u64 v[218:219], v[244:245], 0, s[24:25]
	s_mov_b32 m0, s49
	s_nop 0
	global_load_lds_dwordx4 v[218:219], off
	v_lshl_add_u64 v[218:219], v[246:247], 0, s[24:25]
	s_mov_b32 m0, s50
	s_nop 0
	global_load_lds_dwordx4 v[218:219], off
	s_waitcnt vmcnt(8)
	s_waitcnt lgkmcnt(0)
	s_barrier
	s_waitcnt lgkmcnt(0)
	v_mfma_f32_16x16x32_bf16 v[60:63], v[170:173], v[202:205], v[60:63]
	v_mfma_f32_16x16x32_bf16 v[60:63], v[174:177], v[206:209], v[60:63]
	v_mfma_f32_16x16x32_bf16 v[56:59], v[182:185], v[206:209], v[56:59]
	v_mfma_f32_16x16x32_bf16 v[56:59], v[178:181], v[202:205], v[56:59]
	v_mfma_f32_16x16x32_bf16 v[52:55], v[186:189], v[202:205], v[52:55]
	v_mfma_f32_16x16x32_bf16 v[52:55], v[190:193], v[206:209], v[52:55]
	v_mfma_f32_16x16x32_bf16 v[48:51], v[198:201], v[206:209], v[48:51]
	v_mfma_f32_16x16x32_bf16 v[48:51], v[194:197], v[202:205], v[48:51]
	v_mfma_f32_16x16x32_bf16 v[32:35], v[194:197], v[210:213], v[32:35]
	v_mfma_f32_16x16x32_bf16 v[32:35], v[198:201], v[214:217], v[32:35]
	v_mfma_f32_16x16x32_bf16 v[36:39], v[190:193], v[214:217], v[36:39]
	v_mfma_f32_16x16x32_bf16 v[36:39], v[186:189], v[210:213], v[36:39]
	v_mfma_f32_16x16x32_bf16 v[40:43], v[178:181], v[210:213], v[40:43]
	v_mfma_f32_16x16x32_bf16 v[40:43], v[182:185], v[214:217], v[40:43]
	v_mfma_f32_16x16x32_bf16 v[44:47], v[174:177], v[214:217], v[44:47]
	v_mfma_f32_16x16x32_bf16 v[44:47], v[170:173], v[210:213], v[44:47]
	v_mfma_f32_16x16x32_bf16 v[28:31], v[170:173], v[222:225], v[28:31]
	v_mfma_f32_16x16x32_bf16 v[28:31], v[174:177], v[226:229], v[28:31]
	v_mfma_f32_16x16x32_bf16 v[24:27], v[182:185], v[226:229], v[24:27]
	v_mfma_f32_16x16x32_bf16 v[24:27], v[178:181], v[222:225], v[24:27]
	v_mfma_f32_16x16x32_bf16 v[20:23], v[186:189], v[222:225], v[20:23]
	v_mfma_f32_16x16x32_bf16 v[20:23], v[190:193], v[226:229], v[20:23]
	v_mfma_f32_16x16x32_bf16 v[16:19], v[198:201], v[226:229], v[16:19]
	v_mfma_f32_16x16x32_bf16 v[16:19], v[194:197], v[222:225], v[16:19]
	v_mfma_f32_16x16x32_bf16 v[0:3], v[194:197], v[230:233], v[0:3]
	v_mfma_f32_16x16x32_bf16 v[0:3], v[198:201], v[234:237], v[0:3]
	v_mfma_f32_16x16x32_bf16 v[4:7], v[190:193], v[234:237], v[4:7]
	v_mfma_f32_16x16x32_bf16 v[4:7], v[186:189], v[230:233], v[4:7]
	v_mfma_f32_16x16x32_bf16 v[8:11], v[178:181], v[230:233], v[8:11]
	v_mfma_f32_16x16x32_bf16 v[8:11], v[182:185], v[234:237], v[8:11]
	v_mfma_f32_16x16x32_bf16 v[12:15], v[174:177], v[234:237], v[12:15]
	v_mfma_f32_16x16x32_bf16 v[12:15], v[170:173], v[230:233], v[12:15]
	s_barrier
	s_add_u32 s2, s2, 0x100
	s_addc_u32 s3, s3, 0
	s_add_u32 s6, s6, 0x100
	s_addc_u32 s7, s7, 0
	s_cmp_ge_i32 s8, s51
	s_mov_b32 s4, s8
	s_cbranch_scc1 .Lpeel_exit_970

.Lpeel_exit_970:
.LBB0_971:
	s_and_b64 vcc, exec, s[28:29]
	s_cbranch_vccz .LBB0_973
	s_barrier

.LBB0_1054:
	v_mov_b32_e32 v199, 0
	s_andn2_b64 vcc, exec, s[16:17]
	v_mov_b32_e32 v198, 0
	v_mov_b32_e32 v201, 0
	v_mov_b32_e32 v200, 0
	v_mov_b32_e32 v203, 0
	v_mov_b32_e32 v202, 0
	v_mov_b32_e32 v205, 0
	v_mov_b32_e32 v204, 0
	v_mov_b32_e32 v193, 0
	v_mov_b32_e32 v192, 0
	v_mov_b32_e32 v191, 0
	v_mov_b32_e32 v190, 0
	v_mov_b32_e32 v189, 0
	v_mov_b32_e32 v188, 0
	v_mov_b32_e32 v187, 0
	v_mov_b32_e32 v186, 0
	v_mov_b32_e32 v177, 0
	v_mov_b32_e32 v176, 0
	v_mov_b32_e32 v175, 0
	v_mov_b32_e32 v174, 0
	v_mov_b32_e32 v173, 0
	v_mov_b32_e32 v172, 0
	v_mov_b32_e32 v171, 0
	v_mov_b32_e32 v170, 0
	v_mov_b32_e32 v161, 0
	v_mov_b32_e32 v160, 0
	v_mov_b32_e32 v159, 0
	v_mov_b32_e32 v158, 0
	v_mov_b32_e32 v157, 0
	v_mov_b32_e32 v156, 0
	v_mov_b32_e32 v155, 0
	v_mov_b32_e32 v154, 0
	v_mov_b32_e32 v209, 0
	v_mov_b32_e32 v208, 0
	v_mov_b32_e32 v207, 0
	v_mov_b32_e32 v206, 0
	v_mov_b32_e32 v197, 0
	v_mov_b32_e32 v196, 0
	v_mov_b32_e32 v195, 0
	v_mov_b32_e32 v194, 0
	v_mov_b32_e32 v185, 0
	v_mov_b32_e32 v184, 0
	v_mov_b32_e32 v183, 0
	v_mov_b32_e32 v182, 0
	v_mov_b32_e32 v181, 0
	v_mov_b32_e32 v180, 0
	v_mov_b32_e32 v179, 0
	v_mov_b32_e32 v178, 0
	v_mov_b32_e32 v169, 0
	v_mov_b32_e32 v168, 0
	v_mov_b32_e32 v167, 0
	v_mov_b32_e32 v166, 0
	v_mov_b32_e32 v165, 0
	v_mov_b32_e32 v164, 0
	v_mov_b32_e32 v163, 0
	v_mov_b32_e32 v162, 0
	v_mov_b32_e32 v153, 0
	v_mov_b32_e32 v152, 0
	v_mov_b32_e32 v151, 0
	v_mov_b32_e32 v150, 0
	v_mov_b32_e32 v149, 0
	v_mov_b32_e32 v148, 0
	v_mov_b32_e32 v147, 0
	v_mov_b32_e32 v146, 0
	v_mov_b32_e32 v143, 0
	v_mov_b32_e32 v142, 0
	v_mov_b32_e32 v141, 0
	v_mov_b32_e32 v140, 0
	v_mov_b32_e32 v127, 0
	v_mov_b32_e32 v126, 0
	v_mov_b32_e32 v125, 0
	v_mov_b32_e32 v124, 0
	v_mov_b32_e32 v115, 0
	v_mov_b32_e32 v114, 0
	v_mov_b32_e32 v113, 0
	v_mov_b32_e32 v112, 0
	v_mov_b32_e32 v111, 0
	v_mov_b32_e32 v110, 0
	v_mov_b32_e32 v109, 0
	v_mov_b32_e32 v108, 0
	v_mov_b32_e32 v99, 0
	v_mov_b32_e32 v98, 0
	v_mov_b32_e32 v97, 0
	v_mov_b32_e32 v96, 0
	v_mov_b32_e32 v95, 0
	v_mov_b32_e32 v94, 0
	v_mov_b32_e32 v93, 0
	v_mov_b32_e32 v92, 0
	v_mov_b32_e32 v83, 0
	v_mov_b32_e32 v82, 0
	v_mov_b32_e32 v81, 0
	v_mov_b32_e32 v80, 0
	v_mov_b32_e32 v79, 0
	v_mov_b32_e32 v78, 0
	v_mov_b32_e32 v77, 0
	v_mov_b32_e32 v76, 0
	v_mov_b32_e32 v123, 0
	v_mov_b32_e32 v122, 0
	v_mov_b32_e32 v121, 0
	v_mov_b32_e32 v120, 0
	v_mov_b32_e32 v119, 0
	v_mov_b32_e32 v118, 0
	v_mov_b32_e32 v117, 0
	v_mov_b32_e32 v116, 0
	v_mov_b32_e32 v107, 0
	v_mov_b32_e32 v106, 0
	v_mov_b32_e32 v105, 0
	v_mov_b32_e32 v104, 0
	v_mov_b32_e32 v103, 0
	v_mov_b32_e32 v102, 0
	v_mov_b32_e32 v101, 0
	v_mov_b32_e32 v100, 0
	v_mov_b32_e32 v91, 0
	v_mov_b32_e32 v90, 0
	v_mov_b32_e32 v89, 0
	v_mov_b32_e32 v88, 0
	v_mov_b32_e32 v87, 0
	v_mov_b32_e32 v86, 0
	v_mov_b32_e32 v85, 0
	v_mov_b32_e32 v84, 0
	v_mov_b32_e32 v75, 0
	v_mov_b32_e32 v74, 0
	v_mov_b32_e32 v73, 0
	v_mov_b32_e32 v72, 0
	v_mov_b32_e32 v71, 0
	v_mov_b32_e32 v70, 0
	v_mov_b32_e32 v69, 0
	v_mov_b32_e32 v68, 0
	s_cbranch_vccnz .LBB0_1058
	s_add_u32 s24, s24, 0xc000
	s_addc_u32 s25, s25, 0
	s_add_u32 s60, s26, 0x10000
	s_addc_u32 s61, s27, 0
	s_mov_b32 s26, 0
	s_waitcnt lgkmcnt(0)
	ds_read_b128 v[140:143], v222
	ds_read_b128 v[144:147], v222 offset:1024
	ds_read_b128 v[148:151], v222 offset:2048
	ds_read_b128 v[152:155], v222 offset:3072
	ds_read_b128 v[156:159], v223
	ds_read_b128 v[160:163], v223 offset:1024
	ds_read_b128 v[164:167], v223 offset:2048
	ds_read_b128 v[168:171], v223 offset:3072
	s_add_i32 s62, s26, 2
	s_add_u32 s27, s24, 0x4000
	s_addc_u32 s28, s25, 0
	s_cmp_eq_u32 s46, s26
	s_cselect_b32 s30, s0, s27
	s_cselect_b32 s31, s1, s28
	s_cselect_b32 s28, s22, s60
	s_cselect_b32 s29, s23, s61
	s_add_u32 s26, s30, 0x8000
	s_addc_u32 s27, s31, 0
	v_lshl_add_u64 v[204:205], s[24:25], 0, v[132:133]
	s_add_i32 m0, s38, 0xc000
	ds_read_b128 v[172:175], v224
	ds_read_b128 v[176:179], v224 offset:1024
	ds_read_b128 v[180:183], v224 offset:2048
	ds_read_b128 v[184:187], v224 offset:3072
	ds_read_b128 v[188:191], v224 offset:4096
	ds_read_b128 v[192:195], v224 offset:5120
	ds_read_b128 v[196:199], v224 offset:6144
	ds_read_b128 v[200:203], v224 offset:7168
	global_load_lds_dwordx4 v[204:205], off
	v_lshl_add_u64 v[204:205], s[24:25], 0, v[134:135]
	s_add_i32 m0, s38, 0xe000
	s_nop 0
	global_load_lds_dwordx4 v[204:205], off
	s_waitcnt vmcnt(8)
	s_waitcnt lgkmcnt(0)
	s_barrier
	s_waitcnt lgkmcnt(0)
	v_mfma_f32_16x16x32_bf16 v[124:127], v[140:143], v[172:175], 0
	v_mfma_f32_16x16x32_bf16 v[124:127], v[144:147], v[176:179], v[124:127]
	v_mfma_f32_16x16x32_bf16 v[120:123], v[152:155], v[176:179], 0
	v_mfma_f32_16x16x32_bf16 v[120:123], v[148:151], v[172:175], v[120:123]
	v_mfma_f32_16x16x32_bf16 v[108:111], v[156:159], v[172:175], 0
	v_mfma_f32_16x16x32_bf16 v[108:111], v[160:163], v[176:179], v[108:111]
	v_mfma_f32_16x16x32_bf16 v[100:103], v[168:171], v[176:179], 0
	v_mfma_f32_16x16x32_bf16 v[100:103], v[164:167], v[172:175], v[100:103]
	v_mfma_f32_16x16x32_bf16 v[84:87], v[164:167], v[180:183], 0
	v_mfma_f32_16x16x32_bf16 v[84:87], v[168:171], v[184:187], v[84:87]
	v_mfma_f32_16x16x32_bf16 v[92:95], v[160:163], v[184:187], 0
	v_mfma_f32_16x16x32_bf16 v[92:95], v[156:159], v[180:183], v[92:95]
	v_mfma_f32_16x16x32_bf16 v[112:115], v[148:151], v[180:183], 0
	v_mfma_f32_16x16x32_bf16 v[112:115], v[152:155], v[184:187], v[112:115]
	v_mfma_f32_16x16x32_bf16 v[116:119], v[144:147], v[184:187], 0
	v_mfma_f32_16x16x32_bf16 v[116:119], v[140:143], v[180:183], v[116:119]
	v_mfma_f32_16x16x32_bf16 v[104:107], v[140:143], v[188:191], 0
	v_mfma_f32_16x16x32_bf16 v[104:107], v[144:147], v[192:195], v[104:107]
	v_mfma_f32_16x16x32_bf16 v[96:99], v[152:155], v[192:195], 0
	v_mfma_f32_16x16x32_bf16 v[96:99], v[148:151], v[188:191], v[96:99]
	v_mfma_f32_16x16x32_bf16 v[76:79], v[156:159], v[188:191], 0
	v_mfma_f32_16x16x32_bf16 v[76:79], v[160:163], v[192:195], v[76:79]
	v_mfma_f32_16x16x32_bf16 v[72:75], v[168:171], v[192:195], 0
	v_mfma_f32_16x16x32_bf16 v[72:75], v[164:167], v[188:191], v[72:75]
	v_mfma_f32_16x16x32_bf16 v[64:67], v[164:167], v[196:199], 0
	v_mfma_f32_16x16x32_bf16 v[64:67], v[168:171], v[200:203], v[64:67]
	v_mfma_f32_16x16x32_bf16 v[68:71], v[160:163], v[200:203], 0
	v_mfma_f32_16x16x32_bf16 v[68:71], v[156:159], v[196:199], v[68:71]
	v_mfma_f32_16x16x32_bf16 v[80:83], v[148:151], v[196:199], 0
	v_mfma_f32_16x16x32_bf16 v[80:83], v[152:155], v[200:203], v[80:83]
	v_mfma_f32_16x16x32_bf16 v[88:91], v[144:147], v[200:203], 0
	v_mfma_f32_16x16x32_bf16 v[88:91], v[140:143], v[196:199], v[88:91]
	s_barrier
	s_add_i32 s63, s50, s37
	v_lshl_add_u64 v[204:205], s[28:29], 0, v[128:129]
	s_mov_b32 m0, s63
	ds_read_b128 v[172:175], v224 offset:16384
	ds_read_b128 v[176:179], v224 offset:17408
	ds_read_b128 v[180:183], v224 offset:18432
	ds_read_b128 v[184:187], v224 offset:19456
	ds_read_b128 v[188:191], v224 offset:20480
	ds_read_b128 v[192:195], v224 offset:21504
	ds_read_b128 v[196:199], v224 offset:22528
	ds_read_b128 v[200:203], v224 offset:23552
	global_load_lds_dwordx4 v[204:205], off
	s_add_i32 m0, s63, 0x2000
	s_add_u32 s64, s28, 0x4000
	v_lshl_add_u64 v[204:205], s[28:29], 0, v[130:131]
	s_addc_u32 s65, s29, 0
	s_add_i32 s63, s51, s37
	global_load_lds_dwordx4 v[204:205], off
	v_lshl_add_u64 v[204:205], s[64:65], 0, v[128:129]
	s_mov_b32 m0, s63
	s_nop 0
	global_load_lds_dwordx4 v[204:205], off
	v_lshl_add_u64 v[204:205], s[64:65], 0, v[130:131]
	s_add_i32 m0, s63, 0x2000
	s_nop 0
	global_load_lds_dwordx4 v[204:205], off
	v_lshl_add_u64 v[204:205], s[30:31], 0, v[128:129]
	s_mov_b32 m0, s38
	s_nop 0
	global_load_lds_dwordx4 v[204:205], off
	v_lshl_add_u64 v[204:205], s[30:31], 0, v[130:131]
	s_mov_b32 m0, s39
	s_nop 0
	global_load_lds_dwordx4 v[204:205], off
	s_waitcnt vmcnt(8)
	s_waitcnt lgkmcnt(0)
	s_barrier
	s_waitcnt lgkmcnt(0)
	v_mfma_f32_16x16x32_bf16 v[60:63], v[140:143], v[172:175], 0
	v_mfma_f32_16x16x32_bf16 v[60:63], v[144:147], v[176:179], v[60:63]
	v_mfma_f32_16x16x32_bf16 v[56:59], v[152:155], v[176:179], 0
	v_mfma_f32_16x16x32_bf16 v[56:59], v[148:151], v[172:175], v[56:59]
	v_mfma_f32_16x16x32_bf16 v[44:47], v[156:159], v[172:175], 0
	v_mfma_f32_16x16x32_bf16 v[44:47], v[160:163], v[176:179], v[44:47]
	v_mfma_f32_16x16x32_bf16 v[36:39], v[168:171], v[176:179], 0
	v_mfma_f32_16x16x32_bf16 v[36:39], v[164:167], v[172:175], v[36:39]
	v_mfma_f32_16x16x32_bf16 v[20:23], v[164:167], v[180:183], 0
	v_mfma_f32_16x16x32_bf16 v[20:23], v[168:171], v[184:187], v[20:23]
	v_mfma_f32_16x16x32_bf16 v[28:31], v[160:163], v[184:187], 0
	v_mfma_f32_16x16x32_bf16 v[28:31], v[156:159], v[180:183], v[28:31]
	v_mfma_f32_16x16x32_bf16 v[48:51], v[148:151], v[180:183], 0
	v_mfma_f32_16x16x32_bf16 v[48:51], v[152:155], v[184:187], v[48:51]
	v_mfma_f32_16x16x32_bf16 v[52:55], v[144:147], v[184:187], 0
	v_mfma_f32_16x16x32_bf16 v[52:55], v[140:143], v[180:183], v[52:55]
	v_mfma_f32_16x16x32_bf16 v[40:43], v[140:143], v[188:191], 0
	v_mfma_f32_16x16x32_bf16 v[40:43], v[144:147], v[192:195], v[40:43]
	v_mfma_f32_16x16x32_bf16 v[32:35], v[152:155], v[192:195], 0
	v_mfma_f32_16x16x32_bf16 v[32:35], v[148:151], v[188:191], v[32:35]
	v_mfma_f32_16x16x32_bf16 v[12:15], v[156:159], v[188:191], 0
	v_mfma_f32_16x16x32_bf16 v[12:15], v[160:163], v[192:195], v[12:15]
	v_mfma_f32_16x16x32_bf16 v[8:11], v[168:171], v[192:195], 0
	v_mfma_f32_16x16x32_bf16 v[8:11], v[164:167], v[188:191], v[8:11]
	v_mfma_f32_16x16x32_bf16 v[0:3], v[164:167], v[196:199], 0
	v_mfma_f32_16x16x32_bf16 v[0:3], v[168:171], v[200:203], v[0:3]
	v_mfma_f32_16x16x32_bf16 v[4:7], v[160:163], v[200:203], 0
	v_mfma_f32_16x16x32_bf16 v[4:7], v[156:159], v[196:199], v[4:7]
	v_mfma_f32_16x16x32_bf16 v[16:19], v[148:151], v[196:199], 0
	v_mfma_f32_16x16x32_bf16 v[16:19], v[152:155], v[200:203], v[16:19]
	v_mfma_f32_16x16x32_bf16 v[24:27], v[144:147], v[200:203], 0
	v_mfma_f32_16x16x32_bf16 v[24:27], v[140:143], v[196:199], v[24:27]
	s_barrier
	s_add_i32 s63, 0, 0x18000
	s_add_i32 s64, 0, 0x1c000
	v_add_u32_e32 v152, s63, v219
	v_add_u32_e32 v168, s64, v219
	ds_read_b128 v[140:143], v152
	ds_read_b128 v[144:147], v152 offset:1024
	ds_read_b128 v[148:151], v152 offset:2048
	ds_read_b128 v[152:155], v152 offset:3072
	ds_read_b128 v[156:159], v168
	ds_read_b128 v[160:163], v168 offset:1024
	ds_read_b128 v[164:167], v168 offset:2048
	ds_read_b128 v[168:171], v168 offset:3072
	s_add_u32 s30, s30, 0x4000
	s_addc_u32 s31, s31, 0
	s_mov_b32 m0, s40
	v_lshl_add_u64 v[204:205], s[30:31], 0, v[128:129]
	ds_read_b128 v[172:175], v224 offset:32768
	ds_read_b128 v[176:179], v224 offset:33792
	ds_read_b128 v[180:183], v224 offset:34816
	ds_read_b128 v[184:187], v224 offset:35840
	ds_read_b128 v[188:191], v224 offset:36864
	ds_read_b128 v[192:195], v224 offset:37888
	ds_read_b128 v[196:199], v224 offset:38912
	ds_read_b128 v[200:203], v224 offset:39936
	global_load_lds_dwordx4 v[204:205], off
	v_lshl_add_u64 v[204:205], s[30:31], 0, v[130:131]
	s_mov_b32 m0, s41
	s_nop 0
	global_load_lds_dwordx4 v[204:205], off
	s_waitcnt vmcnt(8)
	s_waitcnt lgkmcnt(0)
	s_barrier
	s_waitcnt lgkmcnt(0)
	v_mfma_f32_16x16x32_bf16 v[124:127], v[140:143], v[172:175], v[124:127]
	v_mfma_f32_16x16x32_bf16 v[124:127], v[144:147], v[176:179], v[124:127]
	v_mfma_f32_16x16x32_bf16 v[120:123], v[152:155], v[176:179], v[120:123]
	v_mfma_f32_16x16x32_bf16 v[120:123], v[148:151], v[172:175], v[120:123]
	v_mfma_f32_16x16x32_bf16 v[108:111], v[156:159], v[172:175], v[108:111]
	v_mfma_f32_16x16x32_bf16 v[108:111], v[160:163], v[176:179], v[108:111]
	v_mfma_f32_16x16x32_bf16 v[100:103], v[168:171], v[176:179], v[100:103]
	v_mfma_f32_16x16x32_bf16 v[100:103], v[164:167], v[172:175], v[100:103]
	v_mfma_f32_16x16x32_bf16 v[84:87], v[164:167], v[180:183], v[84:87]
	v_mfma_f32_16x16x32_bf16 v[84:87], v[168:171], v[184:187], v[84:87]
	v_mfma_f32_16x16x32_bf16 v[92:95], v[160:163], v[184:187], v[92:95]
	v_mfma_f32_16x16x32_bf16 v[92:95], v[156:159], v[180:183], v[92:95]
	v_mfma_f32_16x16x32_bf16 v[112:115], v[148:151], v[180:183], v[112:115]
	v_mfma_f32_16x16x32_bf16 v[112:115], v[152:155], v[184:187], v[112:115]
	v_mfma_f32_16x16x32_bf16 v[116:119], v[144:147], v[184:187], v[116:119]
	v_mfma_f32_16x16x32_bf16 v[116:119], v[140:143], v[180:183], v[116:119]
	v_mfma_f32_16x16x32_bf16 v[104:107], v[140:143], v[188:191], v[104:107]
	v_mfma_f32_16x16x32_bf16 v[104:107], v[144:147], v[192:195], v[104:107]
	v_mfma_f32_16x16x32_bf16 v[96:99], v[152:155], v[192:195], v[96:99]
	v_mfma_f32_16x16x32_bf16 v[96:99], v[148:151], v[188:191], v[96:99]
	v_mfma_f32_16x16x32_bf16 v[76:79], v[156:159], v[188:191], v[76:79]
	v_mfma_f32_16x16x32_bf16 v[76:79], v[160:163], v[192:195], v[76:79]
	v_mfma_f32_16x16x32_bf16 v[72:75], v[168:171], v[192:195], v[72:75]
	v_mfma_f32_16x16x32_bf16 v[72:75], v[164:167], v[188:191], v[72:75]
	v_mfma_f32_16x16x32_bf16 v[64:67], v[164:167], v[196:199], v[64:67]
	v_mfma_f32_16x16x32_bf16 v[64:67], v[168:171], v[200:203], v[64:67]
	v_mfma_f32_16x16x32_bf16 v[68:71], v[160:163], v[200:203], v[68:71]
	v_mfma_f32_16x16x32_bf16 v[68:71], v[156:159], v[196:199], v[68:71]
	v_mfma_f32_16x16x32_bf16 v[80:83], v[148:151], v[196:199], v[80:83]
	v_mfma_f32_16x16x32_bf16 v[80:83], v[152:155], v[200:203], v[80:83]
	v_mfma_f32_16x16x32_bf16 v[88:91], v[144:147], v[200:203], v[88:91]
	v_mfma_f32_16x16x32_bf16 v[88:91], v[140:143], v[196:199], v[88:91]
	s_barrier
	s_add_u32 s30, s28, 0x8000
	s_addc_u32 s31, s29, 0
	s_add_i32 s63, s63, s37
	v_lshl_add_u64 v[204:205], s[30:31], 0, v[128:129]
	s_mov_b32 m0, s63
	ds_read_b128 v[172:175], v224 offset:49152
	ds_read_b128 v[176:179], v224 offset:50176
	ds_read_b128 v[180:183], v224 offset:51200
	ds_read_b128 v[184:187], v224 offset:52224
	ds_read_b128 v[188:191], v224 offset:53248
	ds_read_b128 v[192:195], v224 offset:54272
	ds_read_b128 v[196:199], v224 offset:55296
	ds_read_b128 v[200:203], v224 offset:56320
	global_load_lds_dwordx4 v[204:205], off
	s_add_i32 m0, s63, 0x2000
	s_add_u32 s28, s28, 0xc000
	v_lshl_add_u64 v[204:205], s[30:31], 0, v[130:131]
	s_addc_u32 s29, s29, 0
	s_add_i32 s30, s64, s37
	global_load_lds_dwordx4 v[204:205], off
	v_lshl_add_u64 v[204:205], s[28:29], 0, v[128:129]
	s_mov_b32 m0, s30
	s_nop 0
	global_load_lds_dwordx4 v[204:205], off
	v_lshl_add_u64 v[204:205], s[28:29], 0, v[130:131]
	s_add_i32 m0, s30, 0x2000
	s_nop 0
	global_load_lds_dwordx4 v[204:205], off
	v_lshl_add_u64 v[204:205], s[26:27], 0, v[128:129]
	s_mov_b32 m0, s44
	s_nop 0
	global_load_lds_dwordx4 v[204:205], off
	v_lshl_add_u64 v[204:205], s[26:27], 0, v[130:131]
	s_mov_b32 m0, s45
	s_nop 0
	global_load_lds_dwordx4 v[204:205], off
	s_waitcnt vmcnt(8)
	s_waitcnt lgkmcnt(0)
	s_barrier
	s_waitcnt lgkmcnt(0)
	v_mfma_f32_16x16x32_bf16 v[60:63], v[140:143], v[172:175], v[60:63]
	v_mfma_f32_16x16x32_bf16 v[60:63], v[144:147], v[176:179], v[60:63]
	v_mfma_f32_16x16x32_bf16 v[56:59], v[152:155], v[176:179], v[56:59]
	v_mfma_f32_16x16x32_bf16 v[56:59], v[148:151], v[172:175], v[56:59]
	v_mfma_f32_16x16x32_bf16 v[44:47], v[156:159], v[172:175], v[44:47]
	v_mfma_f32_16x16x32_bf16 v[44:47], v[160:163], v[176:179], v[44:47]
	v_mfma_f32_16x16x32_bf16 v[36:39], v[168:171], v[176:179], v[36:39]
	v_mfma_f32_16x16x32_bf16 v[36:39], v[164:167], v[172:175], v[36:39]
	v_mfma_f32_16x16x32_bf16 v[20:23], v[164:167], v[180:183], v[20:23]
	v_mfma_f32_16x16x32_bf16 v[20:23], v[168:171], v[184:187], v[20:23]
	v_mfma_f32_16x16x32_bf16 v[28:31], v[160:163], v[184:187], v[28:31]
	v_mfma_f32_16x16x32_bf16 v[28:31], v[156:159], v[180:183], v[28:31]
	v_mfma_f32_16x16x32_bf16 v[48:51], v[148:151], v[180:183], v[48:51]
	v_mfma_f32_16x16x32_bf16 v[48:51], v[152:155], v[184:187], v[48:51]
	v_mfma_f32_16x16x32_bf16 v[52:55], v[144:147], v[184:187], v[52:55]
	v_mfma_f32_16x16x32_bf16 v[52:55], v[140:143], v[180:183], v[52:55]
	v_mfma_f32_16x16x32_bf16 v[40:43], v[140:143], v[188:191], v[40:43]
	v_mfma_f32_16x16x32_bf16 v[40:43], v[144:147], v[192:195], v[40:43]
	v_mfma_f32_16x16x32_bf16 v[32:35], v[152:155], v[192:195], v[32:35]
	v_mfma_f32_16x16x32_bf16 v[32:35], v[148:151], v[188:191], v[32:35]
	v_mfma_f32_16x16x32_bf16 v[12:15], v[156:159], v[188:191], v[12:15]
	v_mfma_f32_16x16x32_bf16 v[12:15], v[160:163], v[192:195], v[12:15]
	v_mfma_f32_16x16x32_bf16 v[8:11], v[168:171], v[192:195], v[8:11]
	v_mfma_f32_16x16x32_bf16 v[8:11], v[164:167], v[188:191], v[8:11]
	v_mfma_f32_16x16x32_bf16 v[0:3], v[164:167], v[196:199], v[0:3]
	v_mfma_f32_16x16x32_bf16 v[0:3], v[168:171], v[200:203], v[0:3]
	v_mfma_f32_16x16x32_bf16 v[4:7], v[160:163], v[200:203], v[4:7]
	v_mfma_f32_16x16x32_bf16 v[4:7], v[156:159], v[196:199], v[4:7]
	v_mfma_f32_16x16x32_bf16 v[16:19], v[148:151], v[196:199], v[16:19]
	v_mfma_f32_16x16x32_bf16 v[16:19], v[152:155], v[200:203], v[16:19]
	v_mfma_f32_16x16x32_bf16 v[24:27], v[144:147], v[200:203], v[24:27]
	v_mfma_f32_16x16x32_bf16 v[24:27], v[140:143], v[196:199], v[24:27]
	s_barrier
	s_add_u32 s24, s24, 0x10000
	s_addc_u32 s25, s25, 0
	s_add_u32 s60, s60, 0x10000
	s_addc_u32 s61, s61, 0
	s_cmp_ge_i32 s62, s43
	s_mov_b32 s26, s62
	s_cbranch_scc1 .Lpeel_exit_1056

.Lpeel_exit_1056:
	v_pk_mul_f32 v[198:199], v[126:127], 0.5 op_sel_hi:[1,0]
	v_pk_mul_f32 v[200:201], v[124:125], 0.5 op_sel_hi:[1,0]
	v_pk_mul_f32 v[202:203], v[122:123], 0.5 op_sel_hi:[1,0]
	v_pk_mul_f32 v[204:205], v[120:121], 0.5 op_sel_hi:[1,0]
	v_pk_mul_f32 v[208:209], v[110:111], 0.5 op_sel_hi:[1,0]
	v_pk_mul_f32 v[206:207], v[108:109], 0.5 op_sel_hi:[1,0]
	v_pk_mul_f32 v[196:197], v[102:103], 0.5 op_sel_hi:[1,0]
	v_pk_mul_f32 v[194:195], v[100:101], 0.5 op_sel_hi:[1,0]
	v_pk_mul_f32 v[192:193], v[118:119], 0.5 op_sel_hi:[1,0]
	v_pk_mul_f32 v[190:191], v[116:117], 0.5 op_sel_hi:[1,0]
	v_pk_mul_f32 v[188:189], v[114:115], 0.5 op_sel_hi:[1,0]
	v_pk_mul_f32 v[186:187], v[112:113], 0.5 op_sel_hi:[1,0]
	v_pk_mul_f32 v[184:185], v[94:95], 0.5 op_sel_hi:[1,0]
	v_pk_mul_f32 v[182:183], v[92:93], 0.5 op_sel_hi:[1,0]
	v_pk_mul_f32 v[180:181], v[86:87], 0.5 op_sel_hi:[1,0]
	v_pk_mul_f32 v[178:179], v[84:85], 0.5 op_sel_hi:[1,0]
	v_pk_mul_f32 v[176:177], v[106:107], 0.5 op_sel_hi:[1,0]
	v_pk_mul_f32 v[174:175], v[104:105], 0.5 op_sel_hi:[1,0]
	v_pk_mul_f32 v[172:173], v[98:99], 0.5 op_sel_hi:[1,0]
	v_pk_mul_f32 v[170:171], v[96:97], 0.5 op_sel_hi:[1,0]
	v_pk_mul_f32 v[168:169], v[78:79], 0.5 op_sel_hi:[1,0]
	v_pk_mul_f32 v[166:167], v[76:77], 0.5 op_sel_hi:[1,0]
	v_pk_mul_f32 v[164:165], v[74:75], 0.5 op_sel_hi:[1,0]
	v_pk_mul_f32 v[162:163], v[72:73], 0.5 op_sel_hi:[1,0]
	v_pk_mul_f32 v[160:161], v[90:91], 0.5 op_sel_hi:[1,0]
	v_pk_mul_f32 v[158:159], v[88:89], 0.5 op_sel_hi:[1,0]
	v_pk_mul_f32 v[156:157], v[82:83], 0.5 op_sel_hi:[1,0]
	v_pk_mul_f32 v[154:155], v[80:81], 0.5 op_sel_hi:[1,0]
	v_pk_mul_f32 v[152:153], v[70:71], 0.5 op_sel_hi:[1,0]
	v_pk_mul_f32 v[150:151], v[68:69], 0.5 op_sel_hi:[1,0]
	v_pk_mul_f32 v[148:149], v[66:67], 0.5 op_sel_hi:[1,0]
	v_pk_mul_f32 v[146:147], v[64:65], 0.5 op_sel_hi:[1,0]
	v_pk_mul_f32 v[142:143], v[62:63], 0.5 op_sel_hi:[1,0]
	v_pk_mul_f32 v[140:141], v[60:61], 0.5 op_sel_hi:[1,0]
	v_pk_mul_f32 v[126:127], v[58:59], 0.5 op_sel_hi:[1,0]
	v_pk_mul_f32 v[124:125], v[56:57], 0.5 op_sel_hi:[1,0]
	v_pk_mul_f32 v[122:123], v[46:47], 0.5 op_sel_hi:[1,0]
	v_pk_mul_f32 v[120:121], v[44:45], 0.5 op_sel_hi:[1,0]
	v_pk_mul_f32 v[118:119], v[38:39], 0.5 op_sel_hi:[1,0]
	v_pk_mul_f32 v[116:117], v[36:37], 0.5 op_sel_hi:[1,0]
	v_pk_mul_f32 v[114:115], v[54:55], 0.5 op_sel_hi:[1,0]
	v_pk_mul_f32 v[112:113], v[52:53], 0.5 op_sel_hi:[1,0]
	v_pk_mul_f32 v[110:111], v[50:51], 0.5 op_sel_hi:[1,0]
	v_pk_mul_f32 v[108:109], v[48:49], 0.5 op_sel_hi:[1,0]
	v_pk_mul_f32 v[106:107], v[30:31], 0.5 op_sel_hi:[1,0]
	v_pk_mul_f32 v[104:105], v[28:29], 0.5 op_sel_hi:[1,0]
	v_pk_mul_f32 v[102:103], v[22:23], 0.5 op_sel_hi:[1,0]
	v_pk_mul_f32 v[100:101], v[20:21], 0.5 op_sel_hi:[1,0]
	v_pk_mul_f32 v[98:99], v[42:43], 0.5 op_sel_hi:[1,0]
	v_pk_mul_f32 v[96:97], v[40:41], 0.5 op_sel_hi:[1,0]
	v_pk_mul_f32 v[94:95], v[34:35], 0.5 op_sel_hi:[1,0]
	v_pk_mul_f32 v[92:93], v[32:33], 0.5 op_sel_hi:[1,0]
	v_pk_mul_f32 v[90:91], v[14:15], 0.5 op_sel_hi:[1,0]
	v_pk_mul_f32 v[88:89], v[12:13], 0.5 op_sel_hi:[1,0]
	v_pk_mul_f32 v[86:87], v[10:11], 0.5 op_sel_hi:[1,0]
	v_pk_mul_f32 v[84:85], v[8:9], 0.5 op_sel_hi:[1,0]
	v_pk_mul_f32 v[82:83], v[26:27], 0.5 op_sel_hi:[1,0]
	v_pk_mul_f32 v[80:81], v[24:25], 0.5 op_sel_hi:[1,0]
	v_pk_mul_f32 v[78:79], v[18:19], 0.5 op_sel_hi:[1,0]
	v_pk_mul_f32 v[76:77], v[16:17], 0.5 op_sel_hi:[1,0]
	v_pk_mul_f32 v[74:75], v[6:7], 0.5 op_sel_hi:[1,0]
	v_pk_mul_f32 v[72:73], v[4:5], 0.5 op_sel_hi:[1,0]
	v_pk_mul_f32 v[70:71], v[2:3], 0.5 op_sel_hi:[1,0]
	v_pk_mul_f32 v[68:69], v[0:1], 0.5 op_sel_hi:[1,0]

.Lzskip_8:
	s_add_u32 s0, s38, 0x80
	s_addc_u32 s1, s39, 0
	s_add_u32 s38, s6, 0x100
	s_addc_u32 s39, s7, 0
	s_mov_b32 s6, 0
	ds_read_b128 v[128:131], v205
	ds_read_b128 v[132:135], v205 offset:1024
	ds_read_b128 v[136:139], v205 offset:2048
	ds_read_b128 v[140:143], v205 offset:3072
	ds_read_b128 v[144:147], v206
	ds_read_b128 v[160:163], v206 offset:1024
	ds_read_b128 v[164:167], v206 offset:2048
	ds_read_b128 v[168:171], v206 offset:3072
	s_add_i32 s41, s6, 2
	s_add_u32 s68, s0, 0x80
	s_addc_u32 s7, s1, 0
	s_cmp_eq_u32 s57, s6
	s_cselect_b32 s6, s34, s68
	s_cselect_b32 s7, s35, s7
	s_cselect_b32 s69, s37, s39
	s_cselect_b32 s68, s36, s38
	v_lshl_add_u64 v[200:201], s[0:1], 0, v[152:153]
	s_add_i32 m0, s47, 0xc000
	ds_read_b128 v[172:175], v207
	ds_read_b128 v[176:179], v207 offset:1024
	ds_read_b128 v[180:183], v207 offset:2048
	ds_read_b128 v[184:187], v207 offset:3072
	ds_read_b128 v[188:191], v207 offset:4096
	ds_read_b128 v[192:195], v207 offset:5120
	ds_read_b128 v[196:199], v207 offset:6144
	ds_read_b128 v[212:215], v207 offset:7168
	global_load_lds_dwordx4 v[200:201], off
	v_lshl_add_u64 v[200:201], s[0:1], 0, v[154:155]
	s_add_i32 m0, s47, 0xe000
	s_nop 0
	global_load_lds_dwordx4 v[200:201], off
	s_waitcnt vmcnt(8)
	s_waitcnt lgkmcnt(0)
	s_barrier
	s_waitcnt lgkmcnt(0)
	v_mfma_f32_16x16x32_bf16 v[124:127], v[128:131], v[172:175], 0
	v_mfma_f32_16x16x32_bf16 v[124:127], v[132:135], v[176:179], v[124:127]
	v_mfma_f32_16x16x32_bf16 v[120:123], v[140:143], v[176:179], 0
	v_mfma_f32_16x16x32_bf16 v[120:123], v[136:139], v[172:175], v[120:123]
	v_mfma_f32_16x16x32_bf16 v[116:119], v[144:147], v[172:175], 0
	v_mfma_f32_16x16x32_bf16 v[116:119], v[160:163], v[176:179], v[116:119]
	v_mfma_f32_16x16x32_bf16 v[112:115], v[168:171], v[176:179], 0
	v_mfma_f32_16x16x32_bf16 v[112:115], v[164:167], v[172:175], v[112:115]
	v_mfma_f32_16x16x32_bf16 v[96:99], v[164:167], v[180:183], 0
	v_mfma_f32_16x16x32_bf16 v[96:99], v[168:171], v[184:187], v[96:99]
	v_mfma_f32_16x16x32_bf16 v[100:103], v[160:163], v[184:187], 0
	v_mfma_f32_16x16x32_bf16 v[100:103], v[144:147], v[180:183], v[100:103]
	v_mfma_f32_16x16x32_bf16 v[104:107], v[136:139], v[180:183], 0
	v_mfma_f32_16x16x32_bf16 v[104:107], v[140:143], v[184:187], v[104:107]
	v_mfma_f32_16x16x32_bf16 v[108:111], v[132:135], v[184:187], 0
	v_mfma_f32_16x16x32_bf16 v[108:111], v[128:131], v[180:183], v[108:111]
	v_mfma_f32_16x16x32_bf16 v[92:95], v[128:131], v[188:191], 0
	v_mfma_f32_16x16x32_bf16 v[92:95], v[132:135], v[192:195], v[92:95]
	v_mfma_f32_16x16x32_bf16 v[88:91], v[140:143], v[192:195], 0
	v_mfma_f32_16x16x32_bf16 v[88:91], v[136:139], v[188:191], v[88:91]
	v_mfma_f32_16x16x32_bf16 v[84:87], v[144:147], v[188:191], 0
	v_mfma_f32_16x16x32_bf16 v[84:87], v[160:163], v[192:195], v[84:87]
	v_mfma_f32_16x16x32_bf16 v[80:83], v[168:171], v[192:195], 0
	v_mfma_f32_16x16x32_bf16 v[80:83], v[164:167], v[188:191], v[80:83]
	v_mfma_f32_16x16x32_bf16 v[64:67], v[164:167], v[196:199], 0
	v_mfma_f32_16x16x32_bf16 v[64:67], v[168:171], v[212:215], v[64:67]
	v_mfma_f32_16x16x32_bf16 v[68:71], v[160:163], v[212:215], 0
	v_mfma_f32_16x16x32_bf16 v[68:71], v[144:147], v[196:199], v[68:71]
	v_mfma_f32_16x16x32_bf16 v[72:75], v[136:139], v[196:199], 0
	v_mfma_f32_16x16x32_bf16 v[72:75], v[140:143], v[212:215], v[72:75]
	v_mfma_f32_16x16x32_bf16 v[76:79], v[132:135], v[212:215], 0
	v_mfma_f32_16x16x32_bf16 v[76:79], v[128:131], v[196:199], v[76:79]
	s_barrier
	s_add_i32 s70, s60, s46
	v_lshl_add_u64 v[200:201], s[68:69], 0, v[148:149]
	s_mov_b32 m0, s70
	ds_read_b128 v[172:175], v207 offset:16384
	ds_read_b128 v[176:179], v207 offset:17408
	ds_read_b128 v[180:183], v207 offset:18432
	ds_read_b128 v[184:187], v207 offset:19456
	ds_read_b128 v[188:191], v207 offset:20480
	ds_read_b128 v[192:195], v207 offset:21504
	ds_read_b128 v[196:199], v207 offset:22528
	ds_read_b128 v[212:215], v207 offset:23552
	global_load_lds_dwordx4 v[200:201], off
	s_add_i32 m0, s70, 0x2000
	v_lshl_add_u64 v[216:217], s[68:69], 0, v[150:151]
	s_add_u32 s68, s68, s10
	s_addc_u32 s69, s69, s11
	s_add_i32 s70, s61, s46
	global_load_lds_dwordx4 v[216:217], off
	v_lshl_add_u64 v[218:219], s[68:69], 0, v[148:149]
	s_mov_b32 m0, s70
	v_lshl_add_u64 v[220:221], s[68:69], 0, v[150:151]
	global_load_lds_dwordx4 v[218:219], off
	s_add_i32 m0, s70, 0x2000
	v_lshl_add_u64 v[222:223], s[6:7], 0, v[148:149]
	global_load_lds_dwordx4 v[220:221], off
	s_mov_b32 m0, s47
	v_lshl_add_u64 v[224:225], s[6:7], 0, v[150:151]
	global_load_lds_dwordx4 v[222:223], off
	s_mov_b32 m0, s48
	s_nop 0
	global_load_lds_dwordx4 v[224:225], off
	s_waitcnt vmcnt(8)
	s_waitcnt lgkmcnt(0)
	s_barrier
	s_waitcnt lgkmcnt(0)
	v_mfma_f32_16x16x32_bf16 v[60:63], v[128:131], v[172:175], 0
	v_mfma_f32_16x16x32_bf16 v[60:63], v[132:135], v[176:179], v[60:63]
	v_mfma_f32_16x16x32_bf16 v[56:59], v[140:143], v[176:179], 0
	v_mfma_f32_16x16x32_bf16 v[56:59], v[136:139], v[172:175], v[56:59]
	v_mfma_f32_16x16x32_bf16 v[52:55], v[144:147], v[172:175], 0
	v_mfma_f32_16x16x32_bf16 v[52:55], v[160:163], v[176:179], v[52:55]
	v_mfma_f32_16x16x32_bf16 v[48:51], v[168:171], v[176:179], 0
	v_mfma_f32_16x16x32_bf16 v[48:51], v[164:167], v[172:175], v[48:51]
	v_mfma_f32_16x16x32_bf16 v[32:35], v[164:167], v[180:183], 0
	v_mfma_f32_16x16x32_bf16 v[32:35], v[168:171], v[184:187], v[32:35]
	v_mfma_f32_16x16x32_bf16 v[36:39], v[160:163], v[184:187], 0
	v_mfma_f32_16x16x32_bf16 v[36:39], v[144:147], v[180:183], v[36:39]
	v_mfma_f32_16x16x32_bf16 v[40:43], v[136:139], v[180:183], 0
	v_mfma_f32_16x16x32_bf16 v[40:43], v[140:143], v[184:187], v[40:43]
	v_mfma_f32_16x16x32_bf16 v[44:47], v[132:135], v[184:187], 0
	v_mfma_f32_16x16x32_bf16 v[44:47], v[128:131], v[180:183], v[44:47]
	v_mfma_f32_16x16x32_bf16 v[28:31], v[128:131], v[188:191], 0
	v_mfma_f32_16x16x32_bf16 v[28:31], v[132:135], v[192:195], v[28:31]
	v_mfma_f32_16x16x32_bf16 v[24:27], v[140:143], v[192:195], 0
	v_mfma_f32_16x16x32_bf16 v[24:27], v[136:139], v[188:191], v[24:27]
	v_mfma_f32_16x16x32_bf16 v[20:23], v[144:147], v[188:191], 0
	v_mfma_f32_16x16x32_bf16 v[20:23], v[160:163], v[192:195], v[20:23]
	v_mfma_f32_16x16x32_bf16 v[16:19], v[168:171], v[192:195], 0
	v_mfma_f32_16x16x32_bf16 v[16:19], v[164:167], v[188:191], v[16:19]
	v_mfma_f32_16x16x32_bf16 v[0:3], v[164:167], v[196:199], 0
	v_mfma_f32_16x16x32_bf16 v[0:3], v[168:171], v[212:215], v[0:3]
	v_mfma_f32_16x16x32_bf16 v[4:7], v[160:163], v[212:215], 0
	v_mfma_f32_16x16x32_bf16 v[4:7], v[144:147], v[196:199], v[4:7]
	v_mfma_f32_16x16x32_bf16 v[8:11], v[136:139], v[196:199], 0
	v_mfma_f32_16x16x32_bf16 v[8:11], v[140:143], v[212:215], v[8:11]
	v_mfma_f32_16x16x32_bf16 v[12:15], v[132:135], v[212:215], 0
	v_mfma_f32_16x16x32_bf16 v[12:15], v[128:131], v[196:199], v[12:15]
	s_barrier
	s_add_i32 s68, 0, 0x18000
	s_add_i32 s69, 0, 0x1c000
	v_add_u32_e32 v140, s68, v203
	v_add_u32_e32 v168, s69, v203
	ds_read_b128 v[128:131], v140
	ds_read_b128 v[132:135], v140 offset:1024
	ds_read_b128 v[136:139], v140 offset:2048
	ds_read_b128 v[140:143], v140 offset:3072
	ds_read_b128 v[144:147], v168
	ds_read_b128 v[160:163], v168 offset:1024
	ds_read_b128 v[164:167], v168 offset:2048
	ds_read_b128 v[168:171], v168 offset:3072
	s_add_u32 s6, s6, s10
	s_addc_u32 s7, s7, s11
	s_mov_b32 m0, s49
	v_lshl_add_u64 v[226:227], s[6:7], 0, v[148:149]
	ds_read_b128 v[172:175], v207 offset:32768
	ds_read_b128 v[176:179], v207 offset:33792
	ds_read_b128 v[180:183], v207 offset:34816
	ds_read_b128 v[184:187], v207 offset:35840
	ds_read_b128 v[188:191], v207 offset:36864
	ds_read_b128 v[192:195], v207 offset:37888
	ds_read_b128 v[196:199], v207 offset:38912
	ds_read_b128 v[212:215], v207 offset:39936
	global_load_lds_dwordx4 v[226:227], off
	v_lshl_add_u64 v[226:227], s[6:7], 0, v[150:151]
	s_mov_b32 m0, s50
	s_nop 0
	global_load_lds_dwordx4 v[226:227], off
	s_waitcnt vmcnt(8)
	s_waitcnt lgkmcnt(0)
	s_barrier
	s_waitcnt lgkmcnt(0)
	v_mfma_f32_16x16x32_bf16 v[124:127], v[128:131], v[172:175], v[124:127]
	v_mfma_f32_16x16x32_bf16 v[124:127], v[132:135], v[176:179], v[124:127]
	v_mfma_f32_16x16x32_bf16 v[120:123], v[140:143], v[176:179], v[120:123]
	v_mfma_f32_16x16x32_bf16 v[120:123], v[136:139], v[172:175], v[120:123]
	v_mfma_f32_16x16x32_bf16 v[116:119], v[144:147], v[172:175], v[116:119]
	v_mfma_f32_16x16x32_bf16 v[116:119], v[160:163], v[176:179], v[116:119]
	v_mfma_f32_16x16x32_bf16 v[112:115], v[168:171], v[176:179], v[112:115]
	v_mfma_f32_16x16x32_bf16 v[112:115], v[164:167], v[172:175], v[112:115]
	v_mfma_f32_16x16x32_bf16 v[96:99], v[164:167], v[180:183], v[96:99]
	v_mfma_f32_16x16x32_bf16 v[96:99], v[168:171], v[184:187], v[96:99]
	v_mfma_f32_16x16x32_bf16 v[100:103], v[160:163], v[184:187], v[100:103]
	v_mfma_f32_16x16x32_bf16 v[100:103], v[144:147], v[180:183], v[100:103]
	v_mfma_f32_16x16x32_bf16 v[104:107], v[136:139], v[180:183], v[104:107]
	v_mfma_f32_16x16x32_bf16 v[104:107], v[140:143], v[184:187], v[104:107]
	v_mfma_f32_16x16x32_bf16 v[108:111], v[132:135], v[184:187], v[108:111]
	v_mfma_f32_16x16x32_bf16 v[108:111], v[128:131], v[180:183], v[108:111]
	v_mfma_f32_16x16x32_bf16 v[92:95], v[128:131], v[188:191], v[92:95]
	v_mfma_f32_16x16x32_bf16 v[92:95], v[132:135], v[192:195], v[92:95]
	v_mfma_f32_16x16x32_bf16 v[88:91], v[140:143], v[192:195], v[88:91]
	v_mfma_f32_16x16x32_bf16 v[88:91], v[136:139], v[188:191], v[88:91]
	v_mfma_f32_16x16x32_bf16 v[84:87], v[144:147], v[188:191], v[84:87]
	v_mfma_f32_16x16x32_bf16 v[84:87], v[160:163], v[192:195], v[84:87]
	v_mfma_f32_16x16x32_bf16 v[80:83], v[168:171], v[192:195], v[80:83]
	v_mfma_f32_16x16x32_bf16 v[80:83], v[164:167], v[188:191], v[80:83]
	v_mfma_f32_16x16x32_bf16 v[64:67], v[164:167], v[196:199], v[64:67]
	v_mfma_f32_16x16x32_bf16 v[64:67], v[168:171], v[212:215], v[64:67]
	v_mfma_f32_16x16x32_bf16 v[68:71], v[160:163], v[212:215], v[68:71]
	v_mfma_f32_16x16x32_bf16 v[68:71], v[144:147], v[196:199], v[68:71]
	v_mfma_f32_16x16x32_bf16 v[72:75], v[136:139], v[196:199], v[72:75]
	v_mfma_f32_16x16x32_bf16 v[72:75], v[140:143], v[212:215], v[72:75]
	v_mfma_f32_16x16x32_bf16 v[76:79], v[132:135], v[212:215], v[76:79]
	v_mfma_f32_16x16x32_bf16 v[76:79], v[128:131], v[196:199], v[76:79]
	s_barrier
	s_add_i32 s6, s68, s46
	v_lshl_add_u64 v[200:201], v[200:201], 0, s[20:21]
	s_mov_b32 m0, s6
	ds_read_b128 v[172:175], v207 offset:49152
	ds_read_b128 v[176:179], v207 offset:50176
	ds_read_b128 v[180:183], v207 offset:51200
	ds_read_b128 v[184:187], v207 offset:52224
	ds_read_b128 v[188:191], v207 offset:53248
	ds_read_b128 v[192:195], v207 offset:54272
	ds_read_b128 v[196:199], v207 offset:55296
	ds_read_b128 v[212:215], v207 offset:56320
	global_load_lds_dwordx4 v[200:201], off
	v_lshl_add_u64 v[200:201], v[216:217], 0, s[20:21]
	s_add_i32 m0, s6, 0x2000
	s_add_i32 s6, s69, s46
	global_load_lds_dwordx4 v[200:201], off
	v_lshl_add_u64 v[200:201], v[218:219], 0, s[20:21]
	s_mov_b32 m0, s6
	s_nop 0
	global_load_lds_dwordx4 v[200:201], off
	v_lshl_add_u64 v[200:201], v[220:221], 0, s[20:21]
	s_add_i32 m0, s6, 0x2000
	s_nop 0
	global_load_lds_dwordx4 v[200:201], off
	v_lshl_add_u64 v[200:201], v[222:223], 0, s[20:21]
	s_mov_b32 m0, s54
	s_nop 0
	global_load_lds_dwordx4 v[200:201], off
	v_lshl_add_u64 v[200:201], v[224:225], 0, s[20:21]
	s_mov_b32 m0, s55
	s_nop 0
	global_load_lds_dwordx4 v[200:201], off
	s_waitcnt vmcnt(8)
	s_waitcnt lgkmcnt(0)
	s_barrier
	s_waitcnt lgkmcnt(0)
	v_mfma_f32_16x16x32_bf16 v[60:63], v[128:131], v[172:175], v[60:63]
	v_mfma_f32_16x16x32_bf16 v[60:63], v[132:135], v[176:179], v[60:63]
	v_mfma_f32_16x16x32_bf16 v[56:59], v[140:143], v[176:179], v[56:59]
	v_mfma_f32_16x16x32_bf16 v[56:59], v[136:139], v[172:175], v[56:59]
	v_mfma_f32_16x16x32_bf16 v[52:55], v[144:147], v[172:175], v[52:55]
	v_mfma_f32_16x16x32_bf16 v[52:55], v[160:163], v[176:179], v[52:55]
	v_mfma_f32_16x16x32_bf16 v[48:51], v[168:171], v[176:179], v[48:51]
	v_mfma_f32_16x16x32_bf16 v[48:51], v[164:167], v[172:175], v[48:51]
	v_mfma_f32_16x16x32_bf16 v[32:35], v[164:167], v[180:183], v[32:35]
	v_mfma_f32_16x16x32_bf16 v[32:35], v[168:171], v[184:187], v[32:35]
	v_mfma_f32_16x16x32_bf16 v[36:39], v[160:163], v[184:187], v[36:39]
	v_mfma_f32_16x16x32_bf16 v[36:39], v[144:147], v[180:183], v[36:39]
	v_mfma_f32_16x16x32_bf16 v[40:43], v[136:139], v[180:183], v[40:43]
	v_mfma_f32_16x16x32_bf16 v[40:43], v[140:143], v[184:187], v[40:43]
	v_mfma_f32_16x16x32_bf16 v[44:47], v[132:135], v[184:187], v[44:47]
	v_mfma_f32_16x16x32_bf16 v[44:47], v[128:131], v[180:183], v[44:47]
	v_mfma_f32_16x16x32_bf16 v[28:31], v[128:131], v[188:191], v[28:31]
	v_mfma_f32_16x16x32_bf16 v[28:31], v[132:135], v[192:195], v[28:31]
	v_mfma_f32_16x16x32_bf16 v[24:27], v[140:143], v[192:195], v[24:27]
	v_mfma_f32_16x16x32_bf16 v[24:27], v[136:139], v[188:191], v[24:27]
	v_mfma_f32_16x16x32_bf16 v[20:23], v[144:147], v[188:191], v[20:23]
	v_mfma_f32_16x16x32_bf16 v[20:23], v[160:163], v[192:195], v[20:23]
	v_mfma_f32_16x16x32_bf16 v[16:19], v[168:171], v[192:195], v[16:19]
	v_mfma_f32_16x16x32_bf16 v[16:19], v[164:167], v[188:191], v[16:19]
	v_mfma_f32_16x16x32_bf16 v[0:3], v[164:167], v[196:199], v[0:3]
	v_mfma_f32_16x16x32_bf16 v[0:3], v[168:171], v[212:215], v[0:3]
	v_mfma_f32_16x16x32_bf16 v[4:7], v[160:163], v[212:215], v[4:7]
	v_mfma_f32_16x16x32_bf16 v[4:7], v[144:147], v[196:199], v[4:7]
	v_mfma_f32_16x16x32_bf16 v[8:11], v[136:139], v[196:199], v[8:11]
	v_mfma_f32_16x16x32_bf16 v[8:11], v[140:143], v[212:215], v[8:11]
	v_mfma_f32_16x16x32_bf16 v[12:15], v[132:135], v[212:215], v[12:15]
	v_mfma_f32_16x16x32_bf16 v[12:15], v[128:131], v[196:199], v[12:15]
	s_barrier
	s_add_u32 s0, s0, 0x100
	s_addc_u32 s1, s1, 0
	s_add_u32 s38, s38, 0x100
	s_addc_u32 s39, s39, 0
	s_cmp_ge_i32 s41, s56
	s_mov_b32 s6, s41
	s_cbranch_scc1 .Lpeel_exit_1159

.Lpeel_exit_1159:
.LBB0_1160:
	s_and_b64 vcc, exec, s[24:25]
	s_cbranch_vccz .LBB0_1162
	s_barrier
